# transposer with 4 register sets (3 items prefetched ahead per wave) at all transposer sites
# baseline (speedup 1.0000x reference)
.LBB0_231:
	s_or_b64 exec, exec, s[0:1]
	s_cmp_lt_u32 s96, 128
	s_cbranch_scc1 .Ltrp1_A_skip
	s_load_dwordx2 s[0:1], s[92:93], 0x58
	s_load_dwordx2 s[2:3], s[92:93], 0xb8
	s_load_dwordx2 s[4:5], s[92:93], 0xc0
	s_load_dwordx2 s[6:7], s[92:93], 0xc8
	s_load_dwordx2 s[8:9], s[92:93], 0xd0
	s_load_dwordx2 s[10:11], s[92:93], 0xe8
	v_and_b32_e32 v74, 63, v154
	v_lshrrev_b32_e32 v75, 6, v154
	v_mul_u32_u24_e32 v75, 0x2100, v75
	v_lshrrev_b32_e32 v3, 5, v74
	v_and_b32_e32 v4, 31, v74
	v_lshlrev_b32_e32 v4, 2, v4
	v_lshrrev_b32_e32 v5, 3, v74
	v_and_b32_e32 v6, 7, v74
	v_mul_u32_u24_e32 v2, 264, v6
	v_add_u32_e32 v2, v2, v5
	v_lshl_add_u32 v2, v2, 2, v75
	v_lshlrev_b32_e32 v6, 4, v6
	v_mul_u32_u24_e32 v1, 132, v5
	v_add3_u32 v1, v1, v6, v75
	v_readfirstlane_b32 s13, v154
	s_lshr_b32 s13, s13, 6
	s_lshl_b32 s26, s96, 3
	s_add_u32 s13, s13, s26
	s_mov_b32 s12, s13
	s_waitcnt lgkmcnt(0)
	s_mov_b32 s25, 0
	s_cmp_ge_u32 s12, 12288
	s_cbranch_scc1 .Ltrb_pro_end1
	s_cmp_ge_u32 s12, 33280
	s_cselect_b32 s41, 1, 0
	s_cselect_b32 s26, 33280, 0
	s_sub_u32 s42, s12, s26
	s_cmp_ge_u32 s42, 12288
	s_cbranch_scc1 .Ltrb_m3
	s_mul_i32 s43, s42, 43691
	s_lshr_b32 s43, s43, 24
	s_mul_i32 s26, s43, 384
	s_sub_u32 s44, s42, s26
	s_mov_b32 s14, s0
	s_mov_b32 s15, s1
	s_mov_b32 s36, 0xc000
	s_mov_b32 s37, 0x6000000
	s_mov_b32 s38, 0x0
	s_mov_b32 s39, 0x3000000
	s_mov_b32 s40, 0x1000
	s_branch .Ltrb_dec_done2

.Ltrb_dec_done2:
	s_mul_i32 s26, s41, s37
	s_lshl_b32 s27, s43, 6
	s_mul_i32 s27, s27, s36
	s_add_u32 s26, s26, s27
	s_lshl_b32 s27, s44, 7
	s_add_u32 s26, s26, s27
	s_add_u32 s14, s14, s26
	s_addc_u32 s15, s15, 0
	s_mul_i32 s26, s41, s39
	s_add_u32 s26, s26, s38
	s_lshl_b32 s27, s44, 5
	s_mul_i32 s27, s27, s40
	s_add_u32 s26, s26, s27
	s_lshl_b32 s27, s43, 7
	s_add_u32 s26, s26, s27
	s_add_u32 s18, s90, s26
	s_addc_u32 s19, s91, 0
	s_mov_b32 s22, s40
	v_mad_u32_u24 v7, v5, s36, v6
	s_lshl_b32 s45, s36, 3
	global_load_dwordx4 v[10:13], v7, s[14:15] nt
	s_add_u32 s14, s14, s45
	s_addc_u32 s15, s15, 0
	global_load_dwordx4 v[14:17], v7, s[14:15] nt
	s_add_u32 s14, s14, s45
	s_addc_u32 s15, s15, 0
	global_load_dwordx4 v[18:21], v7, s[14:15] nt
	s_add_u32 s14, s14, s45
	s_addc_u32 s15, s15, 0
	global_load_dwordx4 v[22:25], v7, s[14:15] nt
	s_add_u32 s14, s14, s45
	s_addc_u32 s15, s15, 0
	global_load_dwordx4 v[26:29], v7, s[14:15] nt
	s_add_u32 s14, s14, s45
	s_addc_u32 s15, s15, 0
	global_load_dwordx4 v[30:33], v7, s[14:15] nt
	s_add_u32 s14, s14, s45
	s_addc_u32 s15, s15, 0
	global_load_dwordx4 v[34:37], v7, s[14:15] nt
	s_add_u32 s14, s14, s45
	s_addc_u32 s15, s15, 0
	global_load_dwordx4 v[38:41], v7, s[14:15] nt
	s_add_u32 s25, s25, 1
	s_add_u32 s12, s12, 2048
	s_cmp_ge_u32 s12, 12288
	s_cbranch_scc1 .Ltrb_pro_end1
	s_cmp_ge_u32 s12, 33280
	s_cselect_b32 s41, 1, 0
	s_cselect_b32 s26, 33280, 0
	s_sub_u32 s42, s12, s26
	s_cmp_ge_u32 s42, 12288
	s_cbranch_scc1 .Ltrb_m10
	s_mul_i32 s43, s42, 43691
	s_lshr_b32 s43, s43, 24
	s_mul_i32 s26, s43, 384
	s_sub_u32 s44, s42, s26
	s_mov_b32 s14, s0
	s_mov_b32 s15, s1
	s_mov_b32 s36, 0xc000
	s_mov_b32 s37, 0x6000000
	s_mov_b32 s38, 0x0
	s_mov_b32 s39, 0x3000000
	s_mov_b32 s40, 0x1000
	s_branch .Ltrb_dec_done9

.Ltrb_dec_done9:
	s_mul_i32 s26, s41, s37
	s_lshl_b32 s27, s43, 6
	s_mul_i32 s27, s27, s36
	s_add_u32 s26, s26, s27
	s_lshl_b32 s27, s44, 7
	s_add_u32 s26, s26, s27
	s_add_u32 s14, s14, s26
	s_addc_u32 s15, s15, 0
	s_mul_i32 s26, s41, s39
	s_add_u32 s26, s26, s38
	s_lshl_b32 s27, s44, 5
	s_mul_i32 s27, s27, s40
	s_add_u32 s26, s26, s27
	s_lshl_b32 s27, s43, 7
	s_add_u32 s26, s26, s27
	s_add_u32 s20, s90, s26
	s_addc_u32 s21, s91, 0
	s_mov_b32 s23, s40
	v_mad_u32_u24 v7, v5, s36, v6
	s_lshl_b32 s45, s36, 3
	global_load_dwordx4 v[42:45], v7, s[14:15] nt
	s_add_u32 s14, s14, s45
	s_addc_u32 s15, s15, 0
	global_load_dwordx4 v[46:49], v7, s[14:15] nt
	s_add_u32 s14, s14, s45
	s_addc_u32 s15, s15, 0
	global_load_dwordx4 v[50:53], v7, s[14:15] nt
	s_add_u32 s14, s14, s45
	s_addc_u32 s15, s15, 0
	global_load_dwordx4 v[54:57], v7, s[14:15] nt
	s_add_u32 s14, s14, s45
	s_addc_u32 s15, s15, 0
	global_load_dwordx4 v[58:61], v7, s[14:15] nt
	s_add_u32 s14, s14, s45
	s_addc_u32 s15, s15, 0
	global_load_dwordx4 v[62:65], v7, s[14:15] nt
	s_add_u32 s14, s14, s45
	s_addc_u32 s15, s15, 0
	global_load_dwordx4 v[66:69], v7, s[14:15] nt
	s_add_u32 s14, s14, s45
	s_addc_u32 s15, s15, 0
	global_load_dwordx4 v[70:73], v7, s[14:15] nt
	s_add_u32 s25, s25, 1
	s_add_u32 s12, s12, 2048
	s_cmp_ge_u32 s12, 12288
	s_cbranch_scc1 .Ltrb_pro_end1
	s_cmp_ge_u32 s12, 33280
	s_cselect_b32 s41, 1, 0
	s_cselect_b32 s26, 33280, 0
	s_sub_u32 s42, s12, s26
	s_cmp_ge_u32 s42, 12288
	s_cbranch_scc1 .Ltrb_m17
	s_mul_i32 s43, s42, 43691
	s_lshr_b32 s43, s43, 24
	s_mul_i32 s26, s43, 384
	s_sub_u32 s44, s42, s26
	s_mov_b32 s14, s0
	s_mov_b32 s15, s1
	s_mov_b32 s36, 0xc000
	s_mov_b32 s37, 0x6000000
	s_mov_b32 s38, 0x0
	s_mov_b32 s39, 0x3000000
	s_mov_b32 s40, 0x1000
	s_branch .Ltrb_dec_done16

.Ltrb_dec_done16:
	s_mul_i32 s26, s41, s37
	s_lshl_b32 s27, s43, 6
	s_mul_i32 s27, s27, s36
	s_add_u32 s26, s26, s27
	s_lshl_b32 s27, s44, 7
	s_add_u32 s26, s26, s27
	s_add_u32 s14, s14, s26
	s_addc_u32 s15, s15, 0
	s_mul_i32 s26, s41, s39
	s_add_u32 s26, s26, s38
	s_lshl_b32 s27, s44, 5
	s_mul_i32 s27, s27, s40
	s_add_u32 s26, s26, s27
	s_lshl_b32 s27, s43, 7
	s_add_u32 s26, s26, s27
	s_add_u32 s48, s90, s26
	s_addc_u32 s49, s91, 0
	s_mov_b32 s52, s40
	v_mad_u32_u24 v7, v5, s36, v6
	s_lshl_b32 s45, s36, 3
	global_load_dwordx4 v[114:117], v7, s[14:15] nt
	s_add_u32 s14, s14, s45
	s_addc_u32 s15, s15, 0
	global_load_dwordx4 v[118:121], v7, s[14:15] nt
	s_add_u32 s14, s14, s45
	s_addc_u32 s15, s15, 0
	global_load_dwordx4 v[122:125], v7, s[14:15] nt
	s_add_u32 s14, s14, s45
	s_addc_u32 s15, s15, 0
	global_load_dwordx4 v[126:129], v7, s[14:15] nt
	s_add_u32 s14, s14, s45
	s_addc_u32 s15, s15, 0
	global_load_dwordx4 v[130:133], v7, s[14:15] nt
	s_add_u32 s14, s14, s45
	s_addc_u32 s15, s15, 0
	global_load_dwordx4 v[134:137], v7, s[14:15] nt
	s_add_u32 s14, s14, s45
	s_addc_u32 s15, s15, 0
	global_load_dwordx4 v[138:141], v7, s[14:15] nt
	s_add_u32 s14, s14, s45
	s_addc_u32 s15, s15, 0
	global_load_dwordx4 v[142:145], v7, s[14:15] nt
	s_add_u32 s25, s25, 1
	s_add_u32 s12, s12, 2048
.Ltrb_pro_end1:
	s_cmp_eq_u32 s25, 0
	s_cbranch_scc1 .Ltrb_done
	s_cmp_lt_u32 s12, 12288
	s_cbranch_scc0 .Ltrb_nonext23
	s_cmp_ge_u32 s12, 33280
	s_cselect_b32 s41, 1, 0
	s_cselect_b32 s26, 33280, 0
	s_sub_u32 s42, s12, s26
	s_cmp_ge_u32 s42, 12288
	s_cbranch_scc1 .Ltrb_m26
	s_mul_i32 s43, s42, 43691
	s_lshr_b32 s43, s43, 24
	s_mul_i32 s26, s43, 384
	s_sub_u32 s44, s42, s26
	s_mov_b32 s14, s0
	s_mov_b32 s15, s1
	s_mov_b32 s36, 0xc000
	s_mov_b32 s37, 0x6000000
	s_mov_b32 s38, 0x0
	s_mov_b32 s39, 0x3000000
	s_mov_b32 s40, 0x1000
	s_branch .Ltrb_dec_done25

.Ltrb_dec_done25:
	s_mul_i32 s26, s41, s37
	s_lshl_b32 s27, s43, 6
	s_mul_i32 s27, s27, s36
	s_add_u32 s26, s26, s27
	s_lshl_b32 s27, s44, 7
	s_add_u32 s26, s26, s27
	s_add_u32 s14, s14, s26
	s_addc_u32 s15, s15, 0
	s_mul_i32 s26, s41, s39
	s_add_u32 s26, s26, s38
	s_lshl_b32 s27, s44, 5
	s_mul_i32 s27, s27, s40
	s_add_u32 s26, s26, s27
	s_lshl_b32 s27, s43, 7
	s_add_u32 s26, s26, s27
	s_add_u32 s50, s90, s26
	s_addc_u32 s51, s91, 0
	s_mov_b32 s53, s40
	v_mad_u32_u24 v7, v5, s36, v6
	s_lshl_b32 s45, s36, 3
	global_load_dwordx4 v[160:163], v7, s[14:15] nt
	s_add_u32 s14, s14, s45
	s_addc_u32 s15, s15, 0
	global_load_dwordx4 v[164:167], v7, s[14:15] nt
	s_add_u32 s14, s14, s45
	s_addc_u32 s15, s15, 0
	global_load_dwordx4 v[168:171], v7, s[14:15] nt
	s_add_u32 s14, s14, s45
	s_addc_u32 s15, s15, 0
	global_load_dwordx4 v[172:175], v7, s[14:15] nt
	s_add_u32 s14, s14, s45
	s_addc_u32 s15, s15, 0
	global_load_dwordx4 v[176:179], v7, s[14:15] nt
	s_add_u32 s14, s14, s45
	s_addc_u32 s15, s15, 0
	global_load_dwordx4 v[180:183], v7, s[14:15] nt
	s_add_u32 s14, s14, s45
	s_addc_u32 s15, s15, 0
	global_load_dwordx4 v[184:187], v7, s[14:15] nt
	s_add_u32 s14, s14, s45
	s_addc_u32 s15, s15, 0
	global_load_dwordx4 v[188:191], v7, s[14:15] nt
	s_add_u32 s25, s25, 1
	s_add_u32 s12, s12, 2048
	s_waitcnt vmcnt(24)
	s_branch .Ltrb_after24

.Ltrb_after24:
	ds_write_b32 v1, v10 offset:0
	ds_write_b32 v1, v11 offset:4
	ds_write_b32 v1, v12 offset:8
	ds_write_b32 v1, v13 offset:12
	ds_write_b32 v1, v14 offset:1056
	ds_write_b32 v1, v15 offset:1060
	ds_write_b32 v1, v16 offset:1064
	ds_write_b32 v1, v17 offset:1068
	ds_write_b32 v1, v18 offset:2112
	ds_write_b32 v1, v19 offset:2116
	ds_write_b32 v1, v20 offset:2120
	ds_write_b32 v1, v21 offset:2124
	ds_write_b32 v1, v22 offset:3168
	ds_write_b32 v1, v23 offset:3172
	ds_write_b32 v1, v24 offset:3176
	ds_write_b32 v1, v25 offset:3180
	ds_write_b32 v1, v26 offset:4224
	ds_write_b32 v1, v27 offset:4228
	ds_write_b32 v1, v28 offset:4232
	ds_write_b32 v1, v29 offset:4236
	ds_write_b32 v1, v30 offset:5280
	ds_write_b32 v1, v31 offset:5284
	ds_write_b32 v1, v32 offset:5288
	ds_write_b32 v1, v33 offset:5292
	ds_write_b32 v1, v34 offset:6336
	ds_write_b32 v1, v35 offset:6340
	ds_write_b32 v1, v36 offset:6344
	ds_write_b32 v1, v37 offset:6348
	ds_write_b32 v1, v38 offset:7392
	ds_write_b32 v1, v39 offset:7396
	ds_write_b32 v1, v40 offset:7400
	ds_write_b32 v1, v41 offset:7404
	v_mad_u32_u24 v9, v5, s22, v6
	s_lshl_b32 s46, s22, 3
	s_waitcnt lgkmcnt(0)
	ds_read_b32 v74, v2 offset:0
	ds_read_b32 v75, v2 offset:132
	ds_read_b32 v76, v2 offset:264
	ds_read_b32 v77, v2 offset:396
	ds_read_b32 v78, v2 offset:528
	ds_read_b32 v79, v2 offset:660
	ds_read_b32 v80, v2 offset:792
	ds_read_b32 v81, v2 offset:924
	ds_read_b32 v82, v2 offset:32
	ds_read_b32 v83, v2 offset:164
	ds_read_b32 v84, v2 offset:296
	ds_read_b32 v85, v2 offset:428
	ds_read_b32 v86, v2 offset:560
	ds_read_b32 v87, v2 offset:692
	ds_read_b32 v88, v2 offset:824
	ds_read_b32 v89, v2 offset:956
	s_waitcnt lgkmcnt(8)
	v_cvt_pk_bf16_f32 v106, v74, v75
	v_cvt_pk_bf16_f32 v107, v76, v77
	v_cvt_pk_bf16_f32 v108, v78, v79
	v_cvt_pk_bf16_f32 v109, v80, v81
	global_store_dwordx4 v9, v[106:109], s[18:19]
	s_add_u32 s18, s18, s46
	s_addc_u32 s19, s19, 0
	ds_read_b32 v90, v2 offset:64
	ds_read_b32 v91, v2 offset:196
	ds_read_b32 v92, v2 offset:328
	ds_read_b32 v93, v2 offset:460
	ds_read_b32 v94, v2 offset:592
	ds_read_b32 v95, v2 offset:724
	ds_read_b32 v96, v2 offset:856
	ds_read_b32 v97, v2 offset:988
	s_waitcnt lgkmcnt(8)
	v_cvt_pk_bf16_f32 v110, v82, v83
	v_cvt_pk_bf16_f32 v111, v84, v85
	v_cvt_pk_bf16_f32 v112, v86, v87
	v_cvt_pk_bf16_f32 v113, v88, v89
	global_store_dwordx4 v9, v[110:113], s[18:19]
	s_add_u32 s18, s18, s46
	s_addc_u32 s19, s19, 0
	ds_read_b32 v98, v2 offset:96
	ds_read_b32 v99, v2 offset:228
	ds_read_b32 v100, v2 offset:360
	ds_read_b32 v101, v2 offset:492
	ds_read_b32 v102, v2 offset:624
	ds_read_b32 v103, v2 offset:756
	ds_read_b32 v104, v2 offset:888
	ds_read_b32 v105, v2 offset:1020
	s_waitcnt lgkmcnt(8)
	v_cvt_pk_bf16_f32 v106, v90, v91
	v_cvt_pk_bf16_f32 v107, v92, v93
	v_cvt_pk_bf16_f32 v108, v94, v95
	v_cvt_pk_bf16_f32 v109, v96, v97
	global_store_dwordx4 v9, v[106:109], s[18:19]
	s_add_u32 s18, s18, s46
	s_addc_u32 s19, s19, 0
	s_waitcnt lgkmcnt(0)
	v_cvt_pk_bf16_f32 v110, v98, v99
	v_cvt_pk_bf16_f32 v111, v100, v101
	v_cvt_pk_bf16_f32 v112, v102, v103
	v_cvt_pk_bf16_f32 v113, v104, v105
	global_store_dwordx4 v9, v[110:113], s[18:19]
	s_sub_u32 s25, s25, 1
	s_cmp_eq_u32 s25, 0
	s_cbranch_scc1 .Ltrb_done
	s_cmp_lt_u32 s12, 12288
	s_cbranch_scc0 .Ltrb_nonext32
	s_cmp_ge_u32 s12, 33280
	s_cselect_b32 s41, 1, 0
	s_cselect_b32 s26, 33280, 0
	s_sub_u32 s42, s12, s26
	s_cmp_ge_u32 s42, 12288
	s_cbranch_scc1 .Ltrb_m35
	s_mul_i32 s43, s42, 43691
	s_lshr_b32 s43, s43, 24
	s_mul_i32 s26, s43, 384
	s_sub_u32 s44, s42, s26
	s_mov_b32 s14, s0
	s_mov_b32 s15, s1
	s_mov_b32 s36, 0xc000
	s_mov_b32 s37, 0x6000000
	s_mov_b32 s38, 0x0
	s_mov_b32 s39, 0x3000000
	s_mov_b32 s40, 0x1000
	s_branch .Ltrb_dec_done34

.Ltrb_dec_done34:
	s_mul_i32 s26, s41, s37
	s_lshl_b32 s27, s43, 6
	s_mul_i32 s27, s27, s36
	s_add_u32 s26, s26, s27
	s_lshl_b32 s27, s44, 7
	s_add_u32 s26, s26, s27
	s_add_u32 s14, s14, s26
	s_addc_u32 s15, s15, 0
	s_mul_i32 s26, s41, s39
	s_add_u32 s26, s26, s38
	s_lshl_b32 s27, s44, 5
	s_mul_i32 s27, s27, s40
	s_add_u32 s26, s26, s27
	s_lshl_b32 s27, s43, 7
	s_add_u32 s26, s26, s27
	s_add_u32 s18, s90, s26
	s_addc_u32 s19, s91, 0
	s_mov_b32 s22, s40
	v_mad_u32_u24 v7, v5, s36, v6
	s_lshl_b32 s45, s36, 3
	global_load_dwordx4 v[10:13], v7, s[14:15] nt
	s_add_u32 s14, s14, s45
	s_addc_u32 s15, s15, 0
	global_load_dwordx4 v[14:17], v7, s[14:15] nt
	s_add_u32 s14, s14, s45
	s_addc_u32 s15, s15, 0
	global_load_dwordx4 v[18:21], v7, s[14:15] nt
	s_add_u32 s14, s14, s45
	s_addc_u32 s15, s15, 0
	global_load_dwordx4 v[22:25], v7, s[14:15] nt
	s_add_u32 s14, s14, s45
	s_addc_u32 s15, s15, 0
	global_load_dwordx4 v[26:29], v7, s[14:15] nt
	s_add_u32 s14, s14, s45
	s_addc_u32 s15, s15, 0
	global_load_dwordx4 v[30:33], v7, s[14:15] nt
	s_add_u32 s14, s14, s45
	s_addc_u32 s15, s15, 0
	global_load_dwordx4 v[34:37], v7, s[14:15] nt
	s_add_u32 s14, s14, s45
	s_addc_u32 s15, s15, 0
	global_load_dwordx4 v[38:41], v7, s[14:15] nt
	s_add_u32 s25, s25, 1
	s_add_u32 s12, s12, 2048
	s_waitcnt vmcnt(28)
	s_branch .Ltrb_after33

.Ltrb_after33:
	ds_write_b32 v1, v42 offset:0
	ds_write_b32 v1, v43 offset:4
	ds_write_b32 v1, v44 offset:8
	ds_write_b32 v1, v45 offset:12
	ds_write_b32 v1, v46 offset:1056
	ds_write_b32 v1, v47 offset:1060
	ds_write_b32 v1, v48 offset:1064
	ds_write_b32 v1, v49 offset:1068
	ds_write_b32 v1, v50 offset:2112
	ds_write_b32 v1, v51 offset:2116
	ds_write_b32 v1, v52 offset:2120
	ds_write_b32 v1, v53 offset:2124
	ds_write_b32 v1, v54 offset:3168
	ds_write_b32 v1, v55 offset:3172
	ds_write_b32 v1, v56 offset:3176
	ds_write_b32 v1, v57 offset:3180
	ds_write_b32 v1, v58 offset:4224
	ds_write_b32 v1, v59 offset:4228
	ds_write_b32 v1, v60 offset:4232
	ds_write_b32 v1, v61 offset:4236
	ds_write_b32 v1, v62 offset:5280
	ds_write_b32 v1, v63 offset:5284
	ds_write_b32 v1, v64 offset:5288
	ds_write_b32 v1, v65 offset:5292
	ds_write_b32 v1, v66 offset:6336
	ds_write_b32 v1, v67 offset:6340
	ds_write_b32 v1, v68 offset:6344
	ds_write_b32 v1, v69 offset:6348
	ds_write_b32 v1, v70 offset:7392
	ds_write_b32 v1, v71 offset:7396
	ds_write_b32 v1, v72 offset:7400
	ds_write_b32 v1, v73 offset:7404
	v_mad_u32_u24 v9, v5, s23, v6
	s_lshl_b32 s46, s23, 3
	s_waitcnt lgkmcnt(0)
	ds_read_b32 v74, v2 offset:0
	ds_read_b32 v75, v2 offset:132
	ds_read_b32 v76, v2 offset:264
	ds_read_b32 v77, v2 offset:396
	ds_read_b32 v78, v2 offset:528
	ds_read_b32 v79, v2 offset:660
	ds_read_b32 v80, v2 offset:792
	ds_read_b32 v81, v2 offset:924
	ds_read_b32 v82, v2 offset:32
	ds_read_b32 v83, v2 offset:164
	ds_read_b32 v84, v2 offset:296
	ds_read_b32 v85, v2 offset:428
	ds_read_b32 v86, v2 offset:560
	ds_read_b32 v87, v2 offset:692
	ds_read_b32 v88, v2 offset:824
	ds_read_b32 v89, v2 offset:956
	s_waitcnt lgkmcnt(8)
	v_cvt_pk_bf16_f32 v106, v74, v75
	v_cvt_pk_bf16_f32 v107, v76, v77
	v_cvt_pk_bf16_f32 v108, v78, v79
	v_cvt_pk_bf16_f32 v109, v80, v81
	global_store_dwordx4 v9, v[106:109], s[20:21]
	s_add_u32 s20, s20, s46
	s_addc_u32 s21, s21, 0
	ds_read_b32 v90, v2 offset:64
	ds_read_b32 v91, v2 offset:196
	ds_read_b32 v92, v2 offset:328
	ds_read_b32 v93, v2 offset:460
	ds_read_b32 v94, v2 offset:592
	ds_read_b32 v95, v2 offset:724
	ds_read_b32 v96, v2 offset:856
	ds_read_b32 v97, v2 offset:988
	s_waitcnt lgkmcnt(8)
	v_cvt_pk_bf16_f32 v110, v82, v83
	v_cvt_pk_bf16_f32 v111, v84, v85
	v_cvt_pk_bf16_f32 v112, v86, v87
	v_cvt_pk_bf16_f32 v113, v88, v89
	global_store_dwordx4 v9, v[110:113], s[20:21]
	s_add_u32 s20, s20, s46
	s_addc_u32 s21, s21, 0
	ds_read_b32 v98, v2 offset:96
	ds_read_b32 v99, v2 offset:228
	ds_read_b32 v100, v2 offset:360
	ds_read_b32 v101, v2 offset:492
	ds_read_b32 v102, v2 offset:624
	ds_read_b32 v103, v2 offset:756
	ds_read_b32 v104, v2 offset:888
	ds_read_b32 v105, v2 offset:1020
	s_waitcnt lgkmcnt(8)
	v_cvt_pk_bf16_f32 v106, v90, v91
	v_cvt_pk_bf16_f32 v107, v92, v93
	v_cvt_pk_bf16_f32 v108, v94, v95
	v_cvt_pk_bf16_f32 v109, v96, v97
	global_store_dwordx4 v9, v[106:109], s[20:21]
	s_add_u32 s20, s20, s46
	s_addc_u32 s21, s21, 0
	s_waitcnt lgkmcnt(0)
	v_cvt_pk_bf16_f32 v110, v98, v99
	v_cvt_pk_bf16_f32 v111, v100, v101
	v_cvt_pk_bf16_f32 v112, v102, v103
	v_cvt_pk_bf16_f32 v113, v104, v105
	global_store_dwordx4 v9, v[110:113], s[20:21]
	s_sub_u32 s25, s25, 1
	s_cmp_eq_u32 s25, 0
	s_cbranch_scc1 .Ltrb_done
	s_cmp_lt_u32 s12, 12288
	s_cbranch_scc0 .Ltrb_nonext41
	s_cmp_ge_u32 s12, 33280
	s_cselect_b32 s41, 1, 0
	s_cselect_b32 s26, 33280, 0
	s_sub_u32 s42, s12, s26
	s_cmp_ge_u32 s42, 12288
	s_cbranch_scc1 .Ltrb_m44
	s_mul_i32 s43, s42, 43691
	s_lshr_b32 s43, s43, 24
	s_mul_i32 s26, s43, 384
	s_sub_u32 s44, s42, s26
	s_mov_b32 s14, s0
	s_mov_b32 s15, s1
	s_mov_b32 s36, 0xc000
	s_mov_b32 s37, 0x6000000
	s_mov_b32 s38, 0x0
	s_mov_b32 s39, 0x3000000
	s_mov_b32 s40, 0x1000
	s_branch .Ltrb_dec_done43

.Ltrb_dec_done43:
	s_mul_i32 s26, s41, s37
	s_lshl_b32 s27, s43, 6
	s_mul_i32 s27, s27, s36
	s_add_u32 s26, s26, s27
	s_lshl_b32 s27, s44, 7
	s_add_u32 s26, s26, s27
	s_add_u32 s14, s14, s26
	s_addc_u32 s15, s15, 0
	s_mul_i32 s26, s41, s39
	s_add_u32 s26, s26, s38
	s_lshl_b32 s27, s44, 5
	s_mul_i32 s27, s27, s40
	s_add_u32 s26, s26, s27
	s_lshl_b32 s27, s43, 7
	s_add_u32 s26, s26, s27
	s_add_u32 s20, s90, s26
	s_addc_u32 s21, s91, 0
	s_mov_b32 s23, s40
	v_mad_u32_u24 v7, v5, s36, v6
	s_lshl_b32 s45, s36, 3
	global_load_dwordx4 v[42:45], v7, s[14:15] nt
	s_add_u32 s14, s14, s45
	s_addc_u32 s15, s15, 0
	global_load_dwordx4 v[46:49], v7, s[14:15] nt
	s_add_u32 s14, s14, s45
	s_addc_u32 s15, s15, 0
	global_load_dwordx4 v[50:53], v7, s[14:15] nt
	s_add_u32 s14, s14, s45
	s_addc_u32 s15, s15, 0
	global_load_dwordx4 v[54:57], v7, s[14:15] nt
	s_add_u32 s14, s14, s45
	s_addc_u32 s15, s15, 0
	global_load_dwordx4 v[58:61], v7, s[14:15] nt
	s_add_u32 s14, s14, s45
	s_addc_u32 s15, s15, 0
	global_load_dwordx4 v[62:65], v7, s[14:15] nt
	s_add_u32 s14, s14, s45
	s_addc_u32 s15, s15, 0
	global_load_dwordx4 v[66:69], v7, s[14:15] nt
	s_add_u32 s14, s14, s45
	s_addc_u32 s15, s15, 0
	global_load_dwordx4 v[70:73], v7, s[14:15] nt
	s_add_u32 s25, s25, 1
	s_add_u32 s12, s12, 2048
	s_waitcnt vmcnt(32)
	s_branch .Ltrb_after42

.Ltrb_after42:
	ds_write_b32 v1, v114 offset:0
	ds_write_b32 v1, v115 offset:4
	ds_write_b32 v1, v116 offset:8
	ds_write_b32 v1, v117 offset:12
	ds_write_b32 v1, v118 offset:1056
	ds_write_b32 v1, v119 offset:1060
	ds_write_b32 v1, v120 offset:1064
	ds_write_b32 v1, v121 offset:1068
	ds_write_b32 v1, v122 offset:2112
	ds_write_b32 v1, v123 offset:2116
	ds_write_b32 v1, v124 offset:2120
	ds_write_b32 v1, v125 offset:2124
	ds_write_b32 v1, v126 offset:3168
	ds_write_b32 v1, v127 offset:3172
	ds_write_b32 v1, v128 offset:3176
	ds_write_b32 v1, v129 offset:3180
	ds_write_b32 v1, v130 offset:4224
	ds_write_b32 v1, v131 offset:4228
	ds_write_b32 v1, v132 offset:4232
	ds_write_b32 v1, v133 offset:4236
	ds_write_b32 v1, v134 offset:5280
	ds_write_b32 v1, v135 offset:5284
	ds_write_b32 v1, v136 offset:5288
	ds_write_b32 v1, v137 offset:5292
	ds_write_b32 v1, v138 offset:6336
	ds_write_b32 v1, v139 offset:6340
	ds_write_b32 v1, v140 offset:6344
	ds_write_b32 v1, v141 offset:6348
	ds_write_b32 v1, v142 offset:7392
	ds_write_b32 v1, v143 offset:7396
	ds_write_b32 v1, v144 offset:7400
	ds_write_b32 v1, v145 offset:7404
	v_mad_u32_u24 v9, v5, s52, v6
	s_lshl_b32 s46, s52, 3
	s_waitcnt lgkmcnt(0)
	ds_read_b32 v74, v2 offset:0
	ds_read_b32 v75, v2 offset:132
	ds_read_b32 v76, v2 offset:264
	ds_read_b32 v77, v2 offset:396
	ds_read_b32 v78, v2 offset:528
	ds_read_b32 v79, v2 offset:660
	ds_read_b32 v80, v2 offset:792
	ds_read_b32 v81, v2 offset:924
	ds_read_b32 v82, v2 offset:32
	ds_read_b32 v83, v2 offset:164
	ds_read_b32 v84, v2 offset:296
	ds_read_b32 v85, v2 offset:428
	ds_read_b32 v86, v2 offset:560
	ds_read_b32 v87, v2 offset:692
	ds_read_b32 v88, v2 offset:824
	ds_read_b32 v89, v2 offset:956
	s_waitcnt lgkmcnt(8)
	v_cvt_pk_bf16_f32 v106, v74, v75
	v_cvt_pk_bf16_f32 v107, v76, v77
	v_cvt_pk_bf16_f32 v108, v78, v79
	v_cvt_pk_bf16_f32 v109, v80, v81
	global_store_dwordx4 v9, v[106:109], s[48:49]
	s_add_u32 s48, s48, s46
	s_addc_u32 s49, s49, 0
	ds_read_b32 v90, v2 offset:64
	ds_read_b32 v91, v2 offset:196
	ds_read_b32 v92, v2 offset:328
	ds_read_b32 v93, v2 offset:460
	ds_read_b32 v94, v2 offset:592
	ds_read_b32 v95, v2 offset:724
	ds_read_b32 v96, v2 offset:856
	ds_read_b32 v97, v2 offset:988
	s_waitcnt lgkmcnt(8)
	v_cvt_pk_bf16_f32 v110, v82, v83
	v_cvt_pk_bf16_f32 v111, v84, v85
	v_cvt_pk_bf16_f32 v112, v86, v87
	v_cvt_pk_bf16_f32 v113, v88, v89
	global_store_dwordx4 v9, v[110:113], s[48:49]
	s_add_u32 s48, s48, s46
	s_addc_u32 s49, s49, 0
	ds_read_b32 v98, v2 offset:96
	ds_read_b32 v99, v2 offset:228
	ds_read_b32 v100, v2 offset:360
	ds_read_b32 v101, v2 offset:492
	ds_read_b32 v102, v2 offset:624
	ds_read_b32 v103, v2 offset:756
	ds_read_b32 v104, v2 offset:888
	ds_read_b32 v105, v2 offset:1020
	s_waitcnt lgkmcnt(8)
	v_cvt_pk_bf16_f32 v106, v90, v91
	v_cvt_pk_bf16_f32 v107, v92, v93
	v_cvt_pk_bf16_f32 v108, v94, v95
	v_cvt_pk_bf16_f32 v109, v96, v97
	global_store_dwordx4 v9, v[106:109], s[48:49]
	s_add_u32 s48, s48, s46
	s_addc_u32 s49, s49, 0
	s_waitcnt lgkmcnt(0)
	v_cvt_pk_bf16_f32 v110, v98, v99
	v_cvt_pk_bf16_f32 v111, v100, v101
	v_cvt_pk_bf16_f32 v112, v102, v103
	v_cvt_pk_bf16_f32 v113, v104, v105
	global_store_dwordx4 v9, v[110:113], s[48:49]
	s_sub_u32 s25, s25, 1
	s_cmp_eq_u32 s25, 0
	s_cbranch_scc1 .Ltrb_done
	s_cmp_lt_u32 s12, 12288
	s_cbranch_scc0 .Ltrb_nonext50
	s_cmp_ge_u32 s12, 33280
	s_cselect_b32 s41, 1, 0
	s_cselect_b32 s26, 33280, 0
	s_sub_u32 s42, s12, s26
	s_cmp_ge_u32 s42, 12288
	s_cbranch_scc1 .Ltrb_m53
	s_mul_i32 s43, s42, 43691
	s_lshr_b32 s43, s43, 24
	s_mul_i32 s26, s43, 384
	s_sub_u32 s44, s42, s26
	s_mov_b32 s14, s0
	s_mov_b32 s15, s1
	s_mov_b32 s36, 0xc000
	s_mov_b32 s37, 0x6000000
	s_mov_b32 s38, 0x0
	s_mov_b32 s39, 0x3000000
	s_mov_b32 s40, 0x1000
	s_branch .Ltrb_dec_done52

.Ltrb_dec_done52:
	s_mul_i32 s26, s41, s37
	s_lshl_b32 s27, s43, 6
	s_mul_i32 s27, s27, s36
	s_add_u32 s26, s26, s27
	s_lshl_b32 s27, s44, 7
	s_add_u32 s26, s26, s27
	s_add_u32 s14, s14, s26
	s_addc_u32 s15, s15, 0
	s_mul_i32 s26, s41, s39
	s_add_u32 s26, s26, s38
	s_lshl_b32 s27, s44, 5
	s_mul_i32 s27, s27, s40
	s_add_u32 s26, s26, s27
	s_lshl_b32 s27, s43, 7
	s_add_u32 s26, s26, s27
	s_add_u32 s48, s90, s26
	s_addc_u32 s49, s91, 0
	s_mov_b32 s52, s40
	v_mad_u32_u24 v7, v5, s36, v6
	s_lshl_b32 s45, s36, 3
	global_load_dwordx4 v[114:117], v7, s[14:15] nt
	s_add_u32 s14, s14, s45
	s_addc_u32 s15, s15, 0
	global_load_dwordx4 v[118:121], v7, s[14:15] nt
	s_add_u32 s14, s14, s45
	s_addc_u32 s15, s15, 0
	global_load_dwordx4 v[122:125], v7, s[14:15] nt
	s_add_u32 s14, s14, s45
	s_addc_u32 s15, s15, 0
	global_load_dwordx4 v[126:129], v7, s[14:15] nt
	s_add_u32 s14, s14, s45
	s_addc_u32 s15, s15, 0
	global_load_dwordx4 v[130:133], v7, s[14:15] nt
	s_add_u32 s14, s14, s45
	s_addc_u32 s15, s15, 0
	global_load_dwordx4 v[134:137], v7, s[14:15] nt
	s_add_u32 s14, s14, s45
	s_addc_u32 s15, s15, 0
	global_load_dwordx4 v[138:141], v7, s[14:15] nt
	s_add_u32 s14, s14, s45
	s_addc_u32 s15, s15, 0
	global_load_dwordx4 v[142:145], v7, s[14:15] nt
	s_add_u32 s25, s25, 1
	s_add_u32 s12, s12, 2048
	s_waitcnt vmcnt(36)
	s_branch .Ltrb_after51

.Ltrb_after51:
	ds_write_b32 v1, v160 offset:0
	ds_write_b32 v1, v161 offset:4
	ds_write_b32 v1, v162 offset:8
	ds_write_b32 v1, v163 offset:12
	ds_write_b32 v1, v164 offset:1056
	ds_write_b32 v1, v165 offset:1060
	ds_write_b32 v1, v166 offset:1064
	ds_write_b32 v1, v167 offset:1068
	ds_write_b32 v1, v168 offset:2112
	ds_write_b32 v1, v169 offset:2116
	ds_write_b32 v1, v170 offset:2120
	ds_write_b32 v1, v171 offset:2124
	ds_write_b32 v1, v172 offset:3168
	ds_write_b32 v1, v173 offset:3172
	ds_write_b32 v1, v174 offset:3176
	ds_write_b32 v1, v175 offset:3180
	ds_write_b32 v1, v176 offset:4224
	ds_write_b32 v1, v177 offset:4228
	ds_write_b32 v1, v178 offset:4232
	ds_write_b32 v1, v179 offset:4236
	ds_write_b32 v1, v180 offset:5280
	ds_write_b32 v1, v181 offset:5284
	ds_write_b32 v1, v182 offset:5288
	ds_write_b32 v1, v183 offset:5292
	ds_write_b32 v1, v184 offset:6336
	ds_write_b32 v1, v185 offset:6340
	ds_write_b32 v1, v186 offset:6344
	ds_write_b32 v1, v187 offset:6348
	ds_write_b32 v1, v188 offset:7392
	ds_write_b32 v1, v189 offset:7396
	ds_write_b32 v1, v190 offset:7400
	ds_write_b32 v1, v191 offset:7404
	v_mad_u32_u24 v9, v5, s53, v6
	s_lshl_b32 s46, s53, 3
	s_waitcnt lgkmcnt(0)
	ds_read_b32 v74, v2 offset:0
	ds_read_b32 v75, v2 offset:132
	ds_read_b32 v76, v2 offset:264
	ds_read_b32 v77, v2 offset:396
	ds_read_b32 v78, v2 offset:528
	ds_read_b32 v79, v2 offset:660
	ds_read_b32 v80, v2 offset:792
	ds_read_b32 v81, v2 offset:924
	ds_read_b32 v82, v2 offset:32
	ds_read_b32 v83, v2 offset:164
	ds_read_b32 v84, v2 offset:296
	ds_read_b32 v85, v2 offset:428
	ds_read_b32 v86, v2 offset:560
	ds_read_b32 v87, v2 offset:692
	ds_read_b32 v88, v2 offset:824
	ds_read_b32 v89, v2 offset:956
	s_waitcnt lgkmcnt(8)
	v_cvt_pk_bf16_f32 v106, v74, v75
	v_cvt_pk_bf16_f32 v107, v76, v77
	v_cvt_pk_bf16_f32 v108, v78, v79
	v_cvt_pk_bf16_f32 v109, v80, v81
	global_store_dwordx4 v9, v[106:109], s[50:51]
	s_add_u32 s50, s50, s46
	s_addc_u32 s51, s51, 0
	ds_read_b32 v90, v2 offset:64
	ds_read_b32 v91, v2 offset:196
	ds_read_b32 v92, v2 offset:328
	ds_read_b32 v93, v2 offset:460
	ds_read_b32 v94, v2 offset:592
	ds_read_b32 v95, v2 offset:724
	ds_read_b32 v96, v2 offset:856
	ds_read_b32 v97, v2 offset:988
	s_waitcnt lgkmcnt(8)
	v_cvt_pk_bf16_f32 v110, v82, v83
	v_cvt_pk_bf16_f32 v111, v84, v85
	v_cvt_pk_bf16_f32 v112, v86, v87
	v_cvt_pk_bf16_f32 v113, v88, v89
	global_store_dwordx4 v9, v[110:113], s[50:51]
	s_add_u32 s50, s50, s46
	s_addc_u32 s51, s51, 0
	ds_read_b32 v98, v2 offset:96
	ds_read_b32 v99, v2 offset:228
	ds_read_b32 v100, v2 offset:360
	ds_read_b32 v101, v2 offset:492
	ds_read_b32 v102, v2 offset:624
	ds_read_b32 v103, v2 offset:756
	ds_read_b32 v104, v2 offset:888
	ds_read_b32 v105, v2 offset:1020
	s_waitcnt lgkmcnt(8)
	v_cvt_pk_bf16_f32 v106, v90, v91
	v_cvt_pk_bf16_f32 v107, v92, v93
	v_cvt_pk_bf16_f32 v108, v94, v95
	v_cvt_pk_bf16_f32 v109, v96, v97
	global_store_dwordx4 v9, v[106:109], s[50:51]
	s_add_u32 s50, s50, s46
	s_addc_u32 s51, s51, 0
	s_waitcnt lgkmcnt(0)
	v_cvt_pk_bf16_f32 v110, v98, v99
	v_cvt_pk_bf16_f32 v111, v100, v101
	v_cvt_pk_bf16_f32 v112, v102, v103
	v_cvt_pk_bf16_f32 v113, v104, v105
	global_store_dwordx4 v9, v[110:113], s[50:51]
	s_sub_u32 s25, s25, 1
	s_cmp_eq_u32 s25, 0
	s_cbranch_scc1 .Ltrb_done
.Ltrb_loop:
	s_cmp_lt_u32 s12, 12288
	s_cbranch_scc0 .Ltrb_nonext59
	s_cmp_ge_u32 s12, 33280
	s_cselect_b32 s41, 1, 0
	s_cselect_b32 s26, 33280, 0
	s_sub_u32 s42, s12, s26
	s_cmp_ge_u32 s42, 12288
	s_cbranch_scc1 .Ltrb_m62
	s_mul_i32 s43, s42, 43691
	s_lshr_b32 s43, s43, 24
	s_mul_i32 s26, s43, 384
	s_sub_u32 s44, s42, s26
	s_mov_b32 s14, s0
	s_mov_b32 s15, s1
	s_mov_b32 s36, 0xc000
	s_mov_b32 s37, 0x6000000
	s_mov_b32 s38, 0x0
	s_mov_b32 s39, 0x3000000
	s_mov_b32 s40, 0x1000
	s_branch .Ltrb_dec_done61

.Ltrb_dec_done61:
	s_mul_i32 s26, s41, s37
	s_lshl_b32 s27, s43, 6
	s_mul_i32 s27, s27, s36
	s_add_u32 s26, s26, s27
	s_lshl_b32 s27, s44, 7
	s_add_u32 s26, s26, s27
	s_add_u32 s14, s14, s26
	s_addc_u32 s15, s15, 0
	s_mul_i32 s26, s41, s39
	s_add_u32 s26, s26, s38
	s_lshl_b32 s27, s44, 5
	s_mul_i32 s27, s27, s40
	s_add_u32 s26, s26, s27
	s_lshl_b32 s27, s43, 7
	s_add_u32 s26, s26, s27
	s_add_u32 s50, s90, s26
	s_addc_u32 s51, s91, 0
	s_mov_b32 s53, s40
	v_mad_u32_u24 v7, v5, s36, v6
	s_lshl_b32 s45, s36, 3
	global_load_dwordx4 v[160:163], v7, s[14:15] nt
	s_add_u32 s14, s14, s45
	s_addc_u32 s15, s15, 0
	global_load_dwordx4 v[164:167], v7, s[14:15] nt
	s_add_u32 s14, s14, s45
	s_addc_u32 s15, s15, 0
	global_load_dwordx4 v[168:171], v7, s[14:15] nt
	s_add_u32 s14, s14, s45
	s_addc_u32 s15, s15, 0
	global_load_dwordx4 v[172:175], v7, s[14:15] nt
	s_add_u32 s14, s14, s45
	s_addc_u32 s15, s15, 0
	global_load_dwordx4 v[176:179], v7, s[14:15] nt
	s_add_u32 s14, s14, s45
	s_addc_u32 s15, s15, 0
	global_load_dwordx4 v[180:183], v7, s[14:15] nt
	s_add_u32 s14, s14, s45
	s_addc_u32 s15, s15, 0
	global_load_dwordx4 v[184:187], v7, s[14:15] nt
	s_add_u32 s14, s14, s45
	s_addc_u32 s15, s15, 0
	global_load_dwordx4 v[188:191], v7, s[14:15] nt
	s_add_u32 s25, s25, 1
	s_add_u32 s12, s12, 2048
	s_waitcnt vmcnt(36)
	s_branch .Ltrb_after60

.Ltrb_dec_done70:
	s_mul_i32 s26, s41, s37
	s_lshl_b32 s27, s43, 6
	s_mul_i32 s27, s27, s36
	s_add_u32 s26, s26, s27
	s_lshl_b32 s27, s44, 7
	s_add_u32 s26, s26, s27
	s_add_u32 s14, s14, s26
	s_addc_u32 s15, s15, 0
	s_mul_i32 s26, s41, s39
	s_add_u32 s26, s26, s38
	s_lshl_b32 s27, s44, 5
	s_mul_i32 s27, s27, s40
	s_add_u32 s26, s26, s27
	s_lshl_b32 s27, s43, 7
	s_add_u32 s26, s26, s27
	s_add_u32 s18, s90, s26
	s_addc_u32 s19, s91, 0
	s_mov_b32 s22, s40
	v_mad_u32_u24 v7, v5, s36, v6
	s_lshl_b32 s45, s36, 3
	global_load_dwordx4 v[10:13], v7, s[14:15] nt
	s_add_u32 s14, s14, s45
	s_addc_u32 s15, s15, 0
	global_load_dwordx4 v[14:17], v7, s[14:15] nt
	s_add_u32 s14, s14, s45
	s_addc_u32 s15, s15, 0
	global_load_dwordx4 v[18:21], v7, s[14:15] nt
	s_add_u32 s14, s14, s45
	s_addc_u32 s15, s15, 0
	global_load_dwordx4 v[22:25], v7, s[14:15] nt
	s_add_u32 s14, s14, s45
	s_addc_u32 s15, s15, 0
	global_load_dwordx4 v[26:29], v7, s[14:15] nt
	s_add_u32 s14, s14, s45
	s_addc_u32 s15, s15, 0
	global_load_dwordx4 v[30:33], v7, s[14:15] nt
	s_add_u32 s14, s14, s45
	s_addc_u32 s15, s15, 0
	global_load_dwordx4 v[34:37], v7, s[14:15] nt
	s_add_u32 s14, s14, s45
	s_addc_u32 s15, s15, 0
	global_load_dwordx4 v[38:41], v7, s[14:15] nt
	s_add_u32 s25, s25, 1
	s_add_u32 s12, s12, 2048
	s_waitcnt vmcnt(36)
	s_branch .Ltrb_after69

.Ltrb_dec_done79:
	s_mul_i32 s26, s41, s37
	s_lshl_b32 s27, s43, 6
	s_mul_i32 s27, s27, s36
	s_add_u32 s26, s26, s27
	s_lshl_b32 s27, s44, 7
	s_add_u32 s26, s26, s27
	s_add_u32 s14, s14, s26
	s_addc_u32 s15, s15, 0
	s_mul_i32 s26, s41, s39
	s_add_u32 s26, s26, s38
	s_lshl_b32 s27, s44, 5
	s_mul_i32 s27, s27, s40
	s_add_u32 s26, s26, s27
	s_lshl_b32 s27, s43, 7
	s_add_u32 s26, s26, s27
	s_add_u32 s20, s90, s26
	s_addc_u32 s21, s91, 0
	s_mov_b32 s23, s40
	v_mad_u32_u24 v7, v5, s36, v6
	s_lshl_b32 s45, s36, 3
	global_load_dwordx4 v[42:45], v7, s[14:15] nt
	s_add_u32 s14, s14, s45
	s_addc_u32 s15, s15, 0
	global_load_dwordx4 v[46:49], v7, s[14:15] nt
	s_add_u32 s14, s14, s45
	s_addc_u32 s15, s15, 0
	global_load_dwordx4 v[50:53], v7, s[14:15] nt
	s_add_u32 s14, s14, s45
	s_addc_u32 s15, s15, 0
	global_load_dwordx4 v[54:57], v7, s[14:15] nt
	s_add_u32 s14, s14, s45
	s_addc_u32 s15, s15, 0
	global_load_dwordx4 v[58:61], v7, s[14:15] nt
	s_add_u32 s14, s14, s45
	s_addc_u32 s15, s15, 0
	global_load_dwordx4 v[62:65], v7, s[14:15] nt
	s_add_u32 s14, s14, s45
	s_addc_u32 s15, s15, 0
	global_load_dwordx4 v[66:69], v7, s[14:15] nt
	s_add_u32 s14, s14, s45
	s_addc_u32 s15, s15, 0
	global_load_dwordx4 v[70:73], v7, s[14:15] nt
	s_add_u32 s25, s25, 1
	s_add_u32 s12, s12, 2048
	s_waitcnt vmcnt(36)
	s_branch .Ltrb_after78

.Ltrb_after87:
	ds_write_b32 v1, v160 offset:0
	ds_write_b32 v1, v161 offset:4
	ds_write_b32 v1, v162 offset:8
	ds_write_b32 v1, v163 offset:12
	ds_write_b32 v1, v164 offset:1056
	ds_write_b32 v1, v165 offset:1060
	ds_write_b32 v1, v166 offset:1064
	ds_write_b32 v1, v167 offset:1068
	ds_write_b32 v1, v168 offset:2112
	ds_write_b32 v1, v169 offset:2116
	ds_write_b32 v1, v170 offset:2120
	ds_write_b32 v1, v171 offset:2124
	ds_write_b32 v1, v172 offset:3168
	ds_write_b32 v1, v173 offset:3172
	ds_write_b32 v1, v174 offset:3176
	ds_write_b32 v1, v175 offset:3180
	ds_write_b32 v1, v176 offset:4224
	ds_write_b32 v1, v177 offset:4228
	ds_write_b32 v1, v178 offset:4232
	ds_write_b32 v1, v179 offset:4236
	ds_write_b32 v1, v180 offset:5280
	ds_write_b32 v1, v181 offset:5284
	ds_write_b32 v1, v182 offset:5288
	ds_write_b32 v1, v183 offset:5292
	ds_write_b32 v1, v184 offset:6336
	ds_write_b32 v1, v185 offset:6340
	ds_write_b32 v1, v186 offset:6344
	ds_write_b32 v1, v187 offset:6348
	ds_write_b32 v1, v188 offset:7392
	ds_write_b32 v1, v189 offset:7396
	ds_write_b32 v1, v190 offset:7400
	ds_write_b32 v1, v191 offset:7404
	v_mad_u32_u24 v9, v5, s53, v6
	s_lshl_b32 s46, s53, 3
	s_waitcnt lgkmcnt(0)
	ds_read_b32 v74, v2 offset:0
	ds_read_b32 v75, v2 offset:132
	ds_read_b32 v76, v2 offset:264
	ds_read_b32 v77, v2 offset:396
	ds_read_b32 v78, v2 offset:528
	ds_read_b32 v79, v2 offset:660
	ds_read_b32 v80, v2 offset:792
	ds_read_b32 v81, v2 offset:924
	ds_read_b32 v82, v2 offset:32
	ds_read_b32 v83, v2 offset:164
	ds_read_b32 v84, v2 offset:296
	ds_read_b32 v85, v2 offset:428
	ds_read_b32 v86, v2 offset:560
	ds_read_b32 v87, v2 offset:692
	ds_read_b32 v88, v2 offset:824
	ds_read_b32 v89, v2 offset:956
	s_waitcnt lgkmcnt(8)
	v_cvt_pk_bf16_f32 v106, v74, v75
	v_cvt_pk_bf16_f32 v107, v76, v77
	v_cvt_pk_bf16_f32 v108, v78, v79
	v_cvt_pk_bf16_f32 v109, v80, v81
	global_store_dwordx4 v9, v[106:109], s[50:51]
	s_add_u32 s50, s50, s46
	s_addc_u32 s51, s51, 0
	ds_read_b32 v90, v2 offset:64
	ds_read_b32 v91, v2 offset:196
	ds_read_b32 v92, v2 offset:328
	ds_read_b32 v93, v2 offset:460
	ds_read_b32 v94, v2 offset:592
	ds_read_b32 v95, v2 offset:724
	ds_read_b32 v96, v2 offset:856
	ds_read_b32 v97, v2 offset:988
	s_waitcnt lgkmcnt(8)
	v_cvt_pk_bf16_f32 v110, v82, v83
	v_cvt_pk_bf16_f32 v111, v84, v85
	v_cvt_pk_bf16_f32 v112, v86, v87
	v_cvt_pk_bf16_f32 v113, v88, v89
	global_store_dwordx4 v9, v[110:113], s[50:51]
	s_add_u32 s50, s50, s46
	s_addc_u32 s51, s51, 0
	ds_read_b32 v98, v2 offset:96
	ds_read_b32 v99, v2 offset:228
	ds_read_b32 v100, v2 offset:360
	ds_read_b32 v101, v2 offset:492
	ds_read_b32 v102, v2 offset:624
	ds_read_b32 v103, v2 offset:756
	ds_read_b32 v104, v2 offset:888
	ds_read_b32 v105, v2 offset:1020
	s_waitcnt lgkmcnt(8)
	v_cvt_pk_bf16_f32 v106, v90, v91
	v_cvt_pk_bf16_f32 v107, v92, v93
	v_cvt_pk_bf16_f32 v108, v94, v95
	v_cvt_pk_bf16_f32 v109, v96, v97
	global_store_dwordx4 v9, v[106:109], s[50:51]
	s_add_u32 s50, s50, s46
	s_addc_u32 s51, s51, 0
	s_waitcnt lgkmcnt(0)
	v_cvt_pk_bf16_f32 v110, v98, v99
	v_cvt_pk_bf16_f32 v111, v100, v101
	v_cvt_pk_bf16_f32 v112, v102, v103
	v_cvt_pk_bf16_f32 v113, v104, v105
	global_store_dwordx4 v9, v[110:113], s[50:51]
	s_sub_u32 s25, s25, 1
	s_cmp_eq_u32 s25, 0
	s_cbranch_scc1 .Ltrb_done
	s_branch .Ltrb_loop

.Ltrp1_B:
	s_cmp_ge_u32 s96, 128
	s_cbranch_scc1 .LBB0_257
	s_load_dwordx2 s[0:1], s[92:93], 0x58
	s_load_dwordx2 s[2:3], s[92:93], 0xb8
	s_load_dwordx2 s[4:5], s[92:93], 0xc0
	s_load_dwordx2 s[6:7], s[92:93], 0xc8
	s_load_dwordx2 s[8:9], s[92:93], 0xd0
	s_load_dwordx2 s[10:11], s[92:93], 0xe8
	v_and_b32_e32 v74, 63, v154
	v_lshrrev_b32_e32 v75, 6, v154
	v_mul_u32_u24_e32 v75, 0x2100, v75
	v_lshrrev_b32_e32 v3, 5, v74
	v_and_b32_e32 v4, 31, v74
	v_lshlrev_b32_e32 v4, 2, v4
	v_lshrrev_b32_e32 v5, 3, v74
	v_and_b32_e32 v6, 7, v74
	v_mul_u32_u24_e32 v2, 264, v6
	v_add_u32_e32 v2, v2, v5
	v_lshl_add_u32 v2, v2, 2, v75
	v_lshlrev_b32_e32 v6, 4, v6
	v_mul_u32_u24_e32 v1, 132, v5
	v_add3_u32 v1, v1, v6, v75
	v_readfirstlane_b32 s13, v154
	s_lshr_b32 s13, s13, 6
	s_lshl_b32 s26, s96, 3
	s_add_u32 s13, s13, s26
	s_mov_b32 s12, s13
	s_waitcnt lgkmcnt(0)
	s_mov_b32 s25, 0
	s_cmp_ge_u32 s12, 12288
	s_cbranch_scc1 .Ltrc_pro_end1
	s_cmp_ge_u32 s12, 33280
	s_cselect_b32 s41, 1, 0
	s_cselect_b32 s26, 33280, 0
	s_sub_u32 s42, s12, s26
	s_cmp_ge_u32 s42, 12288
	s_cbranch_scc1 .Ltrc_m3
	s_mul_i32 s43, s42, 43691
	s_lshr_b32 s43, s43, 24
	s_mul_i32 s26, s43, 384
	s_sub_u32 s44, s42, s26
	s_mov_b32 s14, s0
	s_mov_b32 s15, s1
	s_mov_b32 s36, 0xc000
	s_mov_b32 s37, 0x6000000
	s_mov_b32 s38, 0x0
	s_mov_b32 s39, 0x3000000
	s_mov_b32 s40, 0x1000
	s_branch .Ltrc_dec_done2

.LBB0_493:
	s_cmp_lt_u32 s96, 160
	s_cbranch_scc1 .Lmix0_skip
	s_load_dwordx2 s[0:1], s[92:93], 0x58
	s_load_dwordx2 s[2:3], s[92:93], 0xb8
	s_load_dwordx2 s[4:5], s[92:93], 0xc0
	s_load_dwordx2 s[6:7], s[92:93], 0xc8
	s_load_dwordx2 s[8:9], s[92:93], 0xd0
	s_load_dwordx2 s[10:11], s[92:93], 0xe8
	v_and_b32_e32 v74, 63, v154
	v_lshrrev_b32_e32 v75, 6, v154
	v_mul_u32_u24_e32 v75, 0x2100, v75
	v_lshrrev_b32_e32 v3, 5, v74
	v_and_b32_e32 v4, 31, v74
	v_lshlrev_b32_e32 v4, 2, v4
	v_lshrrev_b32_e32 v5, 3, v74
	v_and_b32_e32 v6, 7, v74
	v_mul_u32_u24_e32 v2, 264, v6
	v_add_u32_e32 v2, v2, v5
	v_lshl_add_u32 v2, v2, 2, v75
	v_lshlrev_b32_e32 v6, 4, v6
	v_mul_u32_u24_e32 v1, 132, v5
	v_add3_u32 v1, v1, v6, v75
	v_readfirstlane_b32 s13, v154
	s_lshr_b32 s13, s13, 6
	s_lshl_b32 s26, s96, 3
	s_add_u32 s13, s13, s26
	s_sub_u32 s12, s13, 1280
	s_add_u32 s12, s12, 12288
	s_waitcnt lgkmcnt(0)
	s_mov_b32 s25, 0
	s_cmp_ge_u32 s12, 33280
	s_cbranch_scc1 .Ltrm_pro_end1
	s_cmp_ge_u32 s12, 33280
	s_cselect_b32 s41, 1, 0
	s_cselect_b32 s26, 33280, 0
	s_sub_u32 s42, s12, s26
	s_cmp_ge_u32 s42, 12288
	s_cbranch_scc1 .Ltrm_m3
	s_mul_i32 s43, s42, 43691
	s_lshr_b32 s43, s43, 24
	s_mul_i32 s26, s43, 384
	s_sub_u32 s44, s42, s26
	s_mov_b32 s14, s0
	s_mov_b32 s15, s1
	s_mov_b32 s36, 0xc000
	s_mov_b32 s37, 0x6000000
	s_mov_b32 s38, 0x0
	s_mov_b32 s39, 0x3000000
	s_mov_b32 s40, 0x1000
	s_branch .Ltrm_dec_done2

.Ltrm_dec_done2:
	s_mul_i32 s26, s41, s37
	s_lshl_b32 s27, s43, 6
	s_mul_i32 s27, s27, s36
	s_add_u32 s26, s26, s27
	s_lshl_b32 s27, s44, 7
	s_add_u32 s26, s26, s27
	s_add_u32 s14, s14, s26
	s_addc_u32 s15, s15, 0
	s_mul_i32 s26, s41, s39
	s_add_u32 s26, s26, s38
	s_lshl_b32 s27, s44, 5
	s_mul_i32 s27, s27, s40
	s_add_u32 s26, s26, s27
	s_lshl_b32 s27, s43, 7
	s_add_u32 s26, s26, s27
	s_add_u32 s18, s90, s26
	s_addc_u32 s19, s91, 0
	s_mov_b32 s22, s40
	v_mad_u32_u24 v7, v5, s36, v6
	s_lshl_b32 s45, s36, 3
	global_load_dwordx4 v[10:13], v7, s[14:15] nt
	s_add_u32 s14, s14, s45
	s_addc_u32 s15, s15, 0
	global_load_dwordx4 v[14:17], v7, s[14:15] nt
	s_add_u32 s14, s14, s45
	s_addc_u32 s15, s15, 0
	global_load_dwordx4 v[18:21], v7, s[14:15] nt
	s_add_u32 s14, s14, s45
	s_addc_u32 s15, s15, 0
	global_load_dwordx4 v[22:25], v7, s[14:15] nt
	s_add_u32 s14, s14, s45
	s_addc_u32 s15, s15, 0
	global_load_dwordx4 v[26:29], v7, s[14:15] nt
	s_add_u32 s14, s14, s45
	s_addc_u32 s15, s15, 0
	global_load_dwordx4 v[30:33], v7, s[14:15] nt
	s_add_u32 s14, s14, s45
	s_addc_u32 s15, s15, 0
	global_load_dwordx4 v[34:37], v7, s[14:15] nt
	s_add_u32 s14, s14, s45
	s_addc_u32 s15, s15, 0
	global_load_dwordx4 v[38:41], v7, s[14:15] nt
	s_add_u32 s25, s25, 1
	s_add_u32 s12, s12, 768
	s_cmp_ge_u32 s12, 33280
	s_cbranch_scc1 .Ltrm_pro_end1
	s_cmp_ge_u32 s12, 33280
	s_cselect_b32 s41, 1, 0
	s_cselect_b32 s26, 33280, 0
	s_sub_u32 s42, s12, s26
	s_cmp_ge_u32 s42, 12288
	s_cbranch_scc1 .Ltrm_m10
	s_mul_i32 s43, s42, 43691
	s_lshr_b32 s43, s43, 24
	s_mul_i32 s26, s43, 384
	s_sub_u32 s44, s42, s26
	s_mov_b32 s14, s0
	s_mov_b32 s15, s1
	s_mov_b32 s36, 0xc000
	s_mov_b32 s37, 0x6000000
	s_mov_b32 s38, 0x0
	s_mov_b32 s39, 0x3000000
	s_mov_b32 s40, 0x1000
	s_branch .Ltrm_dec_done9

.Ltrm_dec_done9:
	s_mul_i32 s26, s41, s37
	s_lshl_b32 s27, s43, 6
	s_mul_i32 s27, s27, s36
	s_add_u32 s26, s26, s27
	s_lshl_b32 s27, s44, 7
	s_add_u32 s26, s26, s27
	s_add_u32 s14, s14, s26
	s_addc_u32 s15, s15, 0
	s_mul_i32 s26, s41, s39
	s_add_u32 s26, s26, s38
	s_lshl_b32 s27, s44, 5
	s_mul_i32 s27, s27, s40
	s_add_u32 s26, s26, s27
	s_lshl_b32 s27, s43, 7
	s_add_u32 s26, s26, s27
	s_add_u32 s20, s90, s26
	s_addc_u32 s21, s91, 0
	s_mov_b32 s23, s40
	v_mad_u32_u24 v7, v5, s36, v6
	s_lshl_b32 s45, s36, 3
	global_load_dwordx4 v[42:45], v7, s[14:15] nt
	s_add_u32 s14, s14, s45
	s_addc_u32 s15, s15, 0
	global_load_dwordx4 v[46:49], v7, s[14:15] nt
	s_add_u32 s14, s14, s45
	s_addc_u32 s15, s15, 0
	global_load_dwordx4 v[50:53], v7, s[14:15] nt
	s_add_u32 s14, s14, s45
	s_addc_u32 s15, s15, 0
	global_load_dwordx4 v[54:57], v7, s[14:15] nt
	s_add_u32 s14, s14, s45
	s_addc_u32 s15, s15, 0
	global_load_dwordx4 v[58:61], v7, s[14:15] nt
	s_add_u32 s14, s14, s45
	s_addc_u32 s15, s15, 0
	global_load_dwordx4 v[62:65], v7, s[14:15] nt
	s_add_u32 s14, s14, s45
	s_addc_u32 s15, s15, 0
	global_load_dwordx4 v[66:69], v7, s[14:15] nt
	s_add_u32 s14, s14, s45
	s_addc_u32 s15, s15, 0
	global_load_dwordx4 v[70:73], v7, s[14:15] nt
	s_add_u32 s25, s25, 1
	s_add_u32 s12, s12, 768
	s_cmp_ge_u32 s12, 33280
	s_cbranch_scc1 .Ltrm_pro_end1
	s_cmp_ge_u32 s12, 33280
	s_cselect_b32 s41, 1, 0
	s_cselect_b32 s26, 33280, 0
	s_sub_u32 s42, s12, s26
	s_cmp_ge_u32 s42, 12288
	s_cbranch_scc1 .Ltrm_m17
	s_mul_i32 s43, s42, 43691
	s_lshr_b32 s43, s43, 24
	s_mul_i32 s26, s43, 384
	s_sub_u32 s44, s42, s26
	s_mov_b32 s14, s0
	s_mov_b32 s15, s1
	s_mov_b32 s36, 0xc000
	s_mov_b32 s37, 0x6000000
	s_mov_b32 s38, 0x0
	s_mov_b32 s39, 0x3000000
	s_mov_b32 s40, 0x1000
	s_branch .Ltrm_dec_done16

.Ltrm_dec_done16:
	s_mul_i32 s26, s41, s37
	s_lshl_b32 s27, s43, 6
	s_mul_i32 s27, s27, s36
	s_add_u32 s26, s26, s27
	s_lshl_b32 s27, s44, 7
	s_add_u32 s26, s26, s27
	s_add_u32 s14, s14, s26
	s_addc_u32 s15, s15, 0
	s_mul_i32 s26, s41, s39
	s_add_u32 s26, s26, s38
	s_lshl_b32 s27, s44, 5
	s_mul_i32 s27, s27, s40
	s_add_u32 s26, s26, s27
	s_lshl_b32 s27, s43, 7
	s_add_u32 s26, s26, s27
	s_add_u32 s48, s90, s26
	s_addc_u32 s49, s91, 0
	s_mov_b32 s52, s40
	v_mad_u32_u24 v7, v5, s36, v6
	s_lshl_b32 s45, s36, 3
	global_load_dwordx4 v[114:117], v7, s[14:15] nt
	s_add_u32 s14, s14, s45
	s_addc_u32 s15, s15, 0
	global_load_dwordx4 v[118:121], v7, s[14:15] nt
	s_add_u32 s14, s14, s45
	s_addc_u32 s15, s15, 0
	global_load_dwordx4 v[122:125], v7, s[14:15] nt
	s_add_u32 s14, s14, s45
	s_addc_u32 s15, s15, 0
	global_load_dwordx4 v[126:129], v7, s[14:15] nt
	s_add_u32 s14, s14, s45
	s_addc_u32 s15, s15, 0
	global_load_dwordx4 v[130:133], v7, s[14:15] nt
	s_add_u32 s14, s14, s45
	s_addc_u32 s15, s15, 0
	global_load_dwordx4 v[134:137], v7, s[14:15] nt
	s_add_u32 s14, s14, s45
	s_addc_u32 s15, s15, 0
	global_load_dwordx4 v[138:141], v7, s[14:15] nt
	s_add_u32 s14, s14, s45
	s_addc_u32 s15, s15, 0
	global_load_dwordx4 v[142:145], v7, s[14:15] nt
	s_add_u32 s25, s25, 1
	s_add_u32 s12, s12, 768
.Ltrm_pro_end1:
	s_cmp_eq_u32 s25, 0
	s_cbranch_scc1 .Ltrm_done
	s_cmp_lt_u32 s12, 33280
	s_cbranch_scc0 .Ltrm_nonext23
	s_cmp_ge_u32 s12, 33280
	s_cselect_b32 s41, 1, 0
	s_cselect_b32 s26, 33280, 0
	s_sub_u32 s42, s12, s26
	s_cmp_ge_u32 s42, 12288
	s_cbranch_scc1 .Ltrm_m26
	s_mul_i32 s43, s42, 43691
	s_lshr_b32 s43, s43, 24
	s_mul_i32 s26, s43, 384
	s_sub_u32 s44, s42, s26
	s_mov_b32 s14, s0
	s_mov_b32 s15, s1
	s_mov_b32 s36, 0xc000
	s_mov_b32 s37, 0x6000000
	s_mov_b32 s38, 0x0
	s_mov_b32 s39, 0x3000000
	s_mov_b32 s40, 0x1000
	s_branch .Ltrm_dec_done25

.Ltrm_dec_done25:
	s_mul_i32 s26, s41, s37
	s_lshl_b32 s27, s43, 6
	s_mul_i32 s27, s27, s36
	s_add_u32 s26, s26, s27
	s_lshl_b32 s27, s44, 7
	s_add_u32 s26, s26, s27
	s_add_u32 s14, s14, s26
	s_addc_u32 s15, s15, 0
	s_mul_i32 s26, s41, s39
	s_add_u32 s26, s26, s38
	s_lshl_b32 s27, s44, 5
	s_mul_i32 s27, s27, s40
	s_add_u32 s26, s26, s27
	s_lshl_b32 s27, s43, 7
	s_add_u32 s26, s26, s27
	s_add_u32 s50, s90, s26
	s_addc_u32 s51, s91, 0
	s_mov_b32 s53, s40
	v_mad_u32_u24 v7, v5, s36, v6
	s_lshl_b32 s45, s36, 3
	global_load_dwordx4 v[160:163], v7, s[14:15] nt
	s_add_u32 s14, s14, s45
	s_addc_u32 s15, s15, 0
	global_load_dwordx4 v[164:167], v7, s[14:15] nt
	s_add_u32 s14, s14, s45
	s_addc_u32 s15, s15, 0
	global_load_dwordx4 v[168:171], v7, s[14:15] nt
	s_add_u32 s14, s14, s45
	s_addc_u32 s15, s15, 0
	global_load_dwordx4 v[172:175], v7, s[14:15] nt
	s_add_u32 s14, s14, s45
	s_addc_u32 s15, s15, 0
	global_load_dwordx4 v[176:179], v7, s[14:15] nt
	s_add_u32 s14, s14, s45
	s_addc_u32 s15, s15, 0
	global_load_dwordx4 v[180:183], v7, s[14:15] nt
	s_add_u32 s14, s14, s45
	s_addc_u32 s15, s15, 0
	global_load_dwordx4 v[184:187], v7, s[14:15] nt
	s_add_u32 s14, s14, s45
	s_addc_u32 s15, s15, 0
	global_load_dwordx4 v[188:191], v7, s[14:15] nt
	s_add_u32 s25, s25, 1
	s_add_u32 s12, s12, 768
	s_waitcnt vmcnt(24)
	s_branch .Ltrm_after24

.Ltrm_after24:
	ds_write_b32 v1, v10 offset:0
	ds_write_b32 v1, v11 offset:4
	ds_write_b32 v1, v12 offset:8
	ds_write_b32 v1, v13 offset:12
	ds_write_b32 v1, v14 offset:1056
	ds_write_b32 v1, v15 offset:1060
	ds_write_b32 v1, v16 offset:1064
	ds_write_b32 v1, v17 offset:1068
	ds_write_b32 v1, v18 offset:2112
	ds_write_b32 v1, v19 offset:2116
	ds_write_b32 v1, v20 offset:2120
	ds_write_b32 v1, v21 offset:2124
	ds_write_b32 v1, v22 offset:3168
	ds_write_b32 v1, v23 offset:3172
	ds_write_b32 v1, v24 offset:3176
	ds_write_b32 v1, v25 offset:3180
	ds_write_b32 v1, v26 offset:4224
	ds_write_b32 v1, v27 offset:4228
	ds_write_b32 v1, v28 offset:4232
	ds_write_b32 v1, v29 offset:4236
	ds_write_b32 v1, v30 offset:5280
	ds_write_b32 v1, v31 offset:5284
	ds_write_b32 v1, v32 offset:5288
	ds_write_b32 v1, v33 offset:5292
	ds_write_b32 v1, v34 offset:6336
	ds_write_b32 v1, v35 offset:6340
	ds_write_b32 v1, v36 offset:6344
	ds_write_b32 v1, v37 offset:6348
	ds_write_b32 v1, v38 offset:7392
	ds_write_b32 v1, v39 offset:7396
	ds_write_b32 v1, v40 offset:7400
	ds_write_b32 v1, v41 offset:7404
	v_mad_u32_u24 v9, v5, s22, v6
	s_lshl_b32 s46, s22, 3
	s_waitcnt lgkmcnt(0)
	ds_read_b32 v74, v2 offset:0
	ds_read_b32 v75, v2 offset:132
	ds_read_b32 v76, v2 offset:264
	ds_read_b32 v77, v2 offset:396
	ds_read_b32 v78, v2 offset:528
	ds_read_b32 v79, v2 offset:660
	ds_read_b32 v80, v2 offset:792
	ds_read_b32 v81, v2 offset:924
	ds_read_b32 v82, v2 offset:32
	ds_read_b32 v83, v2 offset:164
	ds_read_b32 v84, v2 offset:296
	ds_read_b32 v85, v2 offset:428
	ds_read_b32 v86, v2 offset:560
	ds_read_b32 v87, v2 offset:692
	ds_read_b32 v88, v2 offset:824
	ds_read_b32 v89, v2 offset:956
	s_waitcnt lgkmcnt(8)
	v_cvt_pk_bf16_f32 v106, v74, v75
	v_cvt_pk_bf16_f32 v107, v76, v77
	v_cvt_pk_bf16_f32 v108, v78, v79
	v_cvt_pk_bf16_f32 v109, v80, v81
	global_store_dwordx4 v9, v[106:109], s[18:19]
	s_add_u32 s18, s18, s46
	s_addc_u32 s19, s19, 0
	ds_read_b32 v90, v2 offset:64
	ds_read_b32 v91, v2 offset:196
	ds_read_b32 v92, v2 offset:328
	ds_read_b32 v93, v2 offset:460
	ds_read_b32 v94, v2 offset:592
	ds_read_b32 v95, v2 offset:724
	ds_read_b32 v96, v2 offset:856
	ds_read_b32 v97, v2 offset:988
	s_waitcnt lgkmcnt(8)
	v_cvt_pk_bf16_f32 v110, v82, v83
	v_cvt_pk_bf16_f32 v111, v84, v85
	v_cvt_pk_bf16_f32 v112, v86, v87
	v_cvt_pk_bf16_f32 v113, v88, v89
	global_store_dwordx4 v9, v[110:113], s[18:19]
	s_add_u32 s18, s18, s46
	s_addc_u32 s19, s19, 0
	ds_read_b32 v98, v2 offset:96
	ds_read_b32 v99, v2 offset:228
	ds_read_b32 v100, v2 offset:360
	ds_read_b32 v101, v2 offset:492
	ds_read_b32 v102, v2 offset:624
	ds_read_b32 v103, v2 offset:756
	ds_read_b32 v104, v2 offset:888
	ds_read_b32 v105, v2 offset:1020
	s_waitcnt lgkmcnt(8)
	v_cvt_pk_bf16_f32 v106, v90, v91
	v_cvt_pk_bf16_f32 v107, v92, v93
	v_cvt_pk_bf16_f32 v108, v94, v95
	v_cvt_pk_bf16_f32 v109, v96, v97
	global_store_dwordx4 v9, v[106:109], s[18:19]
	s_add_u32 s18, s18, s46
	s_addc_u32 s19, s19, 0
	s_waitcnt lgkmcnt(0)
	v_cvt_pk_bf16_f32 v110, v98, v99
	v_cvt_pk_bf16_f32 v111, v100, v101
	v_cvt_pk_bf16_f32 v112, v102, v103
	v_cvt_pk_bf16_f32 v113, v104, v105
	global_store_dwordx4 v9, v[110:113], s[18:19]
	s_sub_u32 s25, s25, 1
	s_cmp_eq_u32 s25, 0
	s_cbranch_scc1 .Ltrm_done
	s_cmp_lt_u32 s12, 33280
	s_cbranch_scc0 .Ltrm_nonext32
	s_cmp_ge_u32 s12, 33280
	s_cselect_b32 s41, 1, 0
	s_cselect_b32 s26, 33280, 0
	s_sub_u32 s42, s12, s26
	s_cmp_ge_u32 s42, 12288
	s_cbranch_scc1 .Ltrm_m35
	s_mul_i32 s43, s42, 43691
	s_lshr_b32 s43, s43, 24
	s_mul_i32 s26, s43, 384
	s_sub_u32 s44, s42, s26
	s_mov_b32 s14, s0
	s_mov_b32 s15, s1
	s_mov_b32 s36, 0xc000
	s_mov_b32 s37, 0x6000000
	s_mov_b32 s38, 0x0
	s_mov_b32 s39, 0x3000000
	s_mov_b32 s40, 0x1000
	s_branch .Ltrm_dec_done34

.Ltrm_dec_done34:
	s_mul_i32 s26, s41, s37
	s_lshl_b32 s27, s43, 6
	s_mul_i32 s27, s27, s36
	s_add_u32 s26, s26, s27
	s_lshl_b32 s27, s44, 7
	s_add_u32 s26, s26, s27
	s_add_u32 s14, s14, s26
	s_addc_u32 s15, s15, 0
	s_mul_i32 s26, s41, s39
	s_add_u32 s26, s26, s38
	s_lshl_b32 s27, s44, 5
	s_mul_i32 s27, s27, s40
	s_add_u32 s26, s26, s27
	s_lshl_b32 s27, s43, 7
	s_add_u32 s26, s26, s27
	s_add_u32 s18, s90, s26
	s_addc_u32 s19, s91, 0
	s_mov_b32 s22, s40
	v_mad_u32_u24 v7, v5, s36, v6
	s_lshl_b32 s45, s36, 3
	global_load_dwordx4 v[10:13], v7, s[14:15] nt
	s_add_u32 s14, s14, s45
	s_addc_u32 s15, s15, 0
	global_load_dwordx4 v[14:17], v7, s[14:15] nt
	s_add_u32 s14, s14, s45
	s_addc_u32 s15, s15, 0
	global_load_dwordx4 v[18:21], v7, s[14:15] nt
	s_add_u32 s14, s14, s45
	s_addc_u32 s15, s15, 0
	global_load_dwordx4 v[22:25], v7, s[14:15] nt
	s_add_u32 s14, s14, s45
	s_addc_u32 s15, s15, 0
	global_load_dwordx4 v[26:29], v7, s[14:15] nt
	s_add_u32 s14, s14, s45
	s_addc_u32 s15, s15, 0
	global_load_dwordx4 v[30:33], v7, s[14:15] nt
	s_add_u32 s14, s14, s45
	s_addc_u32 s15, s15, 0
	global_load_dwordx4 v[34:37], v7, s[14:15] nt
	s_add_u32 s14, s14, s45
	s_addc_u32 s15, s15, 0
	global_load_dwordx4 v[38:41], v7, s[14:15] nt
	s_add_u32 s25, s25, 1
	s_add_u32 s12, s12, 768
	s_waitcnt vmcnt(28)
	s_branch .Ltrm_after33

.Ltrm_after33:
	ds_write_b32 v1, v42 offset:0
	ds_write_b32 v1, v43 offset:4
	ds_write_b32 v1, v44 offset:8
	ds_write_b32 v1, v45 offset:12
	ds_write_b32 v1, v46 offset:1056
	ds_write_b32 v1, v47 offset:1060
	ds_write_b32 v1, v48 offset:1064
	ds_write_b32 v1, v49 offset:1068
	ds_write_b32 v1, v50 offset:2112
	ds_write_b32 v1, v51 offset:2116
	ds_write_b32 v1, v52 offset:2120
	ds_write_b32 v1, v53 offset:2124
	ds_write_b32 v1, v54 offset:3168
	ds_write_b32 v1, v55 offset:3172
	ds_write_b32 v1, v56 offset:3176
	ds_write_b32 v1, v57 offset:3180
	ds_write_b32 v1, v58 offset:4224
	ds_write_b32 v1, v59 offset:4228
	ds_write_b32 v1, v60 offset:4232
	ds_write_b32 v1, v61 offset:4236
	ds_write_b32 v1, v62 offset:5280
	ds_write_b32 v1, v63 offset:5284
	ds_write_b32 v1, v64 offset:5288
	ds_write_b32 v1, v65 offset:5292
	ds_write_b32 v1, v66 offset:6336
	ds_write_b32 v1, v67 offset:6340
	ds_write_b32 v1, v68 offset:6344
	ds_write_b32 v1, v69 offset:6348
	ds_write_b32 v1, v70 offset:7392
	ds_write_b32 v1, v71 offset:7396
	ds_write_b32 v1, v72 offset:7400
	ds_write_b32 v1, v73 offset:7404
	v_mad_u32_u24 v9, v5, s23, v6
	s_lshl_b32 s46, s23, 3
	s_waitcnt lgkmcnt(0)
	ds_read_b32 v74, v2 offset:0
	ds_read_b32 v75, v2 offset:132
	ds_read_b32 v76, v2 offset:264
	ds_read_b32 v77, v2 offset:396
	ds_read_b32 v78, v2 offset:528
	ds_read_b32 v79, v2 offset:660
	ds_read_b32 v80, v2 offset:792
	ds_read_b32 v81, v2 offset:924
	ds_read_b32 v82, v2 offset:32
	ds_read_b32 v83, v2 offset:164
	ds_read_b32 v84, v2 offset:296
	ds_read_b32 v85, v2 offset:428
	ds_read_b32 v86, v2 offset:560
	ds_read_b32 v87, v2 offset:692
	ds_read_b32 v88, v2 offset:824
	ds_read_b32 v89, v2 offset:956
	s_waitcnt lgkmcnt(8)
	v_cvt_pk_bf16_f32 v106, v74, v75
	v_cvt_pk_bf16_f32 v107, v76, v77
	v_cvt_pk_bf16_f32 v108, v78, v79
	v_cvt_pk_bf16_f32 v109, v80, v81
	global_store_dwordx4 v9, v[106:109], s[20:21]
	s_add_u32 s20, s20, s46
	s_addc_u32 s21, s21, 0
	ds_read_b32 v90, v2 offset:64
	ds_read_b32 v91, v2 offset:196
	ds_read_b32 v92, v2 offset:328
	ds_read_b32 v93, v2 offset:460
	ds_read_b32 v94, v2 offset:592
	ds_read_b32 v95, v2 offset:724
	ds_read_b32 v96, v2 offset:856
	ds_read_b32 v97, v2 offset:988
	s_waitcnt lgkmcnt(8)
	v_cvt_pk_bf16_f32 v110, v82, v83
	v_cvt_pk_bf16_f32 v111, v84, v85
	v_cvt_pk_bf16_f32 v112, v86, v87
	v_cvt_pk_bf16_f32 v113, v88, v89
	global_store_dwordx4 v9, v[110:113], s[20:21]
	s_add_u32 s20, s20, s46
	s_addc_u32 s21, s21, 0
	ds_read_b32 v98, v2 offset:96
	ds_read_b32 v99, v2 offset:228
	ds_read_b32 v100, v2 offset:360
	ds_read_b32 v101, v2 offset:492
	ds_read_b32 v102, v2 offset:624
	ds_read_b32 v103, v2 offset:756
	ds_read_b32 v104, v2 offset:888
	ds_read_b32 v105, v2 offset:1020
	s_waitcnt lgkmcnt(8)
	v_cvt_pk_bf16_f32 v106, v90, v91
	v_cvt_pk_bf16_f32 v107, v92, v93
	v_cvt_pk_bf16_f32 v108, v94, v95
	v_cvt_pk_bf16_f32 v109, v96, v97
	global_store_dwordx4 v9, v[106:109], s[20:21]
	s_add_u32 s20, s20, s46
	s_addc_u32 s21, s21, 0
	s_waitcnt lgkmcnt(0)
	v_cvt_pk_bf16_f32 v110, v98, v99
	v_cvt_pk_bf16_f32 v111, v100, v101
	v_cvt_pk_bf16_f32 v112, v102, v103
	v_cvt_pk_bf16_f32 v113, v104, v105
	global_store_dwordx4 v9, v[110:113], s[20:21]
	s_sub_u32 s25, s25, 1
	s_cmp_eq_u32 s25, 0
	s_cbranch_scc1 .Ltrm_done
	s_cmp_lt_u32 s12, 33280
	s_cbranch_scc0 .Ltrm_nonext41
	s_cmp_ge_u32 s12, 33280
	s_cselect_b32 s41, 1, 0
	s_cselect_b32 s26, 33280, 0
	s_sub_u32 s42, s12, s26
	s_cmp_ge_u32 s42, 12288
	s_cbranch_scc1 .Ltrm_m44
	s_mul_i32 s43, s42, 43691
	s_lshr_b32 s43, s43, 24
	s_mul_i32 s26, s43, 384
	s_sub_u32 s44, s42, s26
	s_mov_b32 s14, s0
	s_mov_b32 s15, s1
	s_mov_b32 s36, 0xc000
	s_mov_b32 s37, 0x6000000
	s_mov_b32 s38, 0x0
	s_mov_b32 s39, 0x3000000
	s_mov_b32 s40, 0x1000
	s_branch .Ltrm_dec_done43

.Ltrm_dec_done43:
	s_mul_i32 s26, s41, s37
	s_lshl_b32 s27, s43, 6
	s_mul_i32 s27, s27, s36
	s_add_u32 s26, s26, s27
	s_lshl_b32 s27, s44, 7
	s_add_u32 s26, s26, s27
	s_add_u32 s14, s14, s26
	s_addc_u32 s15, s15, 0
	s_mul_i32 s26, s41, s39
	s_add_u32 s26, s26, s38
	s_lshl_b32 s27, s44, 5
	s_mul_i32 s27, s27, s40
	s_add_u32 s26, s26, s27
	s_lshl_b32 s27, s43, 7
	s_add_u32 s26, s26, s27
	s_add_u32 s20, s90, s26
	s_addc_u32 s21, s91, 0
	s_mov_b32 s23, s40
	v_mad_u32_u24 v7, v5, s36, v6
	s_lshl_b32 s45, s36, 3
	global_load_dwordx4 v[42:45], v7, s[14:15] nt
	s_add_u32 s14, s14, s45
	s_addc_u32 s15, s15, 0
	global_load_dwordx4 v[46:49], v7, s[14:15] nt
	s_add_u32 s14, s14, s45
	s_addc_u32 s15, s15, 0
	global_load_dwordx4 v[50:53], v7, s[14:15] nt
	s_add_u32 s14, s14, s45
	s_addc_u32 s15, s15, 0
	global_load_dwordx4 v[54:57], v7, s[14:15] nt
	s_add_u32 s14, s14, s45
	s_addc_u32 s15, s15, 0
	global_load_dwordx4 v[58:61], v7, s[14:15] nt
	s_add_u32 s14, s14, s45
	s_addc_u32 s15, s15, 0
	global_load_dwordx4 v[62:65], v7, s[14:15] nt
	s_add_u32 s14, s14, s45
	s_addc_u32 s15, s15, 0
	global_load_dwordx4 v[66:69], v7, s[14:15] nt
	s_add_u32 s14, s14, s45
	s_addc_u32 s15, s15, 0
	global_load_dwordx4 v[70:73], v7, s[14:15] nt
	s_add_u32 s25, s25, 1
	s_add_u32 s12, s12, 768
	s_waitcnt vmcnt(32)
	s_branch .Ltrm_after42

.Ltrm_after42:
	ds_write_b32 v1, v114 offset:0
	ds_write_b32 v1, v115 offset:4
	ds_write_b32 v1, v116 offset:8
	ds_write_b32 v1, v117 offset:12
	ds_write_b32 v1, v118 offset:1056
	ds_write_b32 v1, v119 offset:1060
	ds_write_b32 v1, v120 offset:1064
	ds_write_b32 v1, v121 offset:1068
	ds_write_b32 v1, v122 offset:2112
	ds_write_b32 v1, v123 offset:2116
	ds_write_b32 v1, v124 offset:2120
	ds_write_b32 v1, v125 offset:2124
	ds_write_b32 v1, v126 offset:3168
	ds_write_b32 v1, v127 offset:3172
	ds_write_b32 v1, v128 offset:3176
	ds_write_b32 v1, v129 offset:3180
	ds_write_b32 v1, v130 offset:4224
	ds_write_b32 v1, v131 offset:4228
	ds_write_b32 v1, v132 offset:4232
	ds_write_b32 v1, v133 offset:4236
	ds_write_b32 v1, v134 offset:5280
	ds_write_b32 v1, v135 offset:5284
	ds_write_b32 v1, v136 offset:5288
	ds_write_b32 v1, v137 offset:5292
	ds_write_b32 v1, v138 offset:6336
	ds_write_b32 v1, v139 offset:6340
	ds_write_b32 v1, v140 offset:6344
	ds_write_b32 v1, v141 offset:6348
	ds_write_b32 v1, v142 offset:7392
	ds_write_b32 v1, v143 offset:7396
	ds_write_b32 v1, v144 offset:7400
	ds_write_b32 v1, v145 offset:7404
	v_mad_u32_u24 v9, v5, s52, v6
	s_lshl_b32 s46, s52, 3
	s_waitcnt lgkmcnt(0)
	ds_read_b32 v74, v2 offset:0
	ds_read_b32 v75, v2 offset:132
	ds_read_b32 v76, v2 offset:264
	ds_read_b32 v77, v2 offset:396
	ds_read_b32 v78, v2 offset:528
	ds_read_b32 v79, v2 offset:660
	ds_read_b32 v80, v2 offset:792
	ds_read_b32 v81, v2 offset:924
	ds_read_b32 v82, v2 offset:32
	ds_read_b32 v83, v2 offset:164
	ds_read_b32 v84, v2 offset:296
	ds_read_b32 v85, v2 offset:428
	ds_read_b32 v86, v2 offset:560
	ds_read_b32 v87, v2 offset:692
	ds_read_b32 v88, v2 offset:824
	ds_read_b32 v89, v2 offset:956
	s_waitcnt lgkmcnt(8)
	v_cvt_pk_bf16_f32 v106, v74, v75
	v_cvt_pk_bf16_f32 v107, v76, v77
	v_cvt_pk_bf16_f32 v108, v78, v79
	v_cvt_pk_bf16_f32 v109, v80, v81
	global_store_dwordx4 v9, v[106:109], s[48:49]
	s_add_u32 s48, s48, s46
	s_addc_u32 s49, s49, 0
	ds_read_b32 v90, v2 offset:64
	ds_read_b32 v91, v2 offset:196
	ds_read_b32 v92, v2 offset:328
	ds_read_b32 v93, v2 offset:460
	ds_read_b32 v94, v2 offset:592
	ds_read_b32 v95, v2 offset:724
	ds_read_b32 v96, v2 offset:856
	ds_read_b32 v97, v2 offset:988
	s_waitcnt lgkmcnt(8)
	v_cvt_pk_bf16_f32 v110, v82, v83
	v_cvt_pk_bf16_f32 v111, v84, v85
	v_cvt_pk_bf16_f32 v112, v86, v87
	v_cvt_pk_bf16_f32 v113, v88, v89
	global_store_dwordx4 v9, v[110:113], s[48:49]
	s_add_u32 s48, s48, s46
	s_addc_u32 s49, s49, 0
	ds_read_b32 v98, v2 offset:96
	ds_read_b32 v99, v2 offset:228
	ds_read_b32 v100, v2 offset:360
	ds_read_b32 v101, v2 offset:492
	ds_read_b32 v102, v2 offset:624
	ds_read_b32 v103, v2 offset:756
	ds_read_b32 v104, v2 offset:888
	ds_read_b32 v105, v2 offset:1020
	s_waitcnt lgkmcnt(8)
	v_cvt_pk_bf16_f32 v106, v90, v91
	v_cvt_pk_bf16_f32 v107, v92, v93
	v_cvt_pk_bf16_f32 v108, v94, v95
	v_cvt_pk_bf16_f32 v109, v96, v97
	global_store_dwordx4 v9, v[106:109], s[48:49]
	s_add_u32 s48, s48, s46
	s_addc_u32 s49, s49, 0
	s_waitcnt lgkmcnt(0)
	v_cvt_pk_bf16_f32 v110, v98, v99
	v_cvt_pk_bf16_f32 v111, v100, v101
	v_cvt_pk_bf16_f32 v112, v102, v103
	v_cvt_pk_bf16_f32 v113, v104, v105
	global_store_dwordx4 v9, v[110:113], s[48:49]
	s_sub_u32 s25, s25, 1
	s_cmp_eq_u32 s25, 0
	s_cbranch_scc1 .Ltrm_done
	s_cmp_lt_u32 s12, 33280
	s_cbranch_scc0 .Ltrm_nonext50
	s_cmp_ge_u32 s12, 33280
	s_cselect_b32 s41, 1, 0
	s_cselect_b32 s26, 33280, 0
	s_sub_u32 s42, s12, s26
	s_cmp_ge_u32 s42, 12288
	s_cbranch_scc1 .Ltrm_m53
	s_mul_i32 s43, s42, 43691
	s_lshr_b32 s43, s43, 24
	s_mul_i32 s26, s43, 384
	s_sub_u32 s44, s42, s26
	s_mov_b32 s14, s0
	s_mov_b32 s15, s1
	s_mov_b32 s36, 0xc000
	s_mov_b32 s37, 0x6000000
	s_mov_b32 s38, 0x0
	s_mov_b32 s39, 0x3000000
	s_mov_b32 s40, 0x1000
	s_branch .Ltrm_dec_done52

.Ltrm_dec_done52:
	s_mul_i32 s26, s41, s37
	s_lshl_b32 s27, s43, 6
	s_mul_i32 s27, s27, s36
	s_add_u32 s26, s26, s27
	s_lshl_b32 s27, s44, 7
	s_add_u32 s26, s26, s27
	s_add_u32 s14, s14, s26
	s_addc_u32 s15, s15, 0
	s_mul_i32 s26, s41, s39
	s_add_u32 s26, s26, s38
	s_lshl_b32 s27, s44, 5
	s_mul_i32 s27, s27, s40
	s_add_u32 s26, s26, s27
	s_lshl_b32 s27, s43, 7
	s_add_u32 s26, s26, s27
	s_add_u32 s48, s90, s26
	s_addc_u32 s49, s91, 0
	s_mov_b32 s52, s40
	v_mad_u32_u24 v7, v5, s36, v6
	s_lshl_b32 s45, s36, 3
	global_load_dwordx4 v[114:117], v7, s[14:15] nt
	s_add_u32 s14, s14, s45
	s_addc_u32 s15, s15, 0
	global_load_dwordx4 v[118:121], v7, s[14:15] nt
	s_add_u32 s14, s14, s45
	s_addc_u32 s15, s15, 0
	global_load_dwordx4 v[122:125], v7, s[14:15] nt
	s_add_u32 s14, s14, s45
	s_addc_u32 s15, s15, 0
	global_load_dwordx4 v[126:129], v7, s[14:15] nt
	s_add_u32 s14, s14, s45
	s_addc_u32 s15, s15, 0
	global_load_dwordx4 v[130:133], v7, s[14:15] nt
	s_add_u32 s14, s14, s45
	s_addc_u32 s15, s15, 0
	global_load_dwordx4 v[134:137], v7, s[14:15] nt
	s_add_u32 s14, s14, s45
	s_addc_u32 s15, s15, 0
	global_load_dwordx4 v[138:141], v7, s[14:15] nt
	s_add_u32 s14, s14, s45
	s_addc_u32 s15, s15, 0
	global_load_dwordx4 v[142:145], v7, s[14:15] nt
	s_add_u32 s25, s25, 1
	s_add_u32 s12, s12, 768
	s_waitcnt vmcnt(36)
	s_branch .Ltrm_after51

.Ltrm_loop:
	s_cmp_lt_u32 s12, 33280
	s_cbranch_scc0 .Ltrm_nonext59
	s_cmp_ge_u32 s12, 33280
	s_cselect_b32 s41, 1, 0
	s_cselect_b32 s26, 33280, 0
	s_sub_u32 s42, s12, s26
	s_cmp_ge_u32 s42, 12288
	s_cbranch_scc1 .Ltrm_m62
	s_mul_i32 s43, s42, 43691
	s_lshr_b32 s43, s43, 24
	s_mul_i32 s26, s43, 384
	s_sub_u32 s44, s42, s26
	s_mov_b32 s14, s0
	s_mov_b32 s15, s1
	s_mov_b32 s36, 0xc000
	s_mov_b32 s37, 0x6000000
	s_mov_b32 s38, 0x0
	s_mov_b32 s39, 0x3000000
	s_mov_b32 s40, 0x1000
	s_branch .Ltrm_dec_done61

.Ltrm_dec_done61:
	s_mul_i32 s26, s41, s37
	s_lshl_b32 s27, s43, 6
	s_mul_i32 s27, s27, s36
	s_add_u32 s26, s26, s27
	s_lshl_b32 s27, s44, 7
	s_add_u32 s26, s26, s27
	s_add_u32 s14, s14, s26
	s_addc_u32 s15, s15, 0
	s_mul_i32 s26, s41, s39
	s_add_u32 s26, s26, s38
	s_lshl_b32 s27, s44, 5
	s_mul_i32 s27, s27, s40
	s_add_u32 s26, s26, s27
	s_lshl_b32 s27, s43, 7
	s_add_u32 s26, s26, s27
	s_add_u32 s50, s90, s26
	s_addc_u32 s51, s91, 0
	s_mov_b32 s53, s40
	v_mad_u32_u24 v7, v5, s36, v6
	s_lshl_b32 s45, s36, 3
	global_load_dwordx4 v[160:163], v7, s[14:15] nt
	s_add_u32 s14, s14, s45
	s_addc_u32 s15, s15, 0
	global_load_dwordx4 v[164:167], v7, s[14:15] nt
	s_add_u32 s14, s14, s45
	s_addc_u32 s15, s15, 0
	global_load_dwordx4 v[168:171], v7, s[14:15] nt
	s_add_u32 s14, s14, s45
	s_addc_u32 s15, s15, 0
	global_load_dwordx4 v[172:175], v7, s[14:15] nt
	s_add_u32 s14, s14, s45
	s_addc_u32 s15, s15, 0
	global_load_dwordx4 v[176:179], v7, s[14:15] nt
	s_add_u32 s14, s14, s45
	s_addc_u32 s15, s15, 0
	global_load_dwordx4 v[180:183], v7, s[14:15] nt
	s_add_u32 s14, s14, s45
	s_addc_u32 s15, s15, 0
	global_load_dwordx4 v[184:187], v7, s[14:15] nt
	s_add_u32 s14, s14, s45
	s_addc_u32 s15, s15, 0
	global_load_dwordx4 v[188:191], v7, s[14:15] nt
	s_add_u32 s25, s25, 1
	s_add_u32 s12, s12, 768
	s_waitcnt vmcnt(36)
	s_branch .Ltrm_after60

.Ltrm_dec_done70:
	s_mul_i32 s26, s41, s37
	s_lshl_b32 s27, s43, 6
	s_mul_i32 s27, s27, s36
	s_add_u32 s26, s26, s27
	s_lshl_b32 s27, s44, 7
	s_add_u32 s26, s26, s27
	s_add_u32 s14, s14, s26
	s_addc_u32 s15, s15, 0
	s_mul_i32 s26, s41, s39
	s_add_u32 s26, s26, s38
	s_lshl_b32 s27, s44, 5
	s_mul_i32 s27, s27, s40
	s_add_u32 s26, s26, s27
	s_lshl_b32 s27, s43, 7
	s_add_u32 s26, s26, s27
	s_add_u32 s18, s90, s26
	s_addc_u32 s19, s91, 0
	s_mov_b32 s22, s40
	v_mad_u32_u24 v7, v5, s36, v6
	s_lshl_b32 s45, s36, 3
	global_load_dwordx4 v[10:13], v7, s[14:15] nt
	s_add_u32 s14, s14, s45
	s_addc_u32 s15, s15, 0
	global_load_dwordx4 v[14:17], v7, s[14:15] nt
	s_add_u32 s14, s14, s45
	s_addc_u32 s15, s15, 0
	global_load_dwordx4 v[18:21], v7, s[14:15] nt
	s_add_u32 s14, s14, s45
	s_addc_u32 s15, s15, 0
	global_load_dwordx4 v[22:25], v7, s[14:15] nt
	s_add_u32 s14, s14, s45
	s_addc_u32 s15, s15, 0
	global_load_dwordx4 v[26:29], v7, s[14:15] nt
	s_add_u32 s14, s14, s45
	s_addc_u32 s15, s15, 0
	global_load_dwordx4 v[30:33], v7, s[14:15] nt
	s_add_u32 s14, s14, s45
	s_addc_u32 s15, s15, 0
	global_load_dwordx4 v[34:37], v7, s[14:15] nt
	s_add_u32 s14, s14, s45
	s_addc_u32 s15, s15, 0
	global_load_dwordx4 v[38:41], v7, s[14:15] nt
	s_add_u32 s25, s25, 1
	s_add_u32 s12, s12, 768
	s_waitcnt vmcnt(36)
	s_branch .Ltrm_after69

.Ltrm_dec_done79:
	s_mul_i32 s26, s41, s37
	s_lshl_b32 s27, s43, 6
	s_mul_i32 s27, s27, s36
	s_add_u32 s26, s26, s27
	s_lshl_b32 s27, s44, 7
	s_add_u32 s26, s26, s27
	s_add_u32 s14, s14, s26
	s_addc_u32 s15, s15, 0
	s_mul_i32 s26, s41, s39
	s_add_u32 s26, s26, s38
	s_lshl_b32 s27, s44, 5
	s_mul_i32 s27, s27, s40
	s_add_u32 s26, s26, s27
	s_lshl_b32 s27, s43, 7
	s_add_u32 s26, s26, s27
	s_add_u32 s20, s90, s26
	s_addc_u32 s21, s91, 0
	s_mov_b32 s23, s40
	v_mad_u32_u24 v7, v5, s36, v6
	s_lshl_b32 s45, s36, 3
	global_load_dwordx4 v[42:45], v7, s[14:15] nt
	s_add_u32 s14, s14, s45
	s_addc_u32 s15, s15, 0
	global_load_dwordx4 v[46:49], v7, s[14:15] nt
	s_add_u32 s14, s14, s45
	s_addc_u32 s15, s15, 0
	global_load_dwordx4 v[50:53], v7, s[14:15] nt
	s_add_u32 s14, s14, s45
	s_addc_u32 s15, s15, 0
	global_load_dwordx4 v[54:57], v7, s[14:15] nt
	s_add_u32 s14, s14, s45
	s_addc_u32 s15, s15, 0
	global_load_dwordx4 v[58:61], v7, s[14:15] nt
	s_add_u32 s14, s14, s45
	s_addc_u32 s15, s15, 0
	global_load_dwordx4 v[62:65], v7, s[14:15] nt
	s_add_u32 s14, s14, s45
	s_addc_u32 s15, s15, 0
	global_load_dwordx4 v[66:69], v7, s[14:15] nt
	s_add_u32 s14, s14, s45
	s_addc_u32 s15, s15, 0
	global_load_dwordx4 v[70:73], v7, s[14:15] nt
	s_add_u32 s25, s25, 1
	s_add_u32 s12, s12, 768
	s_waitcnt vmcnt(36)
	s_branch .Ltrm_after78

.LBB0_1179:
	s_waitcnt vmcnt(0)
	s_barrier
	s_cmp_lt_u32 s96, 128
	s_cbranch_scc1 .LBB0_1180
	s_load_dwordx2 s[0:1], s[92:93], 0x58
	s_load_dwordx2 s[2:3], s[92:93], 0xb8
	s_load_dwordx2 s[4:5], s[92:93], 0xc0
	s_load_dwordx2 s[6:7], s[92:93], 0xc8
	s_load_dwordx2 s[8:9], s[92:93], 0xd0
	s_load_dwordx2 s[10:11], s[92:93], 0xe8
	v_and_b32_e32 v74, 63, v154
	v_lshrrev_b32_e32 v75, 6, v154
	v_mul_u32_u24_e32 v75, 0x2100, v75
	v_lshrrev_b32_e32 v3, 5, v74
	v_and_b32_e32 v4, 31, v74
	v_lshlrev_b32_e32 v4, 2, v4
	v_lshrrev_b32_e32 v5, 3, v74
	v_and_b32_e32 v6, 7, v74
	v_mul_u32_u24_e32 v2, 264, v6
	v_add_u32_e32 v2, v2, v5
	v_lshl_add_u32 v2, v2, 2, v75
	v_lshlrev_b32_e32 v6, 4, v6
	v_mul_u32_u24_e32 v1, 132, v5
	v_add3_u32 v1, v1, v6, v75
	v_readfirstlane_b32 s13, v154
	s_lshr_b32 s13, s13, 6
	s_lshl_b32 s26, s96, 3
	s_add_u32 s13, s13, s26
	s_sub_u32 s12, s13, 1024
	s_add_u32 s12, s12, 33280
	s_waitcnt lgkmcnt(0)
	s_mov_b32 s25, 0
	s_cmp_ge_u32 s12, 49664
	s_cbranch_scc1 .Ltrs_pro_end1
	s_cmp_ge_u32 s12, 33280
	s_cselect_b32 s41, 1, 0
	s_cselect_b32 s26, 33280, 0
	s_sub_u32 s42, s12, s26
	s_cmp_ge_u32 s42, 12288
	s_cbranch_scc1 .Ltrs_m3
	s_mul_i32 s43, s42, 43691
	s_lshr_b32 s43, s43, 24
	s_mul_i32 s26, s43, 384
	s_sub_u32 s44, s42, s26
	s_mov_b32 s14, s0
	s_mov_b32 s15, s1
	s_mov_b32 s36, 0xc000
	s_mov_b32 s37, 0x6000000
	s_mov_b32 s38, 0x0
	s_mov_b32 s39, 0x3000000
	s_mov_b32 s40, 0x1000
	s_branch .Ltrs_dec_done2

.Ltrs_dec_done2:
	s_mul_i32 s26, s41, s37
	s_lshl_b32 s27, s43, 6
	s_mul_i32 s27, s27, s36
	s_add_u32 s26, s26, s27
	s_lshl_b32 s27, s44, 7
	s_add_u32 s26, s26, s27
	s_add_u32 s14, s14, s26
	s_addc_u32 s15, s15, 0
	s_mul_i32 s26, s41, s39
	s_add_u32 s26, s26, s38
	s_lshl_b32 s27, s44, 5
	s_mul_i32 s27, s27, s40
	s_add_u32 s26, s26, s27
	s_lshl_b32 s27, s43, 7
	s_add_u32 s26, s26, s27
	s_add_u32 s18, s90, s26
	s_addc_u32 s19, s91, 0
	s_mov_b32 s22, s40
	v_mad_u32_u24 v7, v5, s36, v6
	s_lshl_b32 s45, s36, 3
	global_load_dwordx4 v[10:13], v7, s[14:15] nt
	s_add_u32 s14, s14, s45
	s_addc_u32 s15, s15, 0
	global_load_dwordx4 v[14:17], v7, s[14:15] nt
	s_add_u32 s14, s14, s45
	s_addc_u32 s15, s15, 0
	global_load_dwordx4 v[18:21], v7, s[14:15] nt
	s_add_u32 s14, s14, s45
	s_addc_u32 s15, s15, 0
	global_load_dwordx4 v[22:25], v7, s[14:15] nt
	s_add_u32 s14, s14, s45
	s_addc_u32 s15, s15, 0
	global_load_dwordx4 v[26:29], v7, s[14:15] nt
	s_add_u32 s14, s14, s45
	s_addc_u32 s15, s15, 0
	global_load_dwordx4 v[30:33], v7, s[14:15] nt
	s_add_u32 s14, s14, s45
	s_addc_u32 s15, s15, 0
	global_load_dwordx4 v[34:37], v7, s[14:15] nt
	s_add_u32 s14, s14, s45
	s_addc_u32 s15, s15, 0
	global_load_dwordx4 v[38:41], v7, s[14:15] nt
	s_add_u32 s25, s25, 1
	s_add_u32 s12, s12, 1024
	s_cmp_ge_u32 s12, 49664
	s_cbranch_scc1 .Ltrs_pro_end1
	s_cmp_ge_u32 s12, 33280
	s_cselect_b32 s41, 1, 0
	s_cselect_b32 s26, 33280, 0
	s_sub_u32 s42, s12, s26
	s_cmp_ge_u32 s42, 12288
	s_cbranch_scc1 .Ltrs_m10
	s_mul_i32 s43, s42, 43691
	s_lshr_b32 s43, s43, 24
	s_mul_i32 s26, s43, 384
	s_sub_u32 s44, s42, s26
	s_mov_b32 s14, s0
	s_mov_b32 s15, s1
	s_mov_b32 s36, 0xc000
	s_mov_b32 s37, 0x6000000
	s_mov_b32 s38, 0x0
	s_mov_b32 s39, 0x3000000
	s_mov_b32 s40, 0x1000
	s_branch .Ltrs_dec_done9

.Ltrs_dec_done9:
	s_mul_i32 s26, s41, s37
	s_lshl_b32 s27, s43, 6
	s_mul_i32 s27, s27, s36
	s_add_u32 s26, s26, s27
	s_lshl_b32 s27, s44, 7
	s_add_u32 s26, s26, s27
	s_add_u32 s14, s14, s26
	s_addc_u32 s15, s15, 0
	s_mul_i32 s26, s41, s39
	s_add_u32 s26, s26, s38
	s_lshl_b32 s27, s44, 5
	s_mul_i32 s27, s27, s40
	s_add_u32 s26, s26, s27
	s_lshl_b32 s27, s43, 7
	s_add_u32 s26, s26, s27
	s_add_u32 s20, s90, s26
	s_addc_u32 s21, s91, 0
	s_mov_b32 s23, s40
	v_mad_u32_u24 v7, v5, s36, v6
	s_lshl_b32 s45, s36, 3
	global_load_dwordx4 v[42:45], v7, s[14:15] nt
	s_add_u32 s14, s14, s45
	s_addc_u32 s15, s15, 0
	global_load_dwordx4 v[46:49], v7, s[14:15] nt
	s_add_u32 s14, s14, s45
	s_addc_u32 s15, s15, 0
	global_load_dwordx4 v[50:53], v7, s[14:15] nt
	s_add_u32 s14, s14, s45
	s_addc_u32 s15, s15, 0
	global_load_dwordx4 v[54:57], v7, s[14:15] nt
	s_add_u32 s14, s14, s45
	s_addc_u32 s15, s15, 0
	global_load_dwordx4 v[58:61], v7, s[14:15] nt
	s_add_u32 s14, s14, s45
	s_addc_u32 s15, s15, 0
	global_load_dwordx4 v[62:65], v7, s[14:15] nt
	s_add_u32 s14, s14, s45
	s_addc_u32 s15, s15, 0
	global_load_dwordx4 v[66:69], v7, s[14:15] nt
	s_add_u32 s14, s14, s45
	s_addc_u32 s15, s15, 0
	global_load_dwordx4 v[70:73], v7, s[14:15] nt
	s_add_u32 s25, s25, 1
	s_add_u32 s12, s12, 1024
	s_cmp_ge_u32 s12, 49664
	s_cbranch_scc1 .Ltrs_pro_end1
	s_cmp_ge_u32 s12, 33280
	s_cselect_b32 s41, 1, 0
	s_cselect_b32 s26, 33280, 0
	s_sub_u32 s42, s12, s26
	s_cmp_ge_u32 s42, 12288
	s_cbranch_scc1 .Ltrs_m17
	s_mul_i32 s43, s42, 43691
	s_lshr_b32 s43, s43, 24
	s_mul_i32 s26, s43, 384
	s_sub_u32 s44, s42, s26
	s_mov_b32 s14, s0
	s_mov_b32 s15, s1
	s_mov_b32 s36, 0xc000
	s_mov_b32 s37, 0x6000000
	s_mov_b32 s38, 0x0
	s_mov_b32 s39, 0x3000000
	s_mov_b32 s40, 0x1000
	s_branch .Ltrs_dec_done16

.Ltrs_dec_done16:
	s_mul_i32 s26, s41, s37
	s_lshl_b32 s27, s43, 6
	s_mul_i32 s27, s27, s36
	s_add_u32 s26, s26, s27
	s_lshl_b32 s27, s44, 7
	s_add_u32 s26, s26, s27
	s_add_u32 s14, s14, s26
	s_addc_u32 s15, s15, 0
	s_mul_i32 s26, s41, s39
	s_add_u32 s26, s26, s38
	s_lshl_b32 s27, s44, 5
	s_mul_i32 s27, s27, s40
	s_add_u32 s26, s26, s27
	s_lshl_b32 s27, s43, 7
	s_add_u32 s26, s26, s27
	s_add_u32 s48, s90, s26
	s_addc_u32 s49, s91, 0
	s_mov_b32 s52, s40
	v_mad_u32_u24 v7, v5, s36, v6
	s_lshl_b32 s45, s36, 3
	global_load_dwordx4 v[114:117], v7, s[14:15] nt
	s_add_u32 s14, s14, s45
	s_addc_u32 s15, s15, 0
	global_load_dwordx4 v[118:121], v7, s[14:15] nt
	s_add_u32 s14, s14, s45
	s_addc_u32 s15, s15, 0
	global_load_dwordx4 v[122:125], v7, s[14:15] nt
	s_add_u32 s14, s14, s45
	s_addc_u32 s15, s15, 0
	global_load_dwordx4 v[126:129], v7, s[14:15] nt
	s_add_u32 s14, s14, s45
	s_addc_u32 s15, s15, 0
	global_load_dwordx4 v[130:133], v7, s[14:15] nt
	s_add_u32 s14, s14, s45
	s_addc_u32 s15, s15, 0
	global_load_dwordx4 v[134:137], v7, s[14:15] nt
	s_add_u32 s14, s14, s45
	s_addc_u32 s15, s15, 0
	global_load_dwordx4 v[138:141], v7, s[14:15] nt
	s_add_u32 s14, s14, s45
	s_addc_u32 s15, s15, 0
	global_load_dwordx4 v[142:145], v7, s[14:15] nt
	s_add_u32 s25, s25, 1
	s_add_u32 s12, s12, 1024
.Ltrs_pro_end1:
	s_cmp_eq_u32 s25, 0
	s_cbranch_scc1 .Ltrs_done
	s_cmp_lt_u32 s12, 49664
	s_cbranch_scc0 .Ltrs_nonext23
	s_cmp_ge_u32 s12, 33280
	s_cselect_b32 s41, 1, 0
	s_cselect_b32 s26, 33280, 0
	s_sub_u32 s42, s12, s26
	s_cmp_ge_u32 s42, 12288
	s_cbranch_scc1 .Ltrs_m26
	s_mul_i32 s43, s42, 43691
	s_lshr_b32 s43, s43, 24
	s_mul_i32 s26, s43, 384
	s_sub_u32 s44, s42, s26
	s_mov_b32 s14, s0
	s_mov_b32 s15, s1
	s_mov_b32 s36, 0xc000
	s_mov_b32 s37, 0x6000000
	s_mov_b32 s38, 0x0
	s_mov_b32 s39, 0x3000000
	s_mov_b32 s40, 0x1000
	s_branch .Ltrs_dec_done25

.Ltrs_dec_done25:
	s_mul_i32 s26, s41, s37
	s_lshl_b32 s27, s43, 6
	s_mul_i32 s27, s27, s36
	s_add_u32 s26, s26, s27
	s_lshl_b32 s27, s44, 7
	s_add_u32 s26, s26, s27
	s_add_u32 s14, s14, s26
	s_addc_u32 s15, s15, 0
	s_mul_i32 s26, s41, s39
	s_add_u32 s26, s26, s38
	s_lshl_b32 s27, s44, 5
	s_mul_i32 s27, s27, s40
	s_add_u32 s26, s26, s27
	s_lshl_b32 s27, s43, 7
	s_add_u32 s26, s26, s27
	s_add_u32 s50, s90, s26
	s_addc_u32 s51, s91, 0
	s_mov_b32 s53, s40
	v_mad_u32_u24 v7, v5, s36, v6
	s_lshl_b32 s45, s36, 3
	global_load_dwordx4 v[160:163], v7, s[14:15] nt
	s_add_u32 s14, s14, s45
	s_addc_u32 s15, s15, 0
	global_load_dwordx4 v[164:167], v7, s[14:15] nt
	s_add_u32 s14, s14, s45
	s_addc_u32 s15, s15, 0
	global_load_dwordx4 v[168:171], v7, s[14:15] nt
	s_add_u32 s14, s14, s45
	s_addc_u32 s15, s15, 0
	global_load_dwordx4 v[172:175], v7, s[14:15] nt
	s_add_u32 s14, s14, s45
	s_addc_u32 s15, s15, 0
	global_load_dwordx4 v[176:179], v7, s[14:15] nt
	s_add_u32 s14, s14, s45
	s_addc_u32 s15, s15, 0
	global_load_dwordx4 v[180:183], v7, s[14:15] nt
	s_add_u32 s14, s14, s45
	s_addc_u32 s15, s15, 0
	global_load_dwordx4 v[184:187], v7, s[14:15] nt
	s_add_u32 s14, s14, s45
	s_addc_u32 s15, s15, 0
	global_load_dwordx4 v[188:191], v7, s[14:15] nt
	s_add_u32 s25, s25, 1
	s_add_u32 s12, s12, 1024
	s_waitcnt vmcnt(24)
	s_branch .Ltrs_after24

.Ltrs_after24:
	ds_write_b32 v1, v10 offset:0
	ds_write_b32 v1, v11 offset:4
	ds_write_b32 v1, v12 offset:8
	ds_write_b32 v1, v13 offset:12
	ds_write_b32 v1, v14 offset:1056
	ds_write_b32 v1, v15 offset:1060
	ds_write_b32 v1, v16 offset:1064
	ds_write_b32 v1, v17 offset:1068
	ds_write_b32 v1, v18 offset:2112
	ds_write_b32 v1, v19 offset:2116
	ds_write_b32 v1, v20 offset:2120
	ds_write_b32 v1, v21 offset:2124
	ds_write_b32 v1, v22 offset:3168
	ds_write_b32 v1, v23 offset:3172
	ds_write_b32 v1, v24 offset:3176
	ds_write_b32 v1, v25 offset:3180
	ds_write_b32 v1, v26 offset:4224
	ds_write_b32 v1, v27 offset:4228
	ds_write_b32 v1, v28 offset:4232
	ds_write_b32 v1, v29 offset:4236
	ds_write_b32 v1, v30 offset:5280
	ds_write_b32 v1, v31 offset:5284
	ds_write_b32 v1, v32 offset:5288
	ds_write_b32 v1, v33 offset:5292
	ds_write_b32 v1, v34 offset:6336
	ds_write_b32 v1, v35 offset:6340
	ds_write_b32 v1, v36 offset:6344
	ds_write_b32 v1, v37 offset:6348
	ds_write_b32 v1, v38 offset:7392
	ds_write_b32 v1, v39 offset:7396
	ds_write_b32 v1, v40 offset:7400
	ds_write_b32 v1, v41 offset:7404
	v_mad_u32_u24 v9, v5, s22, v6
	s_lshl_b32 s46, s22, 3
	s_waitcnt lgkmcnt(0)
	ds_read_b32 v74, v2 offset:0
	ds_read_b32 v75, v2 offset:132
	ds_read_b32 v76, v2 offset:264
	ds_read_b32 v77, v2 offset:396
	ds_read_b32 v78, v2 offset:528
	ds_read_b32 v79, v2 offset:660
	ds_read_b32 v80, v2 offset:792
	ds_read_b32 v81, v2 offset:924
	ds_read_b32 v82, v2 offset:32
	ds_read_b32 v83, v2 offset:164
	ds_read_b32 v84, v2 offset:296
	ds_read_b32 v85, v2 offset:428
	ds_read_b32 v86, v2 offset:560
	ds_read_b32 v87, v2 offset:692
	ds_read_b32 v88, v2 offset:824
	ds_read_b32 v89, v2 offset:956
	s_waitcnt lgkmcnt(8)
	v_cvt_pk_bf16_f32 v106, v74, v75
	v_cvt_pk_bf16_f32 v107, v76, v77
	v_cvt_pk_bf16_f32 v108, v78, v79
	v_cvt_pk_bf16_f32 v109, v80, v81
	global_store_dwordx4 v9, v[106:109], s[18:19]
	s_add_u32 s18, s18, s46
	s_addc_u32 s19, s19, 0
	ds_read_b32 v90, v2 offset:64
	ds_read_b32 v91, v2 offset:196
	ds_read_b32 v92, v2 offset:328
	ds_read_b32 v93, v2 offset:460
	ds_read_b32 v94, v2 offset:592
	ds_read_b32 v95, v2 offset:724
	ds_read_b32 v96, v2 offset:856
	ds_read_b32 v97, v2 offset:988
	s_waitcnt lgkmcnt(8)
	v_cvt_pk_bf16_f32 v110, v82, v83
	v_cvt_pk_bf16_f32 v111, v84, v85
	v_cvt_pk_bf16_f32 v112, v86, v87
	v_cvt_pk_bf16_f32 v113, v88, v89
	global_store_dwordx4 v9, v[110:113], s[18:19]
	s_add_u32 s18, s18, s46
	s_addc_u32 s19, s19, 0
	ds_read_b32 v98, v2 offset:96
	ds_read_b32 v99, v2 offset:228
	ds_read_b32 v100, v2 offset:360
	ds_read_b32 v101, v2 offset:492
	ds_read_b32 v102, v2 offset:624
	ds_read_b32 v103, v2 offset:756
	ds_read_b32 v104, v2 offset:888
	ds_read_b32 v105, v2 offset:1020
	s_waitcnt lgkmcnt(8)
	v_cvt_pk_bf16_f32 v106, v90, v91
	v_cvt_pk_bf16_f32 v107, v92, v93
	v_cvt_pk_bf16_f32 v108, v94, v95
	v_cvt_pk_bf16_f32 v109, v96, v97
	global_store_dwordx4 v9, v[106:109], s[18:19]
	s_add_u32 s18, s18, s46
	s_addc_u32 s19, s19, 0
	s_waitcnt lgkmcnt(0)
	v_cvt_pk_bf16_f32 v110, v98, v99
	v_cvt_pk_bf16_f32 v111, v100, v101
	v_cvt_pk_bf16_f32 v112, v102, v103
	v_cvt_pk_bf16_f32 v113, v104, v105
	global_store_dwordx4 v9, v[110:113], s[18:19]
	s_sub_u32 s25, s25, 1
	s_cmp_eq_u32 s25, 0
	s_cbranch_scc1 .Ltrs_done
	s_cmp_lt_u32 s12, 49664
	s_cbranch_scc0 .Ltrs_nonext32
	s_cmp_ge_u32 s12, 33280
	s_cselect_b32 s41, 1, 0
	s_cselect_b32 s26, 33280, 0
	s_sub_u32 s42, s12, s26
	s_cmp_ge_u32 s42, 12288
	s_cbranch_scc1 .Ltrs_m35
	s_mul_i32 s43, s42, 43691
	s_lshr_b32 s43, s43, 24
	s_mul_i32 s26, s43, 384
	s_sub_u32 s44, s42, s26
	s_mov_b32 s14, s0
	s_mov_b32 s15, s1
	s_mov_b32 s36, 0xc000
	s_mov_b32 s37, 0x6000000
	s_mov_b32 s38, 0x0
	s_mov_b32 s39, 0x3000000
	s_mov_b32 s40, 0x1000
	s_branch .Ltrs_dec_done34

.Ltrs_dec_done34:
	s_mul_i32 s26, s41, s37
	s_lshl_b32 s27, s43, 6
	s_mul_i32 s27, s27, s36
	s_add_u32 s26, s26, s27
	s_lshl_b32 s27, s44, 7
	s_add_u32 s26, s26, s27
	s_add_u32 s14, s14, s26
	s_addc_u32 s15, s15, 0
	s_mul_i32 s26, s41, s39
	s_add_u32 s26, s26, s38
	s_lshl_b32 s27, s44, 5
	s_mul_i32 s27, s27, s40
	s_add_u32 s26, s26, s27
	s_lshl_b32 s27, s43, 7
	s_add_u32 s26, s26, s27
	s_add_u32 s18, s90, s26
	s_addc_u32 s19, s91, 0
	s_mov_b32 s22, s40
	v_mad_u32_u24 v7, v5, s36, v6
	s_lshl_b32 s45, s36, 3
	global_load_dwordx4 v[10:13], v7, s[14:15] nt
	s_add_u32 s14, s14, s45
	s_addc_u32 s15, s15, 0
	global_load_dwordx4 v[14:17], v7, s[14:15] nt
	s_add_u32 s14, s14, s45
	s_addc_u32 s15, s15, 0
	global_load_dwordx4 v[18:21], v7, s[14:15] nt
	s_add_u32 s14, s14, s45
	s_addc_u32 s15, s15, 0
	global_load_dwordx4 v[22:25], v7, s[14:15] nt
	s_add_u32 s14, s14, s45
	s_addc_u32 s15, s15, 0
	global_load_dwordx4 v[26:29], v7, s[14:15] nt
	s_add_u32 s14, s14, s45
	s_addc_u32 s15, s15, 0
	global_load_dwordx4 v[30:33], v7, s[14:15] nt
	s_add_u32 s14, s14, s45
	s_addc_u32 s15, s15, 0
	global_load_dwordx4 v[34:37], v7, s[14:15] nt
	s_add_u32 s14, s14, s45
	s_addc_u32 s15, s15, 0
	global_load_dwordx4 v[38:41], v7, s[14:15] nt
	s_add_u32 s25, s25, 1
	s_add_u32 s12, s12, 1024
	s_waitcnt vmcnt(28)
	s_branch .Ltrs_after33

.Ltrs_after33:
	ds_write_b32 v1, v42 offset:0
	ds_write_b32 v1, v43 offset:4
	ds_write_b32 v1, v44 offset:8
	ds_write_b32 v1, v45 offset:12
	ds_write_b32 v1, v46 offset:1056
	ds_write_b32 v1, v47 offset:1060
	ds_write_b32 v1, v48 offset:1064
	ds_write_b32 v1, v49 offset:1068
	ds_write_b32 v1, v50 offset:2112
	ds_write_b32 v1, v51 offset:2116
	ds_write_b32 v1, v52 offset:2120
	ds_write_b32 v1, v53 offset:2124
	ds_write_b32 v1, v54 offset:3168
	ds_write_b32 v1, v55 offset:3172
	ds_write_b32 v1, v56 offset:3176
	ds_write_b32 v1, v57 offset:3180
	ds_write_b32 v1, v58 offset:4224
	ds_write_b32 v1, v59 offset:4228
	ds_write_b32 v1, v60 offset:4232
	ds_write_b32 v1, v61 offset:4236
	ds_write_b32 v1, v62 offset:5280
	ds_write_b32 v1, v63 offset:5284
	ds_write_b32 v1, v64 offset:5288
	ds_write_b32 v1, v65 offset:5292
	ds_write_b32 v1, v66 offset:6336
	ds_write_b32 v1, v67 offset:6340
	ds_write_b32 v1, v68 offset:6344
	ds_write_b32 v1, v69 offset:6348
	ds_write_b32 v1, v70 offset:7392
	ds_write_b32 v1, v71 offset:7396
	ds_write_b32 v1, v72 offset:7400
	ds_write_b32 v1, v73 offset:7404
	v_mad_u32_u24 v9, v5, s23, v6
	s_lshl_b32 s46, s23, 3
	s_waitcnt lgkmcnt(0)
	ds_read_b32 v74, v2 offset:0
	ds_read_b32 v75, v2 offset:132
	ds_read_b32 v76, v2 offset:264
	ds_read_b32 v77, v2 offset:396
	ds_read_b32 v78, v2 offset:528
	ds_read_b32 v79, v2 offset:660
	ds_read_b32 v80, v2 offset:792
	ds_read_b32 v81, v2 offset:924
	ds_read_b32 v82, v2 offset:32
	ds_read_b32 v83, v2 offset:164
	ds_read_b32 v84, v2 offset:296
	ds_read_b32 v85, v2 offset:428
	ds_read_b32 v86, v2 offset:560
	ds_read_b32 v87, v2 offset:692
	ds_read_b32 v88, v2 offset:824
	ds_read_b32 v89, v2 offset:956
	s_waitcnt lgkmcnt(8)
	v_cvt_pk_bf16_f32 v106, v74, v75
	v_cvt_pk_bf16_f32 v107, v76, v77
	v_cvt_pk_bf16_f32 v108, v78, v79
	v_cvt_pk_bf16_f32 v109, v80, v81
	global_store_dwordx4 v9, v[106:109], s[20:21]
	s_add_u32 s20, s20, s46
	s_addc_u32 s21, s21, 0
	ds_read_b32 v90, v2 offset:64
	ds_read_b32 v91, v2 offset:196
	ds_read_b32 v92, v2 offset:328
	ds_read_b32 v93, v2 offset:460
	ds_read_b32 v94, v2 offset:592
	ds_read_b32 v95, v2 offset:724
	ds_read_b32 v96, v2 offset:856
	ds_read_b32 v97, v2 offset:988
	s_waitcnt lgkmcnt(8)
	v_cvt_pk_bf16_f32 v110, v82, v83
	v_cvt_pk_bf16_f32 v111, v84, v85
	v_cvt_pk_bf16_f32 v112, v86, v87
	v_cvt_pk_bf16_f32 v113, v88, v89
	global_store_dwordx4 v9, v[110:113], s[20:21]
	s_add_u32 s20, s20, s46
	s_addc_u32 s21, s21, 0
	ds_read_b32 v98, v2 offset:96
	ds_read_b32 v99, v2 offset:228
	ds_read_b32 v100, v2 offset:360
	ds_read_b32 v101, v2 offset:492
	ds_read_b32 v102, v2 offset:624
	ds_read_b32 v103, v2 offset:756
	ds_read_b32 v104, v2 offset:888
	ds_read_b32 v105, v2 offset:1020
	s_waitcnt lgkmcnt(8)
	v_cvt_pk_bf16_f32 v106, v90, v91
	v_cvt_pk_bf16_f32 v107, v92, v93
	v_cvt_pk_bf16_f32 v108, v94, v95
	v_cvt_pk_bf16_f32 v109, v96, v97
	global_store_dwordx4 v9, v[106:109], s[20:21]
	s_add_u32 s20, s20, s46
	s_addc_u32 s21, s21, 0
	s_waitcnt lgkmcnt(0)
	v_cvt_pk_bf16_f32 v110, v98, v99
	v_cvt_pk_bf16_f32 v111, v100, v101
	v_cvt_pk_bf16_f32 v112, v102, v103
	v_cvt_pk_bf16_f32 v113, v104, v105
	global_store_dwordx4 v9, v[110:113], s[20:21]
	s_sub_u32 s25, s25, 1
	s_cmp_eq_u32 s25, 0
	s_cbranch_scc1 .Ltrs_done
	s_cmp_lt_u32 s12, 49664
	s_cbranch_scc0 .Ltrs_nonext41
	s_cmp_ge_u32 s12, 33280
	s_cselect_b32 s41, 1, 0
	s_cselect_b32 s26, 33280, 0
	s_sub_u32 s42, s12, s26
	s_cmp_ge_u32 s42, 12288
	s_cbranch_scc1 .Ltrs_m44
	s_mul_i32 s43, s42, 43691
	s_lshr_b32 s43, s43, 24
	s_mul_i32 s26, s43, 384
	s_sub_u32 s44, s42, s26
	s_mov_b32 s14, s0
	s_mov_b32 s15, s1
	s_mov_b32 s36, 0xc000
	s_mov_b32 s37, 0x6000000
	s_mov_b32 s38, 0x0
	s_mov_b32 s39, 0x3000000
	s_mov_b32 s40, 0x1000
	s_branch .Ltrs_dec_done43

.Ltrs_dec_done43:
	s_mul_i32 s26, s41, s37
	s_lshl_b32 s27, s43, 6
	s_mul_i32 s27, s27, s36
	s_add_u32 s26, s26, s27
	s_lshl_b32 s27, s44, 7
	s_add_u32 s26, s26, s27
	s_add_u32 s14, s14, s26
	s_addc_u32 s15, s15, 0
	s_mul_i32 s26, s41, s39
	s_add_u32 s26, s26, s38
	s_lshl_b32 s27, s44, 5
	s_mul_i32 s27, s27, s40
	s_add_u32 s26, s26, s27
	s_lshl_b32 s27, s43, 7
	s_add_u32 s26, s26, s27
	s_add_u32 s20, s90, s26
	s_addc_u32 s21, s91, 0
	s_mov_b32 s23, s40
	v_mad_u32_u24 v7, v5, s36, v6
	s_lshl_b32 s45, s36, 3
	global_load_dwordx4 v[42:45], v7, s[14:15] nt
	s_add_u32 s14, s14, s45
	s_addc_u32 s15, s15, 0
	global_load_dwordx4 v[46:49], v7, s[14:15] nt
	s_add_u32 s14, s14, s45
	s_addc_u32 s15, s15, 0
	global_load_dwordx4 v[50:53], v7, s[14:15] nt
	s_add_u32 s14, s14, s45
	s_addc_u32 s15, s15, 0
	global_load_dwordx4 v[54:57], v7, s[14:15] nt
	s_add_u32 s14, s14, s45
	s_addc_u32 s15, s15, 0
	global_load_dwordx4 v[58:61], v7, s[14:15] nt
	s_add_u32 s14, s14, s45
	s_addc_u32 s15, s15, 0
	global_load_dwordx4 v[62:65], v7, s[14:15] nt
	s_add_u32 s14, s14, s45
	s_addc_u32 s15, s15, 0
	global_load_dwordx4 v[66:69], v7, s[14:15] nt
	s_add_u32 s14, s14, s45
	s_addc_u32 s15, s15, 0
	global_load_dwordx4 v[70:73], v7, s[14:15] nt
	s_add_u32 s25, s25, 1
	s_add_u32 s12, s12, 1024
	s_waitcnt vmcnt(32)
	s_branch .Ltrs_after42

.Ltrs_after42:
	ds_write_b32 v1, v114 offset:0
	ds_write_b32 v1, v115 offset:4
	ds_write_b32 v1, v116 offset:8
	ds_write_b32 v1, v117 offset:12
	ds_write_b32 v1, v118 offset:1056
	ds_write_b32 v1, v119 offset:1060
	ds_write_b32 v1, v120 offset:1064
	ds_write_b32 v1, v121 offset:1068
	ds_write_b32 v1, v122 offset:2112
	ds_write_b32 v1, v123 offset:2116
	ds_write_b32 v1, v124 offset:2120
	ds_write_b32 v1, v125 offset:2124
	ds_write_b32 v1, v126 offset:3168
	ds_write_b32 v1, v127 offset:3172
	ds_write_b32 v1, v128 offset:3176
	ds_write_b32 v1, v129 offset:3180
	ds_write_b32 v1, v130 offset:4224
	ds_write_b32 v1, v131 offset:4228
	ds_write_b32 v1, v132 offset:4232
	ds_write_b32 v1, v133 offset:4236
	ds_write_b32 v1, v134 offset:5280
	ds_write_b32 v1, v135 offset:5284
	ds_write_b32 v1, v136 offset:5288
	ds_write_b32 v1, v137 offset:5292
	ds_write_b32 v1, v138 offset:6336
	ds_write_b32 v1, v139 offset:6340
	ds_write_b32 v1, v140 offset:6344
	ds_write_b32 v1, v141 offset:6348
	ds_write_b32 v1, v142 offset:7392
	ds_write_b32 v1, v143 offset:7396
	ds_write_b32 v1, v144 offset:7400
	ds_write_b32 v1, v145 offset:7404
	v_mad_u32_u24 v9, v5, s52, v6
	s_lshl_b32 s46, s52, 3
	s_waitcnt lgkmcnt(0)
	ds_read_b32 v74, v2 offset:0
	ds_read_b32 v75, v2 offset:132
	ds_read_b32 v76, v2 offset:264
	ds_read_b32 v77, v2 offset:396
	ds_read_b32 v78, v2 offset:528
	ds_read_b32 v79, v2 offset:660
	ds_read_b32 v80, v2 offset:792
	ds_read_b32 v81, v2 offset:924
	ds_read_b32 v82, v2 offset:32
	ds_read_b32 v83, v2 offset:164
	ds_read_b32 v84, v2 offset:296
	ds_read_b32 v85, v2 offset:428
	ds_read_b32 v86, v2 offset:560
	ds_read_b32 v87, v2 offset:692
	ds_read_b32 v88, v2 offset:824
	ds_read_b32 v89, v2 offset:956
	s_waitcnt lgkmcnt(8)
	v_cvt_pk_bf16_f32 v106, v74, v75
	v_cvt_pk_bf16_f32 v107, v76, v77
	v_cvt_pk_bf16_f32 v108, v78, v79
	v_cvt_pk_bf16_f32 v109, v80, v81
	global_store_dwordx4 v9, v[106:109], s[48:49]
	s_add_u32 s48, s48, s46
	s_addc_u32 s49, s49, 0
	ds_read_b32 v90, v2 offset:64
	ds_read_b32 v91, v2 offset:196
	ds_read_b32 v92, v2 offset:328
	ds_read_b32 v93, v2 offset:460
	ds_read_b32 v94, v2 offset:592
	ds_read_b32 v95, v2 offset:724
	ds_read_b32 v96, v2 offset:856
	ds_read_b32 v97, v2 offset:988
	s_waitcnt lgkmcnt(8)
	v_cvt_pk_bf16_f32 v110, v82, v83
	v_cvt_pk_bf16_f32 v111, v84, v85
	v_cvt_pk_bf16_f32 v112, v86, v87
	v_cvt_pk_bf16_f32 v113, v88, v89
	global_store_dwordx4 v9, v[110:113], s[48:49]
	s_add_u32 s48, s48, s46
	s_addc_u32 s49, s49, 0
	ds_read_b32 v98, v2 offset:96
	ds_read_b32 v99, v2 offset:228
	ds_read_b32 v100, v2 offset:360
	ds_read_b32 v101, v2 offset:492
	ds_read_b32 v102, v2 offset:624
	ds_read_b32 v103, v2 offset:756
	ds_read_b32 v104, v2 offset:888
	ds_read_b32 v105, v2 offset:1020
	s_waitcnt lgkmcnt(8)
	v_cvt_pk_bf16_f32 v106, v90, v91
	v_cvt_pk_bf16_f32 v107, v92, v93
	v_cvt_pk_bf16_f32 v108, v94, v95
	v_cvt_pk_bf16_f32 v109, v96, v97
	global_store_dwordx4 v9, v[106:109], s[48:49]
	s_add_u32 s48, s48, s46
	s_addc_u32 s49, s49, 0
	s_waitcnt lgkmcnt(0)
	v_cvt_pk_bf16_f32 v110, v98, v99
	v_cvt_pk_bf16_f32 v111, v100, v101
	v_cvt_pk_bf16_f32 v112, v102, v103
	v_cvt_pk_bf16_f32 v113, v104, v105
	global_store_dwordx4 v9, v[110:113], s[48:49]
	s_sub_u32 s25, s25, 1
	s_cmp_eq_u32 s25, 0
	s_cbranch_scc1 .Ltrs_done
	s_cmp_lt_u32 s12, 49664
	s_cbranch_scc0 .Ltrs_nonext50
	s_cmp_ge_u32 s12, 33280
	s_cselect_b32 s41, 1, 0
	s_cselect_b32 s26, 33280, 0
	s_sub_u32 s42, s12, s26
	s_cmp_ge_u32 s42, 12288
	s_cbranch_scc1 .Ltrs_m53
	s_mul_i32 s43, s42, 43691
	s_lshr_b32 s43, s43, 24
	s_mul_i32 s26, s43, 384
	s_sub_u32 s44, s42, s26
	s_mov_b32 s14, s0
	s_mov_b32 s15, s1
	s_mov_b32 s36, 0xc000
	s_mov_b32 s37, 0x6000000
	s_mov_b32 s38, 0x0
	s_mov_b32 s39, 0x3000000
	s_mov_b32 s40, 0x1000
	s_branch .Ltrs_dec_done52

.Ltrs_dec_done52:
	s_mul_i32 s26, s41, s37
	s_lshl_b32 s27, s43, 6
	s_mul_i32 s27, s27, s36
	s_add_u32 s26, s26, s27
	s_lshl_b32 s27, s44, 7
	s_add_u32 s26, s26, s27
	s_add_u32 s14, s14, s26
	s_addc_u32 s15, s15, 0
	s_mul_i32 s26, s41, s39
	s_add_u32 s26, s26, s38
	s_lshl_b32 s27, s44, 5
	s_mul_i32 s27, s27, s40
	s_add_u32 s26, s26, s27
	s_lshl_b32 s27, s43, 7
	s_add_u32 s26, s26, s27
	s_add_u32 s48, s90, s26
	s_addc_u32 s49, s91, 0
	s_mov_b32 s52, s40
	v_mad_u32_u24 v7, v5, s36, v6
	s_lshl_b32 s45, s36, 3
	global_load_dwordx4 v[114:117], v7, s[14:15] nt
	s_add_u32 s14, s14, s45
	s_addc_u32 s15, s15, 0
	global_load_dwordx4 v[118:121], v7, s[14:15] nt
	s_add_u32 s14, s14, s45
	s_addc_u32 s15, s15, 0
	global_load_dwordx4 v[122:125], v7, s[14:15] nt
	s_add_u32 s14, s14, s45
	s_addc_u32 s15, s15, 0
	global_load_dwordx4 v[126:129], v7, s[14:15] nt
	s_add_u32 s14, s14, s45
	s_addc_u32 s15, s15, 0
	global_load_dwordx4 v[130:133], v7, s[14:15] nt
	s_add_u32 s14, s14, s45
	s_addc_u32 s15, s15, 0
	global_load_dwordx4 v[134:137], v7, s[14:15] nt
	s_add_u32 s14, s14, s45
	s_addc_u32 s15, s15, 0
	global_load_dwordx4 v[138:141], v7, s[14:15] nt
	s_add_u32 s14, s14, s45
	s_addc_u32 s15, s15, 0
	global_load_dwordx4 v[142:145], v7, s[14:15] nt
	s_add_u32 s25, s25, 1
	s_add_u32 s12, s12, 1024
	s_waitcnt vmcnt(36)
	s_branch .Ltrs_after51

.Ltrs_loop:
	s_cmp_lt_u32 s12, 49664
	s_cbranch_scc0 .Ltrs_nonext59
	s_cmp_ge_u32 s12, 33280
	s_cselect_b32 s41, 1, 0
	s_cselect_b32 s26, 33280, 0
	s_sub_u32 s42, s12, s26
	s_cmp_ge_u32 s42, 12288
	s_cbranch_scc1 .Ltrs_m62
	s_mul_i32 s43, s42, 43691
	s_lshr_b32 s43, s43, 24
	s_mul_i32 s26, s43, 384
	s_sub_u32 s44, s42, s26
	s_mov_b32 s14, s0
	s_mov_b32 s15, s1
	s_mov_b32 s36, 0xc000
	s_mov_b32 s37, 0x6000000
	s_mov_b32 s38, 0x0
	s_mov_b32 s39, 0x3000000
	s_mov_b32 s40, 0x1000
	s_branch .Ltrs_dec_done61

.Ltrs_dec_done61:
	s_mul_i32 s26, s41, s37
	s_lshl_b32 s27, s43, 6
	s_mul_i32 s27, s27, s36
	s_add_u32 s26, s26, s27
	s_lshl_b32 s27, s44, 7
	s_add_u32 s26, s26, s27
	s_add_u32 s14, s14, s26
	s_addc_u32 s15, s15, 0
	s_mul_i32 s26, s41, s39
	s_add_u32 s26, s26, s38
	s_lshl_b32 s27, s44, 5
	s_mul_i32 s27, s27, s40
	s_add_u32 s26, s26, s27
	s_lshl_b32 s27, s43, 7
	s_add_u32 s26, s26, s27
	s_add_u32 s50, s90, s26
	s_addc_u32 s51, s91, 0
	s_mov_b32 s53, s40
	v_mad_u32_u24 v7, v5, s36, v6
	s_lshl_b32 s45, s36, 3
	global_load_dwordx4 v[160:163], v7, s[14:15] nt
	s_add_u32 s14, s14, s45
	s_addc_u32 s15, s15, 0
	global_load_dwordx4 v[164:167], v7, s[14:15] nt
	s_add_u32 s14, s14, s45
	s_addc_u32 s15, s15, 0
	global_load_dwordx4 v[168:171], v7, s[14:15] nt
	s_add_u32 s14, s14, s45
	s_addc_u32 s15, s15, 0
	global_load_dwordx4 v[172:175], v7, s[14:15] nt
	s_add_u32 s14, s14, s45
	s_addc_u32 s15, s15, 0
	global_load_dwordx4 v[176:179], v7, s[14:15] nt
	s_add_u32 s14, s14, s45
	s_addc_u32 s15, s15, 0
	global_load_dwordx4 v[180:183], v7, s[14:15] nt
	s_add_u32 s14, s14, s45
	s_addc_u32 s15, s15, 0
	global_load_dwordx4 v[184:187], v7, s[14:15] nt
	s_add_u32 s14, s14, s45
	s_addc_u32 s15, s15, 0
	global_load_dwordx4 v[188:191], v7, s[14:15] nt
	s_add_u32 s25, s25, 1
	s_add_u32 s12, s12, 1024
	s_waitcnt vmcnt(36)
	s_branch .Ltrs_after60

.Ltrs_dec_done70:
	s_mul_i32 s26, s41, s37
	s_lshl_b32 s27, s43, 6
	s_mul_i32 s27, s27, s36
	s_add_u32 s26, s26, s27
	s_lshl_b32 s27, s44, 7
	s_add_u32 s26, s26, s27
	s_add_u32 s14, s14, s26
	s_addc_u32 s15, s15, 0
	s_mul_i32 s26, s41, s39
	s_add_u32 s26, s26, s38
	s_lshl_b32 s27, s44, 5
	s_mul_i32 s27, s27, s40
	s_add_u32 s26, s26, s27
	s_lshl_b32 s27, s43, 7
	s_add_u32 s26, s26, s27
	s_add_u32 s18, s90, s26
	s_addc_u32 s19, s91, 0
	s_mov_b32 s22, s40
	v_mad_u32_u24 v7, v5, s36, v6
	s_lshl_b32 s45, s36, 3
	global_load_dwordx4 v[10:13], v7, s[14:15] nt
	s_add_u32 s14, s14, s45
	s_addc_u32 s15, s15, 0
	global_load_dwordx4 v[14:17], v7, s[14:15] nt
	s_add_u32 s14, s14, s45
	s_addc_u32 s15, s15, 0
	global_load_dwordx4 v[18:21], v7, s[14:15] nt
	s_add_u32 s14, s14, s45
	s_addc_u32 s15, s15, 0
	global_load_dwordx4 v[22:25], v7, s[14:15] nt
	s_add_u32 s14, s14, s45
	s_addc_u32 s15, s15, 0
	global_load_dwordx4 v[26:29], v7, s[14:15] nt
	s_add_u32 s14, s14, s45
	s_addc_u32 s15, s15, 0
	global_load_dwordx4 v[30:33], v7, s[14:15] nt
	s_add_u32 s14, s14, s45
	s_addc_u32 s15, s15, 0
	global_load_dwordx4 v[34:37], v7, s[14:15] nt
	s_add_u32 s14, s14, s45
	s_addc_u32 s15, s15, 0
	global_load_dwordx4 v[38:41], v7, s[14:15] nt
	s_add_u32 s25, s25, 1
	s_add_u32 s12, s12, 1024
	s_waitcnt vmcnt(36)
	s_branch .Ltrs_after69

.Ltrs_dec_done79:
	s_mul_i32 s26, s41, s37
	s_lshl_b32 s27, s43, 6
	s_mul_i32 s27, s27, s36
	s_add_u32 s26, s26, s27
	s_lshl_b32 s27, s44, 7
	s_add_u32 s26, s26, s27
	s_add_u32 s14, s14, s26
	s_addc_u32 s15, s15, 0
	s_mul_i32 s26, s41, s39
	s_add_u32 s26, s26, s38
	s_lshl_b32 s27, s44, 5
	s_mul_i32 s27, s27, s40
	s_add_u32 s26, s26, s27
	s_lshl_b32 s27, s43, 7
	s_add_u32 s26, s26, s27
	s_add_u32 s20, s90, s26
	s_addc_u32 s21, s91, 0
	s_mov_b32 s23, s40
	v_mad_u32_u24 v7, v5, s36, v6
	s_lshl_b32 s45, s36, 3
	global_load_dwordx4 v[42:45], v7, s[14:15] nt
	s_add_u32 s14, s14, s45
	s_addc_u32 s15, s15, 0
	global_load_dwordx4 v[46:49], v7, s[14:15] nt
	s_add_u32 s14, s14, s45
	s_addc_u32 s15, s15, 0
	global_load_dwordx4 v[50:53], v7, s[14:15] nt
	s_add_u32 s14, s14, s45
	s_addc_u32 s15, s15, 0
	global_load_dwordx4 v[54:57], v7, s[14:15] nt
	s_add_u32 s14, s14, s45
	s_addc_u32 s15, s15, 0
	global_load_dwordx4 v[58:61], v7, s[14:15] nt
	s_add_u32 s14, s14, s45
	s_addc_u32 s15, s15, 0
	global_load_dwordx4 v[62:65], v7, s[14:15] nt
	s_add_u32 s14, s14, s45
	s_addc_u32 s15, s15, 0
	global_load_dwordx4 v[66:69], v7, s[14:15] nt
	s_add_u32 s14, s14, s45
	s_addc_u32 s15, s15, 0
	global_load_dwordx4 v[70:73], v7, s[14:15] nt
	s_add_u32 s25, s25, 1
	s_add_u32 s12, s12, 1024
	s_waitcnt vmcnt(36)
	s_branch .Ltrs_after78

.LBB0_1734:
	s_cmp_lt_u32 s96, 160
	s_cbranch_scc1 .Lmix1_skip
	s_load_dwordx2 s[0:1], s[92:93], 0x58
	s_load_dwordx2 s[2:3], s[92:93], 0xb8
	s_load_dwordx2 s[4:5], s[92:93], 0xc0
	s_load_dwordx2 s[6:7], s[92:93], 0xc8
	s_load_dwordx2 s[8:9], s[92:93], 0xd0
	s_load_dwordx2 s[10:11], s[92:93], 0xe8
	v_and_b32_e32 v74, 63, v154
	v_lshrrev_b32_e32 v75, 6, v154
	v_mul_u32_u24_e32 v75, 0x2100, v75
	v_lshrrev_b32_e32 v3, 5, v74
	v_and_b32_e32 v4, 31, v74
	v_lshlrev_b32_e32 v4, 2, v4
	v_lshrrev_b32_e32 v5, 3, v74
	v_and_b32_e32 v6, 7, v74
	v_mul_u32_u24_e32 v2, 264, v6
	v_add_u32_e32 v2, v2, v5
	v_lshl_add_u32 v2, v2, 2, v75
	v_lshlrev_b32_e32 v6, 4, v6
	v_mul_u32_u24_e32 v1, 132, v5
	v_add3_u32 v1, v1, v6, v75
	v_readfirstlane_b32 s13, v154
	s_lshr_b32 s13, s13, 6
	s_lshl_b32 s26, s96, 3
	s_add_u32 s13, s13, s26
	s_sub_u32 s12, s13, 1280
	s_add_u32 s12, s12, 49664
	s_waitcnt lgkmcnt(0)
	s_mov_b32 s25, 0
	s_cmp_ge_u32 s12, 60928
	s_cbranch_scc1 .Ltrn_pro_end1
	s_cmp_ge_u32 s12, 33280
	s_cselect_b32 s41, 1, 0
	s_cselect_b32 s26, 33280, 0
	s_sub_u32 s42, s12, s26
	s_cmp_ge_u32 s42, 12288
	s_cbranch_scc1 .Ltrn_m3
	s_mul_i32 s43, s42, 43691
	s_lshr_b32 s43, s43, 24
	s_mul_i32 s26, s43, 384
	s_sub_u32 s44, s42, s26
	s_mov_b32 s14, s0
	s_mov_b32 s15, s1
	s_mov_b32 s36, 0xc000
	s_mov_b32 s37, 0x6000000
	s_mov_b32 s38, 0x0
	s_mov_b32 s39, 0x3000000
	s_mov_b32 s40, 0x1000
	s_branch .Ltrn_dec_done2

.Ltrn_dec_done2:
	s_mul_i32 s26, s41, s37
	s_lshl_b32 s27, s43, 6
	s_mul_i32 s27, s27, s36
	s_add_u32 s26, s26, s27
	s_lshl_b32 s27, s44, 7
	s_add_u32 s26, s26, s27
	s_add_u32 s14, s14, s26
	s_addc_u32 s15, s15, 0
	s_mul_i32 s26, s41, s39
	s_add_u32 s26, s26, s38
	s_lshl_b32 s27, s44, 5
	s_mul_i32 s27, s27, s40
	s_add_u32 s26, s26, s27
	s_lshl_b32 s27, s43, 7
	s_add_u32 s26, s26, s27
	s_add_u32 s18, s90, s26
	s_addc_u32 s19, s91, 0
	s_mov_b32 s22, s40
	v_mad_u32_u24 v7, v5, s36, v6
	s_lshl_b32 s45, s36, 3
	global_load_dwordx4 v[10:13], v7, s[14:15] nt
	s_add_u32 s14, s14, s45
	s_addc_u32 s15, s15, 0
	global_load_dwordx4 v[14:17], v7, s[14:15] nt
	s_add_u32 s14, s14, s45
	s_addc_u32 s15, s15, 0
	global_load_dwordx4 v[18:21], v7, s[14:15] nt
	s_add_u32 s14, s14, s45
	s_addc_u32 s15, s15, 0
	global_load_dwordx4 v[22:25], v7, s[14:15] nt
	s_add_u32 s14, s14, s45
	s_addc_u32 s15, s15, 0
	global_load_dwordx4 v[26:29], v7, s[14:15] nt
	s_add_u32 s14, s14, s45
	s_addc_u32 s15, s15, 0
	global_load_dwordx4 v[30:33], v7, s[14:15] nt
	s_add_u32 s14, s14, s45
	s_addc_u32 s15, s15, 0
	global_load_dwordx4 v[34:37], v7, s[14:15] nt
	s_add_u32 s14, s14, s45
	s_addc_u32 s15, s15, 0
	global_load_dwordx4 v[38:41], v7, s[14:15] nt
	s_add_u32 s25, s25, 1
	s_add_u32 s12, s12, 768
	s_cmp_ge_u32 s12, 60928
	s_cbranch_scc1 .Ltrn_pro_end1
	s_cmp_ge_u32 s12, 33280
	s_cselect_b32 s41, 1, 0
	s_cselect_b32 s26, 33280, 0
	s_sub_u32 s42, s12, s26
	s_cmp_ge_u32 s42, 12288
	s_cbranch_scc1 .Ltrn_m10
	s_mul_i32 s43, s42, 43691
	s_lshr_b32 s43, s43, 24
	s_mul_i32 s26, s43, 384
	s_sub_u32 s44, s42, s26
	s_mov_b32 s14, s0
	s_mov_b32 s15, s1
	s_mov_b32 s36, 0xc000
	s_mov_b32 s37, 0x6000000
	s_mov_b32 s38, 0x0
	s_mov_b32 s39, 0x3000000
	s_mov_b32 s40, 0x1000
	s_branch .Ltrn_dec_done9

.Ltrn_dec_done9:
	s_mul_i32 s26, s41, s37
	s_lshl_b32 s27, s43, 6
	s_mul_i32 s27, s27, s36
	s_add_u32 s26, s26, s27
	s_lshl_b32 s27, s44, 7
	s_add_u32 s26, s26, s27
	s_add_u32 s14, s14, s26
	s_addc_u32 s15, s15, 0
	s_mul_i32 s26, s41, s39
	s_add_u32 s26, s26, s38
	s_lshl_b32 s27, s44, 5
	s_mul_i32 s27, s27, s40
	s_add_u32 s26, s26, s27
	s_lshl_b32 s27, s43, 7
	s_add_u32 s26, s26, s27
	s_add_u32 s20, s90, s26
	s_addc_u32 s21, s91, 0
	s_mov_b32 s23, s40
	v_mad_u32_u24 v7, v5, s36, v6
	s_lshl_b32 s45, s36, 3
	global_load_dwordx4 v[42:45], v7, s[14:15] nt
	s_add_u32 s14, s14, s45
	s_addc_u32 s15, s15, 0
	global_load_dwordx4 v[46:49], v7, s[14:15] nt
	s_add_u32 s14, s14, s45
	s_addc_u32 s15, s15, 0
	global_load_dwordx4 v[50:53], v7, s[14:15] nt
	s_add_u32 s14, s14, s45
	s_addc_u32 s15, s15, 0
	global_load_dwordx4 v[54:57], v7, s[14:15] nt
	s_add_u32 s14, s14, s45
	s_addc_u32 s15, s15, 0
	global_load_dwordx4 v[58:61], v7, s[14:15] nt
	s_add_u32 s14, s14, s45
	s_addc_u32 s15, s15, 0
	global_load_dwordx4 v[62:65], v7, s[14:15] nt
	s_add_u32 s14, s14, s45
	s_addc_u32 s15, s15, 0
	global_load_dwordx4 v[66:69], v7, s[14:15] nt
	s_add_u32 s14, s14, s45
	s_addc_u32 s15, s15, 0
	global_load_dwordx4 v[70:73], v7, s[14:15] nt
	s_add_u32 s25, s25, 1
	s_add_u32 s12, s12, 768
	s_cmp_ge_u32 s12, 60928
	s_cbranch_scc1 .Ltrn_pro_end1
	s_cmp_ge_u32 s12, 33280
	s_cselect_b32 s41, 1, 0
	s_cselect_b32 s26, 33280, 0
	s_sub_u32 s42, s12, s26
	s_cmp_ge_u32 s42, 12288
	s_cbranch_scc1 .Ltrn_m17
	s_mul_i32 s43, s42, 43691
	s_lshr_b32 s43, s43, 24
	s_mul_i32 s26, s43, 384
	s_sub_u32 s44, s42, s26
	s_mov_b32 s14, s0
	s_mov_b32 s15, s1
	s_mov_b32 s36, 0xc000
	s_mov_b32 s37, 0x6000000
	s_mov_b32 s38, 0x0
	s_mov_b32 s39, 0x3000000
	s_mov_b32 s40, 0x1000
	s_branch .Ltrn_dec_done16

.Ltrn_pro_end1:
	s_cmp_eq_u32 s25, 0
	s_cbranch_scc1 .Ltrn_done
	s_cmp_lt_u32 s12, 60928
	s_cbranch_scc0 .Ltrn_nonext23
	s_cmp_ge_u32 s12, 33280
	s_cselect_b32 s41, 1, 0
	s_cselect_b32 s26, 33280, 0
	s_sub_u32 s42, s12, s26
	s_cmp_ge_u32 s42, 12288
	s_cbranch_scc1 .Ltrn_m26
	s_mul_i32 s43, s42, 43691
	s_lshr_b32 s43, s43, 24
	s_mul_i32 s26, s43, 384
	s_sub_u32 s44, s42, s26
	s_mov_b32 s14, s0
	s_mov_b32 s15, s1
	s_mov_b32 s36, 0xc000
	s_mov_b32 s37, 0x6000000
	s_mov_b32 s38, 0x0
	s_mov_b32 s39, 0x3000000
	s_mov_b32 s40, 0x1000
	s_branch .Ltrn_dec_done25

.Ltrn_after24:
	ds_write_b32 v1, v10 offset:0
	ds_write_b32 v1, v11 offset:4
	ds_write_b32 v1, v12 offset:8
	ds_write_b32 v1, v13 offset:12
	ds_write_b32 v1, v14 offset:1056
	ds_write_b32 v1, v15 offset:1060
	ds_write_b32 v1, v16 offset:1064
	ds_write_b32 v1, v17 offset:1068
	ds_write_b32 v1, v18 offset:2112
	ds_write_b32 v1, v19 offset:2116
	ds_write_b32 v1, v20 offset:2120
	ds_write_b32 v1, v21 offset:2124
	ds_write_b32 v1, v22 offset:3168
	ds_write_b32 v1, v23 offset:3172
	ds_write_b32 v1, v24 offset:3176
	ds_write_b32 v1, v25 offset:3180
	ds_write_b32 v1, v26 offset:4224
	ds_write_b32 v1, v27 offset:4228
	ds_write_b32 v1, v28 offset:4232
	ds_write_b32 v1, v29 offset:4236
	ds_write_b32 v1, v30 offset:5280
	ds_write_b32 v1, v31 offset:5284
	ds_write_b32 v1, v32 offset:5288
	ds_write_b32 v1, v33 offset:5292
	ds_write_b32 v1, v34 offset:6336
	ds_write_b32 v1, v35 offset:6340
	ds_write_b32 v1, v36 offset:6344
	ds_write_b32 v1, v37 offset:6348
	ds_write_b32 v1, v38 offset:7392
	ds_write_b32 v1, v39 offset:7396
	ds_write_b32 v1, v40 offset:7400
	ds_write_b32 v1, v41 offset:7404
	v_mad_u32_u24 v9, v5, s22, v6
	s_lshl_b32 s46, s22, 3
	s_waitcnt lgkmcnt(0)
	ds_read_b32 v74, v2 offset:0
	ds_read_b32 v75, v2 offset:132
	ds_read_b32 v76, v2 offset:264
	ds_read_b32 v77, v2 offset:396
	ds_read_b32 v78, v2 offset:528
	ds_read_b32 v79, v2 offset:660
	ds_read_b32 v80, v2 offset:792
	ds_read_b32 v81, v2 offset:924
	ds_read_b32 v82, v2 offset:32
	ds_read_b32 v83, v2 offset:164
	ds_read_b32 v84, v2 offset:296
	ds_read_b32 v85, v2 offset:428
	ds_read_b32 v86, v2 offset:560
	ds_read_b32 v87, v2 offset:692
	ds_read_b32 v88, v2 offset:824
	ds_read_b32 v89, v2 offset:956
	s_waitcnt lgkmcnt(8)
	v_cvt_pk_bf16_f32 v106, v74, v75
	v_cvt_pk_bf16_f32 v107, v76, v77
	v_cvt_pk_bf16_f32 v108, v78, v79
	v_cvt_pk_bf16_f32 v109, v80, v81
	global_store_dwordx4 v9, v[106:109], s[18:19]
	s_add_u32 s18, s18, s46
	s_addc_u32 s19, s19, 0
	ds_read_b32 v90, v2 offset:64
	ds_read_b32 v91, v2 offset:196
	ds_read_b32 v92, v2 offset:328
	ds_read_b32 v93, v2 offset:460
	ds_read_b32 v94, v2 offset:592
	ds_read_b32 v95, v2 offset:724
	ds_read_b32 v96, v2 offset:856
	ds_read_b32 v97, v2 offset:988
	s_waitcnt lgkmcnt(8)
	v_cvt_pk_bf16_f32 v110, v82, v83
	v_cvt_pk_bf16_f32 v111, v84, v85
	v_cvt_pk_bf16_f32 v112, v86, v87
	v_cvt_pk_bf16_f32 v113, v88, v89
	global_store_dwordx4 v9, v[110:113], s[18:19]
	s_add_u32 s18, s18, s46
	s_addc_u32 s19, s19, 0
	ds_read_b32 v98, v2 offset:96
	ds_read_b32 v99, v2 offset:228
	ds_read_b32 v100, v2 offset:360
	ds_read_b32 v101, v2 offset:492
	ds_read_b32 v102, v2 offset:624
	ds_read_b32 v103, v2 offset:756
	ds_read_b32 v104, v2 offset:888
	ds_read_b32 v105, v2 offset:1020
	s_waitcnt lgkmcnt(8)
	v_cvt_pk_bf16_f32 v106, v90, v91
	v_cvt_pk_bf16_f32 v107, v92, v93
	v_cvt_pk_bf16_f32 v108, v94, v95
	v_cvt_pk_bf16_f32 v109, v96, v97
	global_store_dwordx4 v9, v[106:109], s[18:19]
	s_add_u32 s18, s18, s46
	s_addc_u32 s19, s19, 0
	s_waitcnt lgkmcnt(0)
	v_cvt_pk_bf16_f32 v110, v98, v99
	v_cvt_pk_bf16_f32 v111, v100, v101
	v_cvt_pk_bf16_f32 v112, v102, v103
	v_cvt_pk_bf16_f32 v113, v104, v105
	global_store_dwordx4 v9, v[110:113], s[18:19]
	s_sub_u32 s25, s25, 1
	s_cmp_eq_u32 s25, 0
	s_cbranch_scc1 .Ltrn_done
	s_cmp_lt_u32 s12, 60928
	s_cbranch_scc0 .Ltrn_nonext32
	s_cmp_ge_u32 s12, 33280
	s_cselect_b32 s41, 1, 0
	s_cselect_b32 s26, 33280, 0
	s_sub_u32 s42, s12, s26
	s_cmp_ge_u32 s42, 12288
	s_cbranch_scc1 .Ltrn_m35
	s_mul_i32 s43, s42, 43691
	s_lshr_b32 s43, s43, 24
	s_mul_i32 s26, s43, 384
	s_sub_u32 s44, s42, s26
	s_mov_b32 s14, s0
	s_mov_b32 s15, s1
	s_mov_b32 s36, 0xc000
	s_mov_b32 s37, 0x6000000
	s_mov_b32 s38, 0x0
	s_mov_b32 s39, 0x3000000
	s_mov_b32 s40, 0x1000
	s_branch .Ltrn_dec_done34

.Ltrn_after33:
	ds_write_b32 v1, v42 offset:0
	ds_write_b32 v1, v43 offset:4
	ds_write_b32 v1, v44 offset:8
	ds_write_b32 v1, v45 offset:12
	ds_write_b32 v1, v46 offset:1056
	ds_write_b32 v1, v47 offset:1060
	ds_write_b32 v1, v48 offset:1064
	ds_write_b32 v1, v49 offset:1068
	ds_write_b32 v1, v50 offset:2112
	ds_write_b32 v1, v51 offset:2116
	ds_write_b32 v1, v52 offset:2120
	ds_write_b32 v1, v53 offset:2124
	ds_write_b32 v1, v54 offset:3168
	ds_write_b32 v1, v55 offset:3172
	ds_write_b32 v1, v56 offset:3176
	ds_write_b32 v1, v57 offset:3180
	ds_write_b32 v1, v58 offset:4224
	ds_write_b32 v1, v59 offset:4228
	ds_write_b32 v1, v60 offset:4232
	ds_write_b32 v1, v61 offset:4236
	ds_write_b32 v1, v62 offset:5280
	ds_write_b32 v1, v63 offset:5284
	ds_write_b32 v1, v64 offset:5288
	ds_write_b32 v1, v65 offset:5292
	ds_write_b32 v1, v66 offset:6336
	ds_write_b32 v1, v67 offset:6340
	ds_write_b32 v1, v68 offset:6344
	ds_write_b32 v1, v69 offset:6348
	ds_write_b32 v1, v70 offset:7392
	ds_write_b32 v1, v71 offset:7396
	ds_write_b32 v1, v72 offset:7400
	ds_write_b32 v1, v73 offset:7404
	v_mad_u32_u24 v9, v5, s23, v6
	s_lshl_b32 s46, s23, 3
	s_waitcnt lgkmcnt(0)
	ds_read_b32 v74, v2 offset:0
	ds_read_b32 v75, v2 offset:132
	ds_read_b32 v76, v2 offset:264
	ds_read_b32 v77, v2 offset:396
	ds_read_b32 v78, v2 offset:528
	ds_read_b32 v79, v2 offset:660
	ds_read_b32 v80, v2 offset:792
	ds_read_b32 v81, v2 offset:924
	ds_read_b32 v82, v2 offset:32
	ds_read_b32 v83, v2 offset:164
	ds_read_b32 v84, v2 offset:296
	ds_read_b32 v85, v2 offset:428
	ds_read_b32 v86, v2 offset:560
	ds_read_b32 v87, v2 offset:692
	ds_read_b32 v88, v2 offset:824
	ds_read_b32 v89, v2 offset:956
	s_waitcnt lgkmcnt(8)
	v_cvt_pk_bf16_f32 v106, v74, v75
	v_cvt_pk_bf16_f32 v107, v76, v77
	v_cvt_pk_bf16_f32 v108, v78, v79
	v_cvt_pk_bf16_f32 v109, v80, v81
	global_store_dwordx4 v9, v[106:109], s[20:21]
	s_add_u32 s20, s20, s46
	s_addc_u32 s21, s21, 0
	ds_read_b32 v90, v2 offset:64
	ds_read_b32 v91, v2 offset:196
	ds_read_b32 v92, v2 offset:328
	ds_read_b32 v93, v2 offset:460
	ds_read_b32 v94, v2 offset:592
	ds_read_b32 v95, v2 offset:724
	ds_read_b32 v96, v2 offset:856
	ds_read_b32 v97, v2 offset:988
	s_waitcnt lgkmcnt(8)
	v_cvt_pk_bf16_f32 v110, v82, v83
	v_cvt_pk_bf16_f32 v111, v84, v85
	v_cvt_pk_bf16_f32 v112, v86, v87
	v_cvt_pk_bf16_f32 v113, v88, v89
	global_store_dwordx4 v9, v[110:113], s[20:21]
	s_add_u32 s20, s20, s46
	s_addc_u32 s21, s21, 0
	ds_read_b32 v98, v2 offset:96
	ds_read_b32 v99, v2 offset:228
	ds_read_b32 v100, v2 offset:360
	ds_read_b32 v101, v2 offset:492
	ds_read_b32 v102, v2 offset:624
	ds_read_b32 v103, v2 offset:756
	ds_read_b32 v104, v2 offset:888
	ds_read_b32 v105, v2 offset:1020
	s_waitcnt lgkmcnt(8)
	v_cvt_pk_bf16_f32 v106, v90, v91
	v_cvt_pk_bf16_f32 v107, v92, v93
	v_cvt_pk_bf16_f32 v108, v94, v95
	v_cvt_pk_bf16_f32 v109, v96, v97
	global_store_dwordx4 v9, v[106:109], s[20:21]
	s_add_u32 s20, s20, s46
	s_addc_u32 s21, s21, 0
	s_waitcnt lgkmcnt(0)
	v_cvt_pk_bf16_f32 v110, v98, v99
	v_cvt_pk_bf16_f32 v111, v100, v101
	v_cvt_pk_bf16_f32 v112, v102, v103
	v_cvt_pk_bf16_f32 v113, v104, v105
	global_store_dwordx4 v9, v[110:113], s[20:21]
	s_sub_u32 s25, s25, 1
	s_cmp_eq_u32 s25, 0
	s_cbranch_scc1 .Ltrn_done
	s_cmp_lt_u32 s12, 60928
	s_cbranch_scc0 .Ltrn_nonext41
	s_cmp_ge_u32 s12, 33280
	s_cselect_b32 s41, 1, 0
	s_cselect_b32 s26, 33280, 0
	s_sub_u32 s42, s12, s26
	s_cmp_ge_u32 s42, 12288
	s_cbranch_scc1 .Ltrn_m44
	s_mul_i32 s43, s42, 43691
	s_lshr_b32 s43, s43, 24
	s_mul_i32 s26, s43, 384
	s_sub_u32 s44, s42, s26
	s_mov_b32 s14, s0
	s_mov_b32 s15, s1
	s_mov_b32 s36, 0xc000
	s_mov_b32 s37, 0x6000000
	s_mov_b32 s38, 0x0
	s_mov_b32 s39, 0x3000000
	s_mov_b32 s40, 0x1000
	s_branch .Ltrn_dec_done43

.Ltrn_after42:
	ds_write_b32 v1, v114 offset:0
	ds_write_b32 v1, v115 offset:4
	ds_write_b32 v1, v116 offset:8
	ds_write_b32 v1, v117 offset:12
	ds_write_b32 v1, v118 offset:1056
	ds_write_b32 v1, v119 offset:1060
	ds_write_b32 v1, v120 offset:1064
	ds_write_b32 v1, v121 offset:1068
	ds_write_b32 v1, v122 offset:2112
	ds_write_b32 v1, v123 offset:2116
	ds_write_b32 v1, v124 offset:2120
	ds_write_b32 v1, v125 offset:2124
	ds_write_b32 v1, v126 offset:3168
	ds_write_b32 v1, v127 offset:3172
	ds_write_b32 v1, v128 offset:3176
	ds_write_b32 v1, v129 offset:3180
	ds_write_b32 v1, v130 offset:4224
	ds_write_b32 v1, v131 offset:4228
	ds_write_b32 v1, v132 offset:4232
	ds_write_b32 v1, v133 offset:4236
	ds_write_b32 v1, v134 offset:5280
	ds_write_b32 v1, v135 offset:5284
	ds_write_b32 v1, v136 offset:5288
	ds_write_b32 v1, v137 offset:5292
	ds_write_b32 v1, v138 offset:6336
	ds_write_b32 v1, v139 offset:6340
	ds_write_b32 v1, v140 offset:6344
	ds_write_b32 v1, v141 offset:6348
	ds_write_b32 v1, v142 offset:7392
	ds_write_b32 v1, v143 offset:7396
	ds_write_b32 v1, v144 offset:7400
	ds_write_b32 v1, v145 offset:7404
	v_mad_u32_u24 v9, v5, s52, v6
	s_lshl_b32 s46, s52, 3
	s_waitcnt lgkmcnt(0)
	ds_read_b32 v74, v2 offset:0
	ds_read_b32 v75, v2 offset:132
	ds_read_b32 v76, v2 offset:264
	ds_read_b32 v77, v2 offset:396
	ds_read_b32 v78, v2 offset:528
	ds_read_b32 v79, v2 offset:660
	ds_read_b32 v80, v2 offset:792
	ds_read_b32 v81, v2 offset:924
	ds_read_b32 v82, v2 offset:32
	ds_read_b32 v83, v2 offset:164
	ds_read_b32 v84, v2 offset:296
	ds_read_b32 v85, v2 offset:428
	ds_read_b32 v86, v2 offset:560
	ds_read_b32 v87, v2 offset:692
	ds_read_b32 v88, v2 offset:824
	ds_read_b32 v89, v2 offset:956
	s_waitcnt lgkmcnt(8)
	v_cvt_pk_bf16_f32 v106, v74, v75
	v_cvt_pk_bf16_f32 v107, v76, v77
	v_cvt_pk_bf16_f32 v108, v78, v79
	v_cvt_pk_bf16_f32 v109, v80, v81
	global_store_dwordx4 v9, v[106:109], s[48:49]
	s_add_u32 s48, s48, s46
	s_addc_u32 s49, s49, 0
	ds_read_b32 v90, v2 offset:64
	ds_read_b32 v91, v2 offset:196
	ds_read_b32 v92, v2 offset:328
	ds_read_b32 v93, v2 offset:460
	ds_read_b32 v94, v2 offset:592
	ds_read_b32 v95, v2 offset:724
	ds_read_b32 v96, v2 offset:856
	ds_read_b32 v97, v2 offset:988
	s_waitcnt lgkmcnt(8)
	v_cvt_pk_bf16_f32 v110, v82, v83
	v_cvt_pk_bf16_f32 v111, v84, v85
	v_cvt_pk_bf16_f32 v112, v86, v87
	v_cvt_pk_bf16_f32 v113, v88, v89
	global_store_dwordx4 v9, v[110:113], s[48:49]
	s_add_u32 s48, s48, s46
	s_addc_u32 s49, s49, 0
	ds_read_b32 v98, v2 offset:96
	ds_read_b32 v99, v2 offset:228
	ds_read_b32 v100, v2 offset:360
	ds_read_b32 v101, v2 offset:492
	ds_read_b32 v102, v2 offset:624
	ds_read_b32 v103, v2 offset:756
	ds_read_b32 v104, v2 offset:888
	ds_read_b32 v105, v2 offset:1020
	s_waitcnt lgkmcnt(8)
	v_cvt_pk_bf16_f32 v106, v90, v91
	v_cvt_pk_bf16_f32 v107, v92, v93
	v_cvt_pk_bf16_f32 v108, v94, v95
	v_cvt_pk_bf16_f32 v109, v96, v97
	global_store_dwordx4 v9, v[106:109], s[48:49]
	s_add_u32 s48, s48, s46
	s_addc_u32 s49, s49, 0
	s_waitcnt lgkmcnt(0)
	v_cvt_pk_bf16_f32 v110, v98, v99
	v_cvt_pk_bf16_f32 v111, v100, v101
	v_cvt_pk_bf16_f32 v112, v102, v103
	v_cvt_pk_bf16_f32 v113, v104, v105
	global_store_dwordx4 v9, v[110:113], s[48:49]
	s_sub_u32 s25, s25, 1
	s_cmp_eq_u32 s25, 0
	s_cbranch_scc1 .Ltrn_done
	s_cmp_lt_u32 s12, 60928
	s_cbranch_scc0 .Ltrn_nonext50
	s_cmp_ge_u32 s12, 33280
	s_cselect_b32 s41, 1, 0
	s_cselect_b32 s26, 33280, 0
	s_sub_u32 s42, s12, s26
	s_cmp_ge_u32 s42, 12288
	s_cbranch_scc1 .Ltrn_m53
	s_mul_i32 s43, s42, 43691
	s_lshr_b32 s43, s43, 24
	s_mul_i32 s26, s43, 384
	s_sub_u32 s44, s42, s26
	s_mov_b32 s14, s0
	s_mov_b32 s15, s1
	s_mov_b32 s36, 0xc000
	s_mov_b32 s37, 0x6000000
	s_mov_b32 s38, 0x0
	s_mov_b32 s39, 0x3000000
	s_mov_b32 s40, 0x1000
	s_branch .Ltrn_dec_done52

.Ltrn_loop:
	s_cmp_lt_u32 s12, 60928
	s_cbranch_scc0 .Ltrn_nonext59
	s_cmp_ge_u32 s12, 33280
	s_cselect_b32 s41, 1, 0
	s_cselect_b32 s26, 33280, 0
	s_sub_u32 s42, s12, s26
	s_cmp_ge_u32 s42, 12288
	s_cbranch_scc1 .Ltrn_m62
	s_mul_i32 s43, s42, 43691
	s_lshr_b32 s43, s43, 24
	s_mul_i32 s26, s43, 384
	s_sub_u32 s44, s42, s26
	s_mov_b32 s14, s0
	s_mov_b32 s15, s1
	s_mov_b32 s36, 0xc000
	s_mov_b32 s37, 0x6000000
	s_mov_b32 s38, 0x0
	s_mov_b32 s39, 0x3000000
	s_mov_b32 s40, 0x1000
	s_branch .Ltrn_dec_done61

.LBB0_2416:
	s_waitcnt vmcnt(0)
	s_barrier
	s_cmp_lt_u32 s96, 128
	s_cbranch_scc1 .LBB0_2417
	s_load_dwordx2 s[0:1], s[92:93], 0x58
	s_load_dwordx2 s[2:3], s[92:93], 0xb8
	s_load_dwordx2 s[4:5], s[92:93], 0xc0
	s_load_dwordx2 s[6:7], s[92:93], 0xc8
	s_load_dwordx2 s[8:9], s[92:93], 0xd0
	s_load_dwordx2 s[10:11], s[92:93], 0xe8
	v_and_b32_e32 v74, 63, v154
	v_lshrrev_b32_e32 v75, 6, v154
	v_mul_u32_u24_e32 v75, 0x2100, v75
	v_lshrrev_b32_e32 v3, 5, v74
	v_and_b32_e32 v4, 31, v74
	v_lshlrev_b32_e32 v4, 2, v4
	v_lshrrev_b32_e32 v5, 3, v74
	v_and_b32_e32 v6, 7, v74
	v_mul_u32_u24_e32 v2, 264, v6
	v_add_u32_e32 v2, v2, v5
	v_lshl_add_u32 v2, v2, 2, v75
	v_lshlrev_b32_e32 v6, 4, v6
	v_mul_u32_u24_e32 v1, 132, v5
	v_add3_u32 v1, v1, v6, v75
	v_readfirstlane_b32 s13, v154
	s_lshr_b32 s13, s13, 6
	s_lshl_b32 s26, s96, 3
	s_add_u32 s13, s13, s26
	s_sub_u32 s12, s13, 1024
	s_add_u32 s12, s12, 60928
	s_waitcnt lgkmcnt(0)
	s_mov_b32 s25, 0
	s_cmp_ge_u32 s12, 66560
	s_cbranch_scc1 .Ltrt_pro_end1
	s_cmp_ge_u32 s12, 33280
	s_cselect_b32 s41, 1, 0
	s_cselect_b32 s26, 33280, 0
	s_sub_u32 s42, s12, s26
	s_cmp_ge_u32 s42, 12288
	s_cbranch_scc1 .Ltrt_m3
	s_mul_i32 s43, s42, 43691
	s_lshr_b32 s43, s43, 24
	s_mul_i32 s26, s43, 384
	s_sub_u32 s44, s42, s26
	s_mov_b32 s14, s0
	s_mov_b32 s15, s1
	s_mov_b32 s36, 0xc000
	s_mov_b32 s37, 0x6000000
	s_mov_b32 s38, 0x0
	s_mov_b32 s39, 0x3000000
	s_mov_b32 s40, 0x1000
	s_branch .Ltrt_dec_done2

.Ltrt_dec_done2:
	s_mul_i32 s26, s41, s37
	s_lshl_b32 s27, s43, 6
	s_mul_i32 s27, s27, s36
	s_add_u32 s26, s26, s27
	s_lshl_b32 s27, s44, 7
	s_add_u32 s26, s26, s27
	s_add_u32 s14, s14, s26
	s_addc_u32 s15, s15, 0
	s_mul_i32 s26, s41, s39
	s_add_u32 s26, s26, s38
	s_lshl_b32 s27, s44, 5
	s_mul_i32 s27, s27, s40
	s_add_u32 s26, s26, s27
	s_lshl_b32 s27, s43, 7
	s_add_u32 s26, s26, s27
	s_add_u32 s18, s90, s26
	s_addc_u32 s19, s91, 0
	s_mov_b32 s22, s40
	v_mad_u32_u24 v7, v5, s36, v6
	s_lshl_b32 s45, s36, 3
	global_load_dwordx4 v[10:13], v7, s[14:15] nt
	s_add_u32 s14, s14, s45
	s_addc_u32 s15, s15, 0
	global_load_dwordx4 v[14:17], v7, s[14:15] nt
	s_add_u32 s14, s14, s45
	s_addc_u32 s15, s15, 0
	global_load_dwordx4 v[18:21], v7, s[14:15] nt
	s_add_u32 s14, s14, s45
	s_addc_u32 s15, s15, 0
	global_load_dwordx4 v[22:25], v7, s[14:15] nt
	s_add_u32 s14, s14, s45
	s_addc_u32 s15, s15, 0
	global_load_dwordx4 v[26:29], v7, s[14:15] nt
	s_add_u32 s14, s14, s45
	s_addc_u32 s15, s15, 0
	global_load_dwordx4 v[30:33], v7, s[14:15] nt
	s_add_u32 s14, s14, s45
	s_addc_u32 s15, s15, 0
	global_load_dwordx4 v[34:37], v7, s[14:15] nt
	s_add_u32 s14, s14, s45
	s_addc_u32 s15, s15, 0
	global_load_dwordx4 v[38:41], v7, s[14:15] nt
	s_add_u32 s25, s25, 1
	s_add_u32 s12, s12, 1024
	s_cmp_ge_u32 s12, 66560
	s_cbranch_scc1 .Ltrt_pro_end1
	s_cmp_ge_u32 s12, 33280
	s_cselect_b32 s41, 1, 0
	s_cselect_b32 s26, 33280, 0
	s_sub_u32 s42, s12, s26
	s_cmp_ge_u32 s42, 12288
	s_cbranch_scc1 .Ltrt_m10
	s_mul_i32 s43, s42, 43691
	s_lshr_b32 s43, s43, 24
	s_mul_i32 s26, s43, 384
	s_sub_u32 s44, s42, s26
	s_mov_b32 s14, s0
	s_mov_b32 s15, s1
	s_mov_b32 s36, 0xc000
	s_mov_b32 s37, 0x6000000
	s_mov_b32 s38, 0x0
	s_mov_b32 s39, 0x3000000
	s_mov_b32 s40, 0x1000
	s_branch .Ltrt_dec_done9

.Ltrt_dec_done9:
	s_mul_i32 s26, s41, s37
	s_lshl_b32 s27, s43, 6
	s_mul_i32 s27, s27, s36
	s_add_u32 s26, s26, s27
	s_lshl_b32 s27, s44, 7
	s_add_u32 s26, s26, s27
	s_add_u32 s14, s14, s26
	s_addc_u32 s15, s15, 0
	s_mul_i32 s26, s41, s39
	s_add_u32 s26, s26, s38
	s_lshl_b32 s27, s44, 5
	s_mul_i32 s27, s27, s40
	s_add_u32 s26, s26, s27
	s_lshl_b32 s27, s43, 7
	s_add_u32 s26, s26, s27
	s_add_u32 s20, s90, s26
	s_addc_u32 s21, s91, 0
	s_mov_b32 s23, s40
	v_mad_u32_u24 v7, v5, s36, v6
	s_lshl_b32 s45, s36, 3
	global_load_dwordx4 v[42:45], v7, s[14:15] nt
	s_add_u32 s14, s14, s45
	s_addc_u32 s15, s15, 0
	global_load_dwordx4 v[46:49], v7, s[14:15] nt
	s_add_u32 s14, s14, s45
	s_addc_u32 s15, s15, 0
	global_load_dwordx4 v[50:53], v7, s[14:15] nt
	s_add_u32 s14, s14, s45
	s_addc_u32 s15, s15, 0
	global_load_dwordx4 v[54:57], v7, s[14:15] nt
	s_add_u32 s14, s14, s45
	s_addc_u32 s15, s15, 0
	global_load_dwordx4 v[58:61], v7, s[14:15] nt
	s_add_u32 s14, s14, s45
	s_addc_u32 s15, s15, 0
	global_load_dwordx4 v[62:65], v7, s[14:15] nt
	s_add_u32 s14, s14, s45
	s_addc_u32 s15, s15, 0
	global_load_dwordx4 v[66:69], v7, s[14:15] nt
	s_add_u32 s14, s14, s45
	s_addc_u32 s15, s15, 0
	global_load_dwordx4 v[70:73], v7, s[14:15] nt
	s_add_u32 s25, s25, 1
	s_add_u32 s12, s12, 1024
	s_cmp_ge_u32 s12, 66560
	s_cbranch_scc1 .Ltrt_pro_end1
	s_cmp_ge_u32 s12, 33280
	s_cselect_b32 s41, 1, 0
	s_cselect_b32 s26, 33280, 0
	s_sub_u32 s42, s12, s26
	s_cmp_ge_u32 s42, 12288
	s_cbranch_scc1 .Ltrt_m17
	s_mul_i32 s43, s42, 43691
	s_lshr_b32 s43, s43, 24
	s_mul_i32 s26, s43, 384
	s_sub_u32 s44, s42, s26
	s_mov_b32 s14, s0
	s_mov_b32 s15, s1
	s_mov_b32 s36, 0xc000
	s_mov_b32 s37, 0x6000000
	s_mov_b32 s38, 0x0
	s_mov_b32 s39, 0x3000000
	s_mov_b32 s40, 0x1000
	s_branch .Ltrt_dec_done16

.Ltrt_pro_end1:
	s_cmp_eq_u32 s25, 0
	s_cbranch_scc1 .Ltrt_done
	s_cmp_lt_u32 s12, 66560
	s_cbranch_scc0 .Ltrt_nonext23
	s_cmp_ge_u32 s12, 33280
	s_cselect_b32 s41, 1, 0
	s_cselect_b32 s26, 33280, 0
	s_sub_u32 s42, s12, s26
	s_cmp_ge_u32 s42, 12288
	s_cbranch_scc1 .Ltrt_m26
	s_mul_i32 s43, s42, 43691
	s_lshr_b32 s43, s43, 24
	s_mul_i32 s26, s43, 384
	s_sub_u32 s44, s42, s26
	s_mov_b32 s14, s0
	s_mov_b32 s15, s1
	s_mov_b32 s36, 0xc000
	s_mov_b32 s37, 0x6000000
	s_mov_b32 s38, 0x0
	s_mov_b32 s39, 0x3000000
	s_mov_b32 s40, 0x1000
	s_branch .Ltrt_dec_done25

.Ltrt_after24:
	ds_write_b32 v1, v10 offset:0
	ds_write_b32 v1, v11 offset:4
	ds_write_b32 v1, v12 offset:8
	ds_write_b32 v1, v13 offset:12
	ds_write_b32 v1, v14 offset:1056
	ds_write_b32 v1, v15 offset:1060
	ds_write_b32 v1, v16 offset:1064
	ds_write_b32 v1, v17 offset:1068
	ds_write_b32 v1, v18 offset:2112
	ds_write_b32 v1, v19 offset:2116
	ds_write_b32 v1, v20 offset:2120
	ds_write_b32 v1, v21 offset:2124
	ds_write_b32 v1, v22 offset:3168
	ds_write_b32 v1, v23 offset:3172
	ds_write_b32 v1, v24 offset:3176
	ds_write_b32 v1, v25 offset:3180
	ds_write_b32 v1, v26 offset:4224
	ds_write_b32 v1, v27 offset:4228
	ds_write_b32 v1, v28 offset:4232
	ds_write_b32 v1, v29 offset:4236
	ds_write_b32 v1, v30 offset:5280
	ds_write_b32 v1, v31 offset:5284
	ds_write_b32 v1, v32 offset:5288
	ds_write_b32 v1, v33 offset:5292
	ds_write_b32 v1, v34 offset:6336
	ds_write_b32 v1, v35 offset:6340
	ds_write_b32 v1, v36 offset:6344
	ds_write_b32 v1, v37 offset:6348
	ds_write_b32 v1, v38 offset:7392
	ds_write_b32 v1, v39 offset:7396
	ds_write_b32 v1, v40 offset:7400
	ds_write_b32 v1, v41 offset:7404
	v_mad_u32_u24 v9, v5, s22, v6
	s_lshl_b32 s46, s22, 3
	s_waitcnt lgkmcnt(0)
	ds_read_b32 v74, v2 offset:0
	ds_read_b32 v75, v2 offset:132
	ds_read_b32 v76, v2 offset:264
	ds_read_b32 v77, v2 offset:396
	ds_read_b32 v78, v2 offset:528
	ds_read_b32 v79, v2 offset:660
	ds_read_b32 v80, v2 offset:792
	ds_read_b32 v81, v2 offset:924
	ds_read_b32 v82, v2 offset:32
	ds_read_b32 v83, v2 offset:164
	ds_read_b32 v84, v2 offset:296
	ds_read_b32 v85, v2 offset:428
	ds_read_b32 v86, v2 offset:560
	ds_read_b32 v87, v2 offset:692
	ds_read_b32 v88, v2 offset:824
	ds_read_b32 v89, v2 offset:956
	s_waitcnt lgkmcnt(8)
	v_cvt_pk_bf16_f32 v106, v74, v75
	v_cvt_pk_bf16_f32 v107, v76, v77
	v_cvt_pk_bf16_f32 v108, v78, v79
	v_cvt_pk_bf16_f32 v109, v80, v81
	global_store_dwordx4 v9, v[106:109], s[18:19]
	s_add_u32 s18, s18, s46
	s_addc_u32 s19, s19, 0
	ds_read_b32 v90, v2 offset:64
	ds_read_b32 v91, v2 offset:196
	ds_read_b32 v92, v2 offset:328
	ds_read_b32 v93, v2 offset:460
	ds_read_b32 v94, v2 offset:592
	ds_read_b32 v95, v2 offset:724
	ds_read_b32 v96, v2 offset:856
	ds_read_b32 v97, v2 offset:988
	s_waitcnt lgkmcnt(8)
	v_cvt_pk_bf16_f32 v110, v82, v83
	v_cvt_pk_bf16_f32 v111, v84, v85
	v_cvt_pk_bf16_f32 v112, v86, v87
	v_cvt_pk_bf16_f32 v113, v88, v89
	global_store_dwordx4 v9, v[110:113], s[18:19]
	s_add_u32 s18, s18, s46
	s_addc_u32 s19, s19, 0
	ds_read_b32 v98, v2 offset:96
	ds_read_b32 v99, v2 offset:228
	ds_read_b32 v100, v2 offset:360
	ds_read_b32 v101, v2 offset:492
	ds_read_b32 v102, v2 offset:624
	ds_read_b32 v103, v2 offset:756
	ds_read_b32 v104, v2 offset:888
	ds_read_b32 v105, v2 offset:1020
	s_waitcnt lgkmcnt(8)
	v_cvt_pk_bf16_f32 v106, v90, v91
	v_cvt_pk_bf16_f32 v107, v92, v93
	v_cvt_pk_bf16_f32 v108, v94, v95
	v_cvt_pk_bf16_f32 v109, v96, v97
	global_store_dwordx4 v9, v[106:109], s[18:19]
	s_add_u32 s18, s18, s46
	s_addc_u32 s19, s19, 0
	s_waitcnt lgkmcnt(0)
	v_cvt_pk_bf16_f32 v110, v98, v99
	v_cvt_pk_bf16_f32 v111, v100, v101
	v_cvt_pk_bf16_f32 v112, v102, v103
	v_cvt_pk_bf16_f32 v113, v104, v105
	global_store_dwordx4 v9, v[110:113], s[18:19]
	s_sub_u32 s25, s25, 1
	s_cmp_eq_u32 s25, 0
	s_cbranch_scc1 .Ltrt_done
	s_cmp_lt_u32 s12, 66560
	s_cbranch_scc0 .Ltrt_nonext32
	s_cmp_ge_u32 s12, 33280
	s_cselect_b32 s41, 1, 0
	s_cselect_b32 s26, 33280, 0
	s_sub_u32 s42, s12, s26
	s_cmp_ge_u32 s42, 12288
	s_cbranch_scc1 .Ltrt_m35
	s_mul_i32 s43, s42, 43691
	s_lshr_b32 s43, s43, 24
	s_mul_i32 s26, s43, 384
	s_sub_u32 s44, s42, s26
	s_mov_b32 s14, s0
	s_mov_b32 s15, s1
	s_mov_b32 s36, 0xc000
	s_mov_b32 s37, 0x6000000
	s_mov_b32 s38, 0x0
	s_mov_b32 s39, 0x3000000
	s_mov_b32 s40, 0x1000
	s_branch .Ltrt_dec_done34

.Ltrt_after33:
	ds_write_b32 v1, v42 offset:0
	ds_write_b32 v1, v43 offset:4
	ds_write_b32 v1, v44 offset:8
	ds_write_b32 v1, v45 offset:12
	ds_write_b32 v1, v46 offset:1056
	ds_write_b32 v1, v47 offset:1060
	ds_write_b32 v1, v48 offset:1064
	ds_write_b32 v1, v49 offset:1068
	ds_write_b32 v1, v50 offset:2112
	ds_write_b32 v1, v51 offset:2116
	ds_write_b32 v1, v52 offset:2120
	ds_write_b32 v1, v53 offset:2124
	ds_write_b32 v1, v54 offset:3168
	ds_write_b32 v1, v55 offset:3172
	ds_write_b32 v1, v56 offset:3176
	ds_write_b32 v1, v57 offset:3180
	ds_write_b32 v1, v58 offset:4224
	ds_write_b32 v1, v59 offset:4228
	ds_write_b32 v1, v60 offset:4232
	ds_write_b32 v1, v61 offset:4236
	ds_write_b32 v1, v62 offset:5280
	ds_write_b32 v1, v63 offset:5284
	ds_write_b32 v1, v64 offset:5288
	ds_write_b32 v1, v65 offset:5292
	ds_write_b32 v1, v66 offset:6336
	ds_write_b32 v1, v67 offset:6340
	ds_write_b32 v1, v68 offset:6344
	ds_write_b32 v1, v69 offset:6348
	ds_write_b32 v1, v70 offset:7392
	ds_write_b32 v1, v71 offset:7396
	ds_write_b32 v1, v72 offset:7400
	ds_write_b32 v1, v73 offset:7404
	v_mad_u32_u24 v9, v5, s23, v6
	s_lshl_b32 s46, s23, 3
	s_waitcnt lgkmcnt(0)
	ds_read_b32 v74, v2 offset:0
	ds_read_b32 v75, v2 offset:132
	ds_read_b32 v76, v2 offset:264
	ds_read_b32 v77, v2 offset:396
	ds_read_b32 v78, v2 offset:528
	ds_read_b32 v79, v2 offset:660
	ds_read_b32 v80, v2 offset:792
	ds_read_b32 v81, v2 offset:924
	ds_read_b32 v82, v2 offset:32
	ds_read_b32 v83, v2 offset:164
	ds_read_b32 v84, v2 offset:296
	ds_read_b32 v85, v2 offset:428
	ds_read_b32 v86, v2 offset:560
	ds_read_b32 v87, v2 offset:692
	ds_read_b32 v88, v2 offset:824
	ds_read_b32 v89, v2 offset:956
	s_waitcnt lgkmcnt(8)
	v_cvt_pk_bf16_f32 v106, v74, v75
	v_cvt_pk_bf16_f32 v107, v76, v77
	v_cvt_pk_bf16_f32 v108, v78, v79
	v_cvt_pk_bf16_f32 v109, v80, v81
	global_store_dwordx4 v9, v[106:109], s[20:21]
	s_add_u32 s20, s20, s46
	s_addc_u32 s21, s21, 0
	ds_read_b32 v90, v2 offset:64
	ds_read_b32 v91, v2 offset:196
	ds_read_b32 v92, v2 offset:328
	ds_read_b32 v93, v2 offset:460
	ds_read_b32 v94, v2 offset:592
	ds_read_b32 v95, v2 offset:724
	ds_read_b32 v96, v2 offset:856
	ds_read_b32 v97, v2 offset:988
	s_waitcnt lgkmcnt(8)
	v_cvt_pk_bf16_f32 v110, v82, v83
	v_cvt_pk_bf16_f32 v111, v84, v85
	v_cvt_pk_bf16_f32 v112, v86, v87
	v_cvt_pk_bf16_f32 v113, v88, v89
	global_store_dwordx4 v9, v[110:113], s[20:21]
	s_add_u32 s20, s20, s46
	s_addc_u32 s21, s21, 0
	ds_read_b32 v98, v2 offset:96
	ds_read_b32 v99, v2 offset:228
	ds_read_b32 v100, v2 offset:360
	ds_read_b32 v101, v2 offset:492
	ds_read_b32 v102, v2 offset:624
	ds_read_b32 v103, v2 offset:756
	ds_read_b32 v104, v2 offset:888
	ds_read_b32 v105, v2 offset:1020
	s_waitcnt lgkmcnt(8)
	v_cvt_pk_bf16_f32 v106, v90, v91
	v_cvt_pk_bf16_f32 v107, v92, v93
	v_cvt_pk_bf16_f32 v108, v94, v95
	v_cvt_pk_bf16_f32 v109, v96, v97
	global_store_dwordx4 v9, v[106:109], s[20:21]
	s_add_u32 s20, s20, s46
	s_addc_u32 s21, s21, 0
	s_waitcnt lgkmcnt(0)
	v_cvt_pk_bf16_f32 v110, v98, v99
	v_cvt_pk_bf16_f32 v111, v100, v101
	v_cvt_pk_bf16_f32 v112, v102, v103
	v_cvt_pk_bf16_f32 v113, v104, v105
	global_store_dwordx4 v9, v[110:113], s[20:21]
	s_sub_u32 s25, s25, 1
	s_cmp_eq_u32 s25, 0
	s_cbranch_scc1 .Ltrt_done
	s_cmp_lt_u32 s12, 66560
	s_cbranch_scc0 .Ltrt_nonext41
	s_cmp_ge_u32 s12, 33280
	s_cselect_b32 s41, 1, 0
	s_cselect_b32 s26, 33280, 0
	s_sub_u32 s42, s12, s26
	s_cmp_ge_u32 s42, 12288
	s_cbranch_scc1 .Ltrt_m44
	s_mul_i32 s43, s42, 43691
	s_lshr_b32 s43, s43, 24
	s_mul_i32 s26, s43, 384
	s_sub_u32 s44, s42, s26
	s_mov_b32 s14, s0
	s_mov_b32 s15, s1
	s_mov_b32 s36, 0xc000
	s_mov_b32 s37, 0x6000000
	s_mov_b32 s38, 0x0
	s_mov_b32 s39, 0x3000000
	s_mov_b32 s40, 0x1000
	s_branch .Ltrt_dec_done43

.Ltrt_after42:
	ds_write_b32 v1, v114 offset:0
	ds_write_b32 v1, v115 offset:4
	ds_write_b32 v1, v116 offset:8
	ds_write_b32 v1, v117 offset:12
	ds_write_b32 v1, v118 offset:1056
	ds_write_b32 v1, v119 offset:1060
	ds_write_b32 v1, v120 offset:1064
	ds_write_b32 v1, v121 offset:1068
	ds_write_b32 v1, v122 offset:2112
	ds_write_b32 v1, v123 offset:2116
	ds_write_b32 v1, v124 offset:2120
	ds_write_b32 v1, v125 offset:2124
	ds_write_b32 v1, v126 offset:3168
	ds_write_b32 v1, v127 offset:3172
	ds_write_b32 v1, v128 offset:3176
	ds_write_b32 v1, v129 offset:3180
	ds_write_b32 v1, v130 offset:4224
	ds_write_b32 v1, v131 offset:4228
	ds_write_b32 v1, v132 offset:4232
	ds_write_b32 v1, v133 offset:4236
	ds_write_b32 v1, v134 offset:5280
	ds_write_b32 v1, v135 offset:5284
	ds_write_b32 v1, v136 offset:5288
	ds_write_b32 v1, v137 offset:5292
	ds_write_b32 v1, v138 offset:6336
	ds_write_b32 v1, v139 offset:6340
	ds_write_b32 v1, v140 offset:6344
	ds_write_b32 v1, v141 offset:6348
	ds_write_b32 v1, v142 offset:7392
	ds_write_b32 v1, v143 offset:7396
	ds_write_b32 v1, v144 offset:7400
	ds_write_b32 v1, v145 offset:7404
	v_mad_u32_u24 v9, v5, s52, v6
	s_lshl_b32 s46, s52, 3
	s_waitcnt lgkmcnt(0)
	ds_read_b32 v74, v2 offset:0
	ds_read_b32 v75, v2 offset:132
	ds_read_b32 v76, v2 offset:264
	ds_read_b32 v77, v2 offset:396
	ds_read_b32 v78, v2 offset:528
	ds_read_b32 v79, v2 offset:660
	ds_read_b32 v80, v2 offset:792
	ds_read_b32 v81, v2 offset:924
	ds_read_b32 v82, v2 offset:32
	ds_read_b32 v83, v2 offset:164
	ds_read_b32 v84, v2 offset:296
	ds_read_b32 v85, v2 offset:428
	ds_read_b32 v86, v2 offset:560
	ds_read_b32 v87, v2 offset:692
	ds_read_b32 v88, v2 offset:824
	ds_read_b32 v89, v2 offset:956
	s_waitcnt lgkmcnt(8)
	v_cvt_pk_bf16_f32 v106, v74, v75
	v_cvt_pk_bf16_f32 v107, v76, v77
	v_cvt_pk_bf16_f32 v108, v78, v79
	v_cvt_pk_bf16_f32 v109, v80, v81
	global_store_dwordx4 v9, v[106:109], s[48:49]
	s_add_u32 s48, s48, s46
	s_addc_u32 s49, s49, 0
	ds_read_b32 v90, v2 offset:64
	ds_read_b32 v91, v2 offset:196
	ds_read_b32 v92, v2 offset:328
	ds_read_b32 v93, v2 offset:460
	ds_read_b32 v94, v2 offset:592
	ds_read_b32 v95, v2 offset:724
	ds_read_b32 v96, v2 offset:856
	ds_read_b32 v97, v2 offset:988
	s_waitcnt lgkmcnt(8)
	v_cvt_pk_bf16_f32 v110, v82, v83
	v_cvt_pk_bf16_f32 v111, v84, v85
	v_cvt_pk_bf16_f32 v112, v86, v87
	v_cvt_pk_bf16_f32 v113, v88, v89
	global_store_dwordx4 v9, v[110:113], s[48:49]
	s_add_u32 s48, s48, s46
	s_addc_u32 s49, s49, 0
	ds_read_b32 v98, v2 offset:96
	ds_read_b32 v99, v2 offset:228
	ds_read_b32 v100, v2 offset:360
	ds_read_b32 v101, v2 offset:492
	ds_read_b32 v102, v2 offset:624
	ds_read_b32 v103, v2 offset:756
	ds_read_b32 v104, v2 offset:888
	ds_read_b32 v105, v2 offset:1020
	s_waitcnt lgkmcnt(8)
	v_cvt_pk_bf16_f32 v106, v90, v91
	v_cvt_pk_bf16_f32 v107, v92, v93
	v_cvt_pk_bf16_f32 v108, v94, v95
	v_cvt_pk_bf16_f32 v109, v96, v97
	global_store_dwordx4 v9, v[106:109], s[48:49]
	s_add_u32 s48, s48, s46
	s_addc_u32 s49, s49, 0
	s_waitcnt lgkmcnt(0)
	v_cvt_pk_bf16_f32 v110, v98, v99
	v_cvt_pk_bf16_f32 v111, v100, v101
	v_cvt_pk_bf16_f32 v112, v102, v103
	v_cvt_pk_bf16_f32 v113, v104, v105
	global_store_dwordx4 v9, v[110:113], s[48:49]
	s_sub_u32 s25, s25, 1
	s_cmp_eq_u32 s25, 0
	s_cbranch_scc1 .Ltrt_done
	s_cmp_lt_u32 s12, 66560
	s_cbranch_scc0 .Ltrt_nonext50
	s_cmp_ge_u32 s12, 33280
	s_cselect_b32 s41, 1, 0
	s_cselect_b32 s26, 33280, 0
	s_sub_u32 s42, s12, s26
	s_cmp_ge_u32 s42, 12288
	s_cbranch_scc1 .Ltrt_m53
	s_mul_i32 s43, s42, 43691
	s_lshr_b32 s43, s43, 24
	s_mul_i32 s26, s43, 384
	s_sub_u32 s44, s42, s26
	s_mov_b32 s14, s0
	s_mov_b32 s15, s1
	s_mov_b32 s36, 0xc000
	s_mov_b32 s37, 0x6000000
	s_mov_b32 s38, 0x0
	s_mov_b32 s39, 0x3000000
	s_mov_b32 s40, 0x1000
	s_branch .Ltrt_dec_done52

.Ltrt_loop:
	s_cmp_lt_u32 s12, 66560
	s_cbranch_scc0 .Ltrt_nonext59
	s_cmp_ge_u32 s12, 33280
	s_cselect_b32 s41, 1, 0
	s_cselect_b32 s26, 33280, 0
	s_sub_u32 s42, s12, s26
	s_cmp_ge_u32 s42, 12288
	s_cbranch_scc1 .Ltrt_m62
	s_mul_i32 s43, s42, 43691
	s_lshr_b32 s43, s43, 24
	s_mul_i32 s26, s43, 384
	s_sub_u32 s44, s42, s26
	s_mov_b32 s14, s0
	s_mov_b32 s15, s1
	s_mov_b32 s36, 0xc000
	s_mov_b32 s37, 0x6000000
	s_mov_b32 s38, 0x0
	s_mov_b32 s39, 0x3000000
	s_mov_b32 s40, 0x1000
	s_branch .Ltrt_dec_done61
